# k16 + ALIGN_EPI barrier moved after the epilogue preamble (leading half issues its bias/gate loads and waits for them while the trailing half finishes its last MFMA segment)
# speedup vs baseline: 1.0018x; 1.0018x over previous
;     template <int NA, int NM> __device__ __forceinline__ void operator()(const f32x4 (&acc)[NA][2][NM][2], const pg8::Unit& u, int ro, int wr, int wc, int fr, int fq) const {
;         const int j = u.pm < 32 ? 0 : (u.pm < 64 ? 1 : 2), type = u.pn >> 2;
;         const int colt = u.pn * 256 + wc * 32 + 8 * fq;
;         const LAS float* rsl = EpiCommon::rstd_slot(ssq, u, wr, wc, fr, fq);
;         f32x4 bv[2][2];
; #pragma unroll
;         for (int bj = 0; bj < 2; ++bj)
; #pragma unroll
;             for (int n = 0; n < 2; ++n) bv[bj][n] = *(const f32x4*)(bias + (size_t)j * PIN + colt + bj * 128 + 4 * n);
; #pragma unroll
;         for (int ai = 0; ai < NA; ++ai)
; #pragma unroll
;             for (int m = 0; m < NM; ++m) {
;                 const int row = u.pm * 256 + ro + ai * 128 + wr * 64 + m * 16 + fr;
;                 const float rs = rsl[ro + ai * 128 + m * 16];
; #pragma unroll
;                 for (int bj = 0; bj < 2; ++bj) {
;                     const f32x4 v0 = acc[ai][bj][m][0] * rs + bv[bj][0], v1 = acc[ai][bj][m][1] * rs + bv[bj][1];
;                     const int c = colt + bj * 128;
;                     u32x4 w;
;                     if (type == 1 || type == 2) {
;                         f32x4 c0, c1;
;                         c0.x = __builtin_amdgcn_rcpf(1.0f + __builtin_amdgcn_exp2f(v0.x * 1.4426950408889634f)); c0.y = __builtin_amdgcn_rcpf(1.0f + __builtin_amdgcn_exp2f(v0.y * 1.4426950408889634f));
;                         c0.z = __builtin_amdgcn_rcpf(1.0f + __builtin_amdgcn_exp2f(v0.z * 1.4426950408889634f)); c0.w = __builtin_amdgcn_rcpf(1.0f + __builtin_amdgcn_exp2f(v0.w * 1.4426950408889634f));
;                         c1.x = __builtin_amdgcn_rcpf(1.0f + __builtin_amdgcn_exp2f(v1.x * 1.4426950408889634f)); c1.y = __builtin_amdgcn_rcpf(1.0f + __builtin_amdgcn_exp2f(v1.y * 1.4426950408889634f));
;                         c1.z = __builtin_amdgcn_rcpf(1.0f + __builtin_amdgcn_exp2f(v1.z * 1.4426950408889634f)); c1.w = __builtin_amdgcn_rcpf(1.0f + __builtin_amdgcn_exp2f(v1.w * 1.4426950408889634f));
;                         w.x = pkh2(c0.x, c0.y); w.y = pkh2(c0.z, c0.w); w.z = pkh2(c1.x, c1.y); w.w = pkh2(c1.z, c1.w);
;                         unsigned short* dst = (type == 1 ? Ff : Fb) + (size_t)row * D + (c - type * 1024);
;                         *(u32x4*)dst = w;
;                     } else {
.LBB0_417:
	s_cmp_lt_i32 s66, 64
	s_movk_i32 s0, 0x2400
	s_cselect_b32 s0, s0, 0x4800
	s_ashr_i32 s7, s64, 2
	s_lshl_b32 s1, s65, 10
	s_cmp_gt_i32 s66, 31
	s_cselect_b32 s0, s0, 0
	s_lshl_b32 s0, s0, 2
	v_lshl_or_b32 v156, s64, 8, v214
	s_add_u32 s10, s8, s0
	s_addc_u32 s11, s9, 0
	v_ashrrev_i32_e32 v157, 31, v156
	v_lshl_add_u64 v[54:55], v[156:157], 2, s[10:11]
	global_load_dwordx4 v[66:69], v[54:55], off offset:16
	global_load_dwordx4 v[70:73], v[54:55], off
	global_load_dwordx4 v[50:53], v[54:55], off offset:528
	s_nop 0
	global_load_dwordx4 v[54:57], v[54:55], off offset:512
	s_add_i32 s0, s7, -1
	s_cmp_gt_u32 s0, 1
	v_add_u32_e32 v157, s1, v213
	s_cselect_b64 s[70:71], -1, 0
	s_cmp_lt_u32 s64, 4
	s_cselect_b64 s[64:65], -1, 0
	s_cmp_eq_u32 s7, 1
	ds_read_b32 v158, v157
	s_cselect_b64 s[68:69], -1, 0
	s_lshl_b32 s5, s66, 8
	v_add_u32_e32 v176, s5, v201
	v_ashrrev_i32_e32 v177, 31, v176
	v_readlane_b32 s0, v254, 19
	v_lshlrev_b64 v[178:179], 12, v[176:177]
	v_add_u32_e32 v216, 0xfffff800, v156
	v_readlane_b32 s1, v254, 20
	s_mov_b64 s[66:67], -1
	s_and_b64 vcc, exec, s[70:71]
	v_readlane_b32 s36, v252, 63
	v_readlane_b32 s37, v253, 0
	v_readlane_b32 s38, v253, 1
	v_readlane_b32 s39, v253, 2
	v_readlane_b32 s40, v253, 3
	v_readlane_b32 s41, v253, 4
	v_readlane_b32 s42, v253, 5
	v_readlane_b32 s43, v253, 6
	v_readlane_b32 s44, v253, 7
	v_readlane_b32 s45, v253, 8
	v_readlane_b32 s46, v253, 9
	v_readlane_b32 s47, v253, 10
	v_readlane_b32 s48, v253, 11
	v_readlane_b32 s49, v253, 12
	v_readlane_b32 s50, v253, 13
	v_readlane_b32 s51, v253, 14
	s_waitcnt vmcnt(0) lgkmcnt(0)
	s_cmp_lg_u64 s[2:3], 0
	s_cbranch_scc0 .Lal_1
	s_barrier
.Lal_1:
	v_pk_fma_f32 v[160:161], v[140:141], v[158:159], v[68:69] op_sel_hi:[1,0,1]
	v_pk_fma_f32 v[172:173], v[144:145], v[158:159], v[72:73] op_sel_hi:[1,0,1]
	v_pk_fma_f32 v[174:175], v[142:143], v[158:159], v[70:71] op_sel_hi:[1,0,1]
	v_pk_fma_f32 v[170:171], v[138:139], v[158:159], v[66:67] op_sel_hi:[1,0,1]
	v_lshl_add_u64 v[144:145], s[0:1], 0, v[178:179]
	v_cndmask_b32_e64 v142, v216, v156, s[64:65]
	s_cbranch_vccz .LBB0_419
	v_readlane_b32 s0, v254, 19
	v_readlane_b32 s1, v254, 20
	v_cvt_pk_bf16_f32 v138, v174, v175
	v_cvt_pk_bf16_f32 v139, v172, v173
	v_cvt_pk_bf16_f32 v140, v170, v171
	v_cvt_pk_bf16_f32 v141, v160, v161
	v_lshl_add_u64 v[180:181], s[0:1], 0, v[178:179]
	v_cndmask_b32_e64 v182, v216, v156, s[64:65]
	s_mov_b64 s[66:67], 0

; #define PG8_STAGE(bufoff, gbase, voff) do { _Pragma("unroll") for (int _i = 0; _i < 2; ++_i) \
;         __builtin_amdgcn_global_load_lds((const unsigned*)((const char*)(gbase) + (voff)[_i]), (LAS unsigned*)(lds + (bufoff) + ldsw + _i * 8192), 16, 0, 0); } while (0)
; #define PG8_LDA(dst, b, h) do { _Pragma("unroll") for (int m = 0; m < 4; ++m) _Pragma("unroll") for (int k = 0; k < 2; ++k) dst[m][k] = *(const LAS bf16x8*)(lds + PG8_SA(b, h) + aoff + m * 2048 + k * 1024); } while (0)
; #define PG8_LDB(dst, b, h) do { _Pragma("unroll") for (int n = 0; n < 2; ++n) _Pragma("unroll") for (int k = 0; k < 2; ++k) dst[n][k] = *(const LAS bf16x8*)(lds + PG8_SB(b, h) + boff + n * 2048 + k * 1024); } while (0)
; #define PG8_MMA(ai, bj, At, Bt) do { __builtin_amdgcn_s_setprio(1); _Pragma("unroll") for (int m = 0; m < 4; ++m) _Pragma("unroll") for (int n = 0; n < 2; ++n) _Pragma("unroll") for (int k = 0; k < 2; ++k) \
;         acc[ai][bj][m][n] = __builtin_amdgcn_mfma_f32_16x16x32_bf16(Bt[n][k], At[m][k], acc[ai][bj][m][n], 0, 0, 0); __builtin_amdgcn_s_setprio(0); } while (0)
; #define PG8_WAIT_V(n) asm volatile("s_waitcnt vmcnt(" #n ")" ::: "memory")
; #define PG8_WAIT_L(n) asm volatile("s_waitcnt lgkmcnt(" #n ")" ::: "memory")
; #define PG8_BAR __builtin_amdgcn_s_barrier()
; #define PG8_SCHED __builtin_amdgcn_sched_barrier(0)
; template <class Epi>
; __device__ __forceinline__ void gemm_phase(LAS unsigned char* lds, const int tid, const Gemm g, const StaticOrder& S, const Epi& E) {
;     ...
;         for (int t = 0; t < nt; t += 2) {
;             const bool last = (t == nt - 2);
;             const char* a1 = cA + (size_t)(t + 1) * kstep;
;             const char* a2 = last ? nA : cA + (size_t)(t + 2) * kstep; const char* b2 = last ? nB : cB + (size_t)(t + 2) * kstep;
;             const char* a3 = a2 + kstep; const char* b3 = b2 + kstep;
;             PG8_LDB(B0, 0, 0); PG8_LDB(B1, 0, 1); PG8_SCHED; PG8_LDA(At, 0, 0); PG8_STAGE(PG8_SA(1, 1), a1 + hstepA, voffA);
;             PG8_WAIT_V(8); PG8_WAIT_L(0); PG8_BAR; PG8_MMA(0, 0, At, B0); PG8_MMA(0, 1, At, B1); PG8_BAR; PG8_SCHED;
;             PG8_LDA(At, 0, 1); PG8_STAGE(PG8_SB(0, 0), b2, voffB); PG8_STAGE(PG8_SB(0, 1), b2 + hstepB, voffB); PG8_STAGE(PG8_SA(0, 0), a2, voffA);
;             PG8_WAIT_V(8); PG8_WAIT_L(0); PG8_BAR; PG8_MMA(1, 0, At, B0); PG8_MMA(1, 1, At, B1); PG8_BAR; PG8_SCHED;
.LBB0_945:
	s_add_u32 s30, s72, 0xfffc0080
	s_addc_u32 s31, s73, -1
	s_add_i32 s76, 0, 0x10000
	s_cmp_eq_u32 vcc_hi, 12
	s_cselect_b32 s75, s9, s31
	s_cselect_b32 s74, s27, s30
	v_add_u32_e32 v0, s76, v178
	s_cselect_b32 s31, s7, vcc_lo
	s_cselect_b32 s30, s28, s65
	s_add_i32 s0, 0, 0x14000
	ds_read_b128 v[18:21], v0
	ds_read_b128 v[22:25], v0 offset:1024
	ds_read_b128 v[26:29], v0 offset:2048
	ds_read_b128 v[30:33], v0 offset:3072
	v_add_u32_e32 v0, s0, v178
	ds_read_b128 v[170:173], v0
	ds_read_b128 v[174:177], v0 offset:1024
	ds_read_b128 v[190:193], v0 offset:2048
	ds_read_b128 v[194:197], v0 offset:3072
	v_lshl_add_u64 v[162:163], s[72:73], 0, v[158:159]
	s_add_i32 m0, s71, 0xc000
	s_nop 0
	global_load_lds_dwordx4 v[162:163], off
	v_lshl_add_u64 v[162:163], s[72:73], 0, v[160:161]
	s_add_i32 m0, s71, 0xe000
	s_nop 0
	global_load_lds_dwordx4 v[162:163], off
	ds_read_b128 v[198:201], v189
	ds_read_b128 v[210:213], v189 offset:1024
	ds_read_b128 v[214:217], v189 offset:2048
	ds_read_b128 v[218:221], v189 offset:3072
	ds_read_b128 v[222:225], v189 offset:4096
	ds_read_b128 v[226:229], v189 offset:5120
	ds_read_b128 v[230:233], v189 offset:6144
	ds_read_b128 v[234:237], v189 offset:7168
	s_waitcnt vmcnt(8)
	s_waitcnt lgkmcnt(0)
	s_barrier
	s_setprio 1
	s_waitcnt lgkmcnt(0)
	v_mfma_f32_16x16x32_bf16 v[142:145], v[18:21], v[198:201], v[142:145]
	v_mfma_f32_16x16x32_bf16 v[138:141], v[26:29], v[198:201], v[138:141]
	v_mfma_f32_16x16x32_bf16 v[126:129], v[18:21], v[214:217], v[126:129]
	v_mfma_f32_16x16x32_bf16 v[122:125], v[26:29], v[214:217], v[122:125]
	v_mfma_f32_16x16x32_bf16 v[110:113], v[18:21], v[222:225], v[110:113]
	v_mfma_f32_16x16x32_bf16 v[106:109], v[26:29], v[222:225], v[106:109]
	v_mfma_f32_16x16x32_bf16 v[94:97], v[18:21], v[230:233], v[94:97]
	v_mfma_f32_16x16x32_bf16 v[90:93], v[26:29], v[230:233], v[90:93]
	v_mfma_f32_16x16x32_bf16 v[142:145], v[22:25], v[210:213], v[142:145]
	v_mfma_f32_16x16x32_bf16 v[138:141], v[30:33], v[210:213], v[138:141]
	v_mfma_f32_16x16x32_bf16 v[126:129], v[22:25], v[218:221], v[126:129]
	v_mfma_f32_16x16x32_bf16 v[122:125], v[30:33], v[218:221], v[122:125]
	v_mfma_f32_16x16x32_bf16 v[110:113], v[22:25], v[226:229], v[110:113]
	v_mfma_f32_16x16x32_bf16 v[106:109], v[30:33], v[226:229], v[106:109]
	v_mfma_f32_16x16x32_bf16 v[94:97], v[22:25], v[234:237], v[94:97]
	v_mfma_f32_16x16x32_bf16 v[90:93], v[30:33], v[234:237], v[90:93]
	s_setprio 0
	s_setprio 1
	v_mfma_f32_16x16x32_bf16 v[134:137], v[170:173], v[198:201], v[134:137]
	v_mfma_f32_16x16x32_bf16 v[130:133], v[190:193], v[198:201], v[130:133]
	v_mfma_f32_16x16x32_bf16 v[118:121], v[170:173], v[214:217], v[118:121]
	v_mfma_f32_16x16x32_bf16 v[114:117], v[190:193], v[214:217], v[114:117]
	v_mfma_f32_16x16x32_bf16 v[102:105], v[170:173], v[222:225], v[102:105]
	v_mfma_f32_16x16x32_bf16 v[98:101], v[190:193], v[222:225], v[98:101]
	v_mfma_f32_16x16x32_bf16 v[86:89], v[170:173], v[230:233], v[86:89]
	v_mfma_f32_16x16x32_bf16 v[82:85], v[190:193], v[230:233], v[82:85]
	v_mfma_f32_16x16x32_bf16 v[134:137], v[174:177], v[210:213], v[134:137]
	v_mfma_f32_16x16x32_bf16 v[130:133], v[194:197], v[210:213], v[130:133]
	v_mfma_f32_16x16x32_bf16 v[118:121], v[174:177], v[218:221], v[118:121]
	v_mfma_f32_16x16x32_bf16 v[114:117], v[194:197], v[218:221], v[114:117]
	v_mfma_f32_16x16x32_bf16 v[102:105], v[174:177], v[226:229], v[102:105]
	v_mfma_f32_16x16x32_bf16 v[98:101], v[194:197], v[226:229], v[98:101]
	v_mfma_f32_16x16x32_bf16 v[86:89], v[174:177], v[234:237], v[86:89]
	v_mfma_f32_16x16x32_bf16 v[82:85], v[194:197], v[234:237], v[82:85]
	s_setprio 0
	s_barrier
	s_add_i32 s1, s76, s93
	v_lshl_add_u64 v[162:163], s[30:31], 0, v[150:151]
	s_mov_b32 m0, s1
	s_nop 0
	global_load_lds_dwordx4 v[162:163], off
	s_add_i32 m0, s1, 0x2000
	s_add_u32 s76, s30, 0x40000
	v_lshl_add_u64 v[164:165], s[30:31], 0, v[154:155]
	s_addc_u32 s77, s31, 0
	s_add_i32 s0, s0, s93
	global_load_lds_dwordx4 v[164:165], off
	v_lshl_add_u64 v[202:203], s[76:77], 0, v[150:151]
	s_mov_b32 m0, s0
	v_lshl_add_u64 v[206:207], s[74:75], 0, v[152:153]
	global_load_lds_dwordx4 v[202:203], off
	v_lshl_add_u64 v[202:203], s[76:77], 0, v[154:155]
	s_add_i32 m0, s0, 0x2000
	s_nop 0
	global_load_lds_dwordx4 v[202:203], off
	v_lshl_add_u64 v[202:203], s[74:75], 0, v[148:149]
	s_mov_b32 m0, s71
	s_nop 0
	global_load_lds_dwordx4 v[202:203], off
	s_mov_b32 m0, s88
	s_nop 0
	global_load_lds_dwordx4 v[206:207], off
	ds_read_b128 v[198:201], v189 offset:16384
	ds_read_b128 v[210:213], v189 offset:17408
	ds_read_b128 v[214:217], v189 offset:18432
	ds_read_b128 v[218:221], v189 offset:19456
	ds_read_b128 v[222:225], v189 offset:20480
	ds_read_b128 v[226:229], v189 offset:21504
	ds_read_b128 v[230:233], v189 offset:22528
	ds_read_b128 v[234:237], v189 offset:23552
	s_waitcnt vmcnt(8)
	s_waitcnt lgkmcnt(0)
	s_barrier
; #define PG8_STAGE(bufoff, gbase, voff) do { _Pragma("unroll") for (int _i = 0; _i < 2; ++_i) \
;         __builtin_amdgcn_global_load_lds((const unsigned*)((const char*)(gbase) + (voff)[_i]), (LAS unsigned*)(lds + (bufoff) + ldsw + _i * 8192), 16, 0, 0); } while (0)
; #define PG8_LDA(dst, b, h) do { _Pragma("unroll") for (int m = 0; m < 4; ++m) _Pragma("unroll") for (int k = 0; k < 2; ++k) dst[m][k] = *(const LAS bf16x8*)(lds + PG8_SA(b, h) + aoff + m * 2048 + k * 1024); } while (0)
; #define PG8_LDB(dst, b, h) do { _Pragma("unroll") for (int n = 0; n < 2; ++n) _Pragma("unroll") for (int k = 0; k < 2; ++k) dst[n][k] = *(const LAS bf16x8*)(lds + PG8_SB(b, h) + boff + n * 2048 + k * 1024); } while (0)
; #define PG8_MMA(ai, bj, At, Bt) do { __builtin_amdgcn_s_setprio(1); _Pragma("unroll") for (int m = 0; m < 4; ++m) _Pragma("unroll") for (int n = 0; n < 2; ++n) _Pragma("unroll") for (int k = 0; k < 2; ++k) \
;         acc[ai][bj][m][n] = __builtin_amdgcn_mfma_f32_16x16x32_bf16(Bt[n][k], At[m][k], acc[ai][bj][m][n], 0, 0, 0); __builtin_amdgcn_s_setprio(0); } while (0)
; #define PG8_WAIT_V(n) asm volatile("s_waitcnt vmcnt(" #n ")" ::: "memory")
; #define PG8_WAIT_L(n) asm volatile("s_waitcnt lgkmcnt(" #n ")" ::: "memory")
; #define PG8_BAR __builtin_amdgcn_s_barrier()
; #define PG8_SCHED __builtin_amdgcn_sched_barrier(0)
; template <class Epi>
; __device__ __forceinline__ void gemm_phase(LAS unsigned char* lds, const int tid, const Gemm g, const StaticOrder& S, const Epi& E) {
;     ...
;             PG8_WAIT_V(8); PG8_WAIT_L(0); PG8_BAR; PG8_MMA(1, 0, At, B0); PG8_MMA(1, 1, At, B1); PG8_BAR; PG8_SCHED;
;             PG8_LDB(B0, 1, 0); PG8_LDB(B1, 1, 1); PG8_SCHED; PG8_LDA(At, 1, 0); PG8_STAGE(PG8_SA(0, 1), a2 + hstepA, voffA);
;             PG8_WAIT_V(8); PG8_WAIT_L(0); PG8_BAR; PG8_MMA(0, 0, At, B0); PG8_MMA(0, 1, At, B1); PG8_BAR; PG8_SCHED;
	s_setprio 1
	s_waitcnt lgkmcnt(0)
	v_mfma_f32_16x16x32_bf16 v[78:81], v[18:21], v[198:201], v[78:81]
	v_mfma_f32_16x16x32_bf16 v[74:77], v[26:29], v[198:201], v[74:77]
	v_mfma_f32_16x16x32_bf16 v[62:65], v[18:21], v[214:217], v[62:65]
	v_mfma_f32_16x16x32_bf16 v[58:61], v[26:29], v[214:217], v[58:61]
	v_mfma_f32_16x16x32_bf16 v[46:49], v[18:21], v[222:225], v[46:49]
	v_mfma_f32_16x16x32_bf16 v[42:45], v[26:29], v[222:225], v[42:45]
	v_mfma_f32_16x16x32_bf16 v[14:17], v[18:21], v[230:233], v[14:17]
	v_mfma_f32_16x16x32_bf16 v[10:13], v[26:29], v[230:233], v[10:13]
	v_mfma_f32_16x16x32_bf16 v[78:81], v[22:25], v[210:213], v[78:81]
	v_mfma_f32_16x16x32_bf16 v[74:77], v[30:33], v[210:213], v[74:77]
	v_mfma_f32_16x16x32_bf16 v[62:65], v[22:25], v[218:221], v[62:65]
	v_mfma_f32_16x16x32_bf16 v[58:61], v[30:33], v[218:221], v[58:61]
	v_mfma_f32_16x16x32_bf16 v[46:49], v[22:25], v[226:229], v[46:49]
	v_mfma_f32_16x16x32_bf16 v[42:45], v[30:33], v[226:229], v[42:45]
	v_mfma_f32_16x16x32_bf16 v[14:17], v[22:25], v[234:237], v[14:17]
	v_mfma_f32_16x16x32_bf16 v[10:13], v[30:33], v[234:237], v[10:13]
	s_setprio 0
	s_setprio 1
	v_mfma_f32_16x16x32_bf16 v[38:41], v[170:173], v[222:225], v[38:41]
	v_mfma_f32_16x16x32_bf16 v[34:37], v[190:193], v[222:225], v[34:37]
	v_mfma_f32_16x16x32_bf16 v[6:9], v[170:173], v[230:233], v[6:9]
	v_mfma_f32_16x16x32_bf16 v[2:5], v[190:193], v[230:233], v[2:5]
	v_mfma_f32_16x16x32_bf16 v[18:21], v[170:173], v[198:201], v[70:73]
	v_mfma_f32_16x16x32_bf16 v[22:25], v[190:193], v[198:201], v[66:69]
	v_mfma_f32_16x16x32_bf16 v[26:29], v[170:173], v[214:217], v[54:57]
	v_mfma_f32_16x16x32_bf16 v[30:33], v[190:193], v[214:217], v[50:53]
	v_mfma_f32_16x16x32_bf16 v[38:41], v[174:177], v[226:229], v[38:41]
	v_mfma_f32_16x16x32_bf16 v[34:37], v[194:197], v[226:229], v[34:37]
	v_mfma_f32_16x16x32_bf16 v[6:9], v[174:177], v[234:237], v[6:9]
	v_mfma_f32_16x16x32_bf16 v[2:5], v[194:197], v[234:237], v[2:5]
	v_mfma_f32_16x16x32_bf16 v[18:21], v[174:177], v[210:213], v[18:21]
	v_mfma_f32_16x16x32_bf16 v[22:25], v[194:197], v[210:213], v[22:25]
	v_mfma_f32_16x16x32_bf16 v[26:29], v[174:177], v[218:221], v[26:29]
	v_mfma_f32_16x16x32_bf16 v[30:33], v[194:197], v[218:221], v[30:33]
	s_setprio 0
	s_barrier
	s_add_i32 s0, 0, 0x18000
	v_add_u32_e32 v0, s0, v178
	s_add_i32 s1, 0, 0x1c000
	ds_read_b128 v[50:53], v0
	ds_read_b128 v[54:57], v0 offset:1024
	ds_read_b128 v[66:69], v0 offset:2048
	ds_read_b128 v[70:73], v0 offset:3072
	v_add_u32_e32 v0, s1, v178
	ds_read_b128 v[170:173], v0
	ds_read_b128 v[174:177], v0 offset:1024
	ds_read_b128 v[190:193], v0 offset:2048
	ds_read_b128 v[194:197], v0 offset:3072
	s_add_u32 s74, s74, 0x40000
	s_addc_u32 s75, s75, 0
	s_mov_b32 m0, s83
	v_lshl_add_u64 v[238:239], s[74:75], 0, v[148:149]
	global_load_lds_dwordx4 v[238:239], off
	v_lshl_add_u64 v[238:239], s[74:75], 0, v[152:153]
	s_mov_b32 m0, s16
	s_nop 0
	global_load_lds_dwordx4 v[238:239], off
	ds_read_b128 v[198:201], v189 offset:32768
	ds_read_b128 v[210:213], v189 offset:33792
	ds_read_b128 v[214:217], v189 offset:34816
	ds_read_b128 v[218:221], v189 offset:35840
	ds_read_b128 v[222:225], v189 offset:36864
	ds_read_b128 v[226:229], v189 offset:37888
	ds_read_b128 v[230:233], v189 offset:38912
	ds_read_b128 v[234:237], v189 offset:39936
	s_waitcnt vmcnt(8)
	s_waitcnt lgkmcnt(0)
	s_barrier
	s_setprio 1
	s_waitcnt lgkmcnt(0)
	v_mfma_f32_16x16x32_bf16 v[142:145], v[50:53], v[198:201], v[142:145]
	v_mfma_f32_16x16x32_bf16 v[138:141], v[66:69], v[198:201], v[138:141]
	v_mfma_f32_16x16x32_bf16 v[126:129], v[50:53], v[214:217], v[126:129]
	v_mfma_f32_16x16x32_bf16 v[122:125], v[66:69], v[214:217], v[122:125]
	v_mfma_f32_16x16x32_bf16 v[110:113], v[50:53], v[222:225], v[110:113]
	v_mfma_f32_16x16x32_bf16 v[106:109], v[66:69], v[222:225], v[106:109]
	v_mfma_f32_16x16x32_bf16 v[94:97], v[50:53], v[230:233], v[94:97]
	v_mfma_f32_16x16x32_bf16 v[90:93], v[66:69], v[230:233], v[90:93]
	v_mfma_f32_16x16x32_bf16 v[142:145], v[54:57], v[210:213], v[142:145]
	v_mfma_f32_16x16x32_bf16 v[138:141], v[70:73], v[210:213], v[138:141]
	v_mfma_f32_16x16x32_bf16 v[126:129], v[54:57], v[218:221], v[126:129]
	v_mfma_f32_16x16x32_bf16 v[122:125], v[70:73], v[218:221], v[122:125]
	v_mfma_f32_16x16x32_bf16 v[110:113], v[54:57], v[226:229], v[110:113]
	v_mfma_f32_16x16x32_bf16 v[106:109], v[70:73], v[226:229], v[106:109]
	v_mfma_f32_16x16x32_bf16 v[94:97], v[54:57], v[234:237], v[94:97]
	v_mfma_f32_16x16x32_bf16 v[90:93], v[70:73], v[234:237], v[90:93]
	s_setprio 0
	s_setprio 1
	v_mfma_f32_16x16x32_bf16 v[134:137], v[170:173], v[198:201], v[134:137]
	v_mfma_f32_16x16x32_bf16 v[130:133], v[190:193], v[198:201], v[130:133]
	v_mfma_f32_16x16x32_bf16 v[118:121], v[170:173], v[214:217], v[118:121]
	v_mfma_f32_16x16x32_bf16 v[114:117], v[190:193], v[214:217], v[114:117]
	v_mfma_f32_16x16x32_bf16 v[102:105], v[170:173], v[222:225], v[102:105]
	v_mfma_f32_16x16x32_bf16 v[98:101], v[190:193], v[222:225], v[98:101]
	v_mfma_f32_16x16x32_bf16 v[86:89], v[170:173], v[230:233], v[86:89]
	v_mfma_f32_16x16x32_bf16 v[82:85], v[190:193], v[230:233], v[82:85]
	v_mfma_f32_16x16x32_bf16 v[134:137], v[174:177], v[210:213], v[134:137]
	v_mfma_f32_16x16x32_bf16 v[130:133], v[194:197], v[210:213], v[130:133]
	v_mfma_f32_16x16x32_bf16 v[118:121], v[174:177], v[218:221], v[118:121]
	v_mfma_f32_16x16x32_bf16 v[114:117], v[194:197], v[218:221], v[114:117]
	v_mfma_f32_16x16x32_bf16 v[102:105], v[174:177], v[226:229], v[102:105]
	v_mfma_f32_16x16x32_bf16 v[98:101], v[194:197], v[226:229], v[98:101]
	v_mfma_f32_16x16x32_bf16 v[86:89], v[174:177], v[234:237], v[86:89]
	v_mfma_f32_16x16x32_bf16 v[82:85], v[194:197], v[234:237], v[82:85]
	s_setprio 0
	s_barrier
; #define LAS __attribute__((address_space(3)))
; #define PG8_BAR __builtin_amdgcn_s_barrier()
; template <class Epi>
; __device__ __forceinline__ void gemm_phase(LAS unsigned char* lds, const int tid, const Gemm g, const StaticOrder& S, const Epi& E) {
;     ...
;             PG8_LDA(At, 1, 1); PG8_STAGE(PG8_SB(1, 0), b3, voffB); PG8_STAGE(PG8_SB(1, 1), b3 + hstepB, voffB); PG8_STAGE(PG8_SA(1, 0), a3, voffA);
;             PG8_WAIT_V(8); PG8_WAIT_L(0); PG8_BAR; PG8_MMA(1, 0, At, B0); PG8_MMA(1, 1, At, B1); PG8_BAR; PG8_SCHED;
;         }
;         if (wr == 0) PG8_BAR;
;     template <int NA, int NM> __device__ __forceinline__ void operator()(const f32x4 (&acc)[NA][2][NM][2], const pg8::Unit& u, int ro, int wr, int wc, int fr, int fq) const {
;         const int j = u.pm < 32 ? 0 : (u.pm < 64 ? 1 : 2);
;         const int colt = 4096 + u.pn * 256 + wc * 32 + 8 * fq;
;         const LAS float* rsl = EpiCommon::rstd_slot(ssq, u, wr, wc, fr, fq);
;         f32x4 bv[2][2];
; #pragma unroll
;         for (int bj = 0; bj < 2; ++bj)
; #pragma unroll
;             for (int n = 0; n < 2; ++n) bv[bj][n] = *(const f32x4*)(bias + (size_t)j * PIN + colt + bj * 128 + 4 * n);
; #pragma unroll
;         for (int ai = 0; ai < NA; ++ai)
; #pragma unroll
;             for (int m = 0; m < NM; ++m) {
;                 const int row = u.pm * 256 + ro + ai * 128 + wr * 64 + m * 16 + fr;
;                 const float rs = rsl[ro + ai * 128 + m * 16];
;                 f32x4 v[2][2];
; #pragma unroll
;                 for (int bj = 0; bj < 2; ++bj) { v[bj][0] = acc[ai][bj][m][0] * rs + bv[bj][0]; v[bj][1] = acc[ai][bj][m][1] * rs + bv[bj][1]; }
;                 if (u.pn < 4) {
; #pragma unroll
;                     for (int bj = 0; bj < 2; ++bj) {
;                         bf16_t* p = QV + (size_t)row * 2048 + (colt - 4096) + bj * 128;
;                         const u32x4 on = *(const u32x4*)p;
;                         u32x4 w;
;                         w.x = pk2(bflo(on.x) * siluf_(v[bj][0].x), bfhi(on.x) * siluf_(v[bj][0].y)); w.y = pk2(bflo(on.y) * siluf_(v[bj][0].z), bfhi(on.y) * siluf_(v[bj][0].w));
;                         w.z = pk2(bflo(on.z) * siluf_(v[bj][1].x), bfhi(on.z) * siluf_(v[bj][1].y)); w.w = pk2(bflo(on.w) * siluf_(v[bj][1].z), bfhi(on.w) * siluf_(v[bj][1].w));
;                         if (!dry) *(u32x4*)p = w; else asm volatile("" :: "v"(w));
	s_add_i32 s0, s0, s93
	v_lshl_add_u64 v[162:163], v[162:163], 0, s[36:37]
	s_mov_b32 m0, s0
	s_nop 0
	global_load_lds_dwordx4 v[162:163], off
	s_add_i32 m0, s0, 0x2000
	s_add_u32 s30, s30, 0x40080
	v_lshl_add_u64 v[162:163], v[164:165], 0, s[36:37]
	s_addc_u32 s31, s31, 0
	s_add_i32 s0, s1, s93
	global_load_lds_dwordx4 v[162:163], off
	v_lshl_add_u64 v[162:163], s[30:31], 0, v[150:151]
	s_mov_b32 m0, s0
	s_nop 0
	global_load_lds_dwordx4 v[162:163], off
	v_lshl_add_u64 v[162:163], s[30:31], 0, v[154:155]
	s_add_i32 m0, s0, 0x2000
	s_nop 0
	global_load_lds_dwordx4 v[162:163], off
	v_lshl_add_u64 v[162:163], v[202:203], 0, s[36:37]
	s_mov_b32 m0, s92
	s_nop 0
	global_load_lds_dwordx4 v[162:163], off
	v_lshl_add_u64 v[162:163], v[206:207], 0, s[36:37]
	s_mov_b32 m0, s89
	s_nop 0
	global_load_lds_dwordx4 v[162:163], off
	ds_read_b128 v[198:201], v189 offset:49152
	ds_read_b128 v[210:213], v189 offset:50176
	ds_read_b128 v[214:217], v189 offset:51200
	ds_read_b128 v[218:221], v189 offset:52224
	ds_read_b128 v[222:225], v189 offset:53248
	ds_read_b128 v[226:229], v189 offset:54272
	ds_read_b128 v[230:233], v189 offset:55296
	ds_read_b128 v[234:237], v189 offset:56320
	s_waitcnt vmcnt(8)
	s_waitcnt lgkmcnt(0)
	s_barrier
	s_setprio 1
	s_waitcnt lgkmcnt(0)
	v_mfma_f32_16x16x32_bf16 v[78:81], v[50:53], v[198:201], v[78:81]
	v_mfma_f32_16x16x32_bf16 v[74:77], v[66:69], v[198:201], v[74:77]
	v_mfma_f32_16x16x32_bf16 v[62:65], v[50:53], v[214:217], v[62:65]
	v_mfma_f32_16x16x32_bf16 v[58:61], v[66:69], v[214:217], v[58:61]
	v_mfma_f32_16x16x32_bf16 v[46:49], v[50:53], v[222:225], v[46:49]
	v_mfma_f32_16x16x32_bf16 v[42:45], v[66:69], v[222:225], v[42:45]
	v_mfma_f32_16x16x32_bf16 v[14:17], v[50:53], v[230:233], v[14:17]
	v_mfma_f32_16x16x32_bf16 v[10:13], v[66:69], v[230:233], v[10:13]
	v_mfma_f32_16x16x32_bf16 v[78:81], v[54:57], v[210:213], v[78:81]
	v_mfma_f32_16x16x32_bf16 v[74:77], v[70:73], v[210:213], v[74:77]
	v_mfma_f32_16x16x32_bf16 v[62:65], v[54:57], v[218:221], v[62:65]
	v_mfma_f32_16x16x32_bf16 v[58:61], v[70:73], v[218:221], v[58:61]
	v_mfma_f32_16x16x32_bf16 v[46:49], v[54:57], v[226:229], v[46:49]
	v_mfma_f32_16x16x32_bf16 v[42:45], v[70:73], v[226:229], v[42:45]
	v_mfma_f32_16x16x32_bf16 v[14:17], v[54:57], v[234:237], v[14:17]
	v_mfma_f32_16x16x32_bf16 v[10:13], v[70:73], v[234:237], v[10:13]
	s_setprio 0
	s_setprio 1
	v_mfma_f32_16x16x32_bf16 v[18:21], v[170:173], v[198:201], v[18:21]
	v_mfma_f32_16x16x32_bf16 v[70:73], v[174:177], v[210:213], v[18:21]
	v_mfma_f32_16x16x32_bf16 v[18:21], v[190:193], v[198:201], v[22:25]
	v_mfma_f32_16x16x32_bf16 v[66:69], v[194:197], v[210:213], v[18:21]
	v_mfma_f32_16x16x32_bf16 v[18:21], v[170:173], v[214:217], v[26:29]
	v_mfma_f32_16x16x32_bf16 v[54:57], v[174:177], v[218:221], v[18:21]
	v_mfma_f32_16x16x32_bf16 v[18:21], v[190:193], v[214:217], v[30:33]
	v_mfma_f32_16x16x32_bf16 v[50:53], v[194:197], v[218:221], v[18:21]
	v_mfma_f32_16x16x32_bf16 v[18:21], v[170:173], v[222:225], v[38:41]
	v_mfma_f32_16x16x32_bf16 v[38:41], v[174:177], v[226:229], v[18:21]
	v_mfma_f32_16x16x32_bf16 v[18:21], v[190:193], v[222:225], v[34:37]
	v_mfma_f32_16x16x32_bf16 v[6:9], v[170:173], v[230:233], v[6:9]
	v_mfma_f32_16x16x32_bf16 v[2:5], v[190:193], v[230:233], v[2:5]
	v_mfma_f32_16x16x32_bf16 v[34:37], v[194:197], v[226:229], v[18:21]
	v_mfma_f32_16x16x32_bf16 v[6:9], v[174:177], v[234:237], v[6:9]
	v_mfma_f32_16x16x32_bf16 v[2:5], v[194:197], v[234:237], v[2:5]
	s_setprio 0
	s_barrier
	s_add_i32 vcc_hi, vcc_hi, 2
	s_add_u32 s72, s72, 0x100
	s_addc_u32 s73, s73, 0
	s_add_u32 s65, s65, 0x100
	s_addc_u32 vcc_lo, vcc_lo, 0
	s_cmp_gt_u32 vcc_hi, 13
	s_cbranch_scc0 .LBB0_945
.LBB0_948:
	s_cmp_lt_i32 s64, 64
	s_movk_i32 s0, 0x2400
	s_cselect_b32 s0, s0, 0x4800
	s_lshl_b32 s28, s70, 8
	s_lshl_b32 s1, s8, 10
	s_cmp_gt_i32 s64, 31
	s_cselect_b32 s0, s0, 0
	s_lshl_b32 s0, s0, 2
	v_readlane_b32 s8, v255, 41
	v_add_u32_e32 v170, s28, v180
	v_readlane_b32 s9, v255, 42
	s_add_u32 s8, s8, s0
	s_addc_u32 s9, s9, 0
	v_ashrrev_i32_e32 v171, 31, v170
	v_lshl_add_u64 v[26:27], v[170:171], 2, s[8:9]
	global_load_dwordx4 v[22:25], v[26:27], off offset:16
	global_load_dwordx4 v[30:33], v[26:27], off
	global_load_dwordx4 v[18:21], v[26:27], off offset:528
	s_nop 0
	global_load_dwordx4 v[26:29], v[26:27], off offset:512
	v_add_u32_e32 v190, s1, v188
	ds_read_b32 v0, v190
	s_lshl_b32 s7, s64, 8
	s_cmp_gt_i32 s70, 3
	s_cselect_b64 s[72:73], -1, 0
	v_readlane_b32 s36, v252, 63
	s_mov_b64 s[30:31], -1
	s_and_b64 vcc, exec, s[72:73]
	v_readlane_b32 s37, v253, 0
	v_readlane_b32 s40, v253, 3
	v_readlane_b32 s41, v253, 4
	v_readlane_b32 s42, v253, 5
	v_readlane_b32 s43, v253, 6
	v_readlane_b32 s44, v253, 7
	v_readlane_b32 s45, v253, 8
	v_readlane_b32 s46, v253, 9
	v_readlane_b32 s47, v253, 10
	v_readlane_b32 s48, v253, 11
	v_readlane_b32 s49, v253, 12
	v_readlane_b32 s50, v253, 13
	v_readlane_b32 s51, v253, 14
	v_readlane_b32 s38, v253, 1
	v_readlane_b32 s39, v253, 2
	s_cmp_gt_i32 s70, 3
	s_cbranch_scc1 .Lg2pf_skip
	v_readlane_b32 s100, v254, 19
	v_readlane_b32 s101, v254, 20
	v_add_u32_e32 v244, s7, v147
	v_ashrrev_i32_e32 v245, 31, v244
	v_lshlrev_b64 v[244:245], 12, v[244:245]
	s_nop 1
	v_lshl_add_u64 v[244:245], s[100:101], 0, v[244:245]
	v_lshl_add_u64 v[244:245], v[170:171], 1, v[244:245]
	s_mov_b32 s100, 0xffffe000
	s_mov_b32 s101, -1
	v_lshl_add_u64 v[244:245], v[244:245], 0, s[100:101]
	global_load_dwordx4 v[210:213], v[244:245], off
	global_load_dwordx4 v[214:217], v[244:245], off offset:256
	s_mov_b32 s100, 0x10000
	s_mov_b32 s101, 0
	v_lshl_add_u64 v[246:247], v[244:245], 0, s[100:101]
	global_load_dwordx4 v[218:221], v[246:247], off
	global_load_dwordx4 v[222:225], v[246:247], off offset:256
	v_lshl_add_u64 v[246:247], v[246:247], 0, s[100:101]
	global_load_dwordx4 v[226:229], v[246:247], off
	global_load_dwordx4 v[230:233], v[246:247], off offset:256
	v_lshl_add_u64 v[246:247], v[246:247], 0, s[100:101]
	global_load_dwordx4 v[234:237], v[246:247], off
	global_load_dwordx4 v[240:243], v[246:247], off offset:256
	s_waitcnt vmcnt(8) lgkmcnt(0)
	s_branch .Lg2pf_join

; #define PG8_BAR __builtin_amdgcn_s_barrier()
; template <class Epi>
; __device__ __forceinline__ void gemm_phase(LAS unsigned char* lds, const int tid, const Gemm g, const StaticOrder& S, const Epi& E) {
;     ...
;         if (wr == 0) PG8_BAR;
.Lg2pf_join:
	s_cmp_lg_u64 s[4:5], 0
	s_cbranch_scc0 .Lal_2
	s_barrier

; #define PG8_STAGE(bufoff, gbase, voff) do { _Pragma("unroll") for (int _i = 0; _i < 2; ++_i) \
;         __builtin_amdgcn_global_load_lds((const unsigned*)((const char*)(gbase) + (voff)[_i]), (LAS unsigned*)(lds + (bufoff) + ldsw + _i * 8192), 16, 0, 0); } while (0)
; #define PG8_LDA(dst, b, h) do { _Pragma("unroll") for (int m = 0; m < 4; ++m) _Pragma("unroll") for (int k = 0; k < 2; ++k) dst[m][k] = *(const LAS bf16x8*)(lds + PG8_SA(b, h) + aoff + m * 2048 + k * 1024); } while (0)
; #define PG8_LDB(dst, b, h) do { _Pragma("unroll") for (int n = 0; n < 2; ++n) _Pragma("unroll") for (int k = 0; k < 2; ++k) dst[n][k] = *(const LAS bf16x8*)(lds + PG8_SB(b, h) + boff + n * 2048 + k * 1024); } while (0)
; #define PG8_MMA(ai, bj, At, Bt) do { __builtin_amdgcn_s_setprio(1); _Pragma("unroll") for (int m = 0; m < 4; ++m) _Pragma("unroll") for (int n = 0; n < 2; ++n) _Pragma("unroll") for (int k = 0; k < 2; ++k) \
;         acc[ai][bj][m][n] = __builtin_amdgcn_mfma_f32_16x16x32_bf16(Bt[n][k], At[m][k], acc[ai][bj][m][n], 0, 0, 0); __builtin_amdgcn_s_setprio(0); } while (0)
; #define PG8_WAIT_V(n) asm volatile("s_waitcnt vmcnt(" #n ")" ::: "memory")
; #define PG8_WAIT_L(n) asm volatile("s_waitcnt lgkmcnt(" #n ")" ::: "memory")
; #define PG8_BAR __builtin_amdgcn_s_barrier()
; #define PG8_SCHED __builtin_amdgcn_sched_barrier(0)
; template <class Epi>
; __device__ __forceinline__ void gemm_phase(LAS unsigned char* lds, const int tid, const Gemm g, const StaticOrder& S, const Epi& E) {
;     ...
;         for (int t = 0; t < nt; t += 2) {
;             const bool last = (t == nt - 2);
;             const char* a1 = cA + (size_t)(t + 1) * kstep;
;             const char* a2 = last ? nA : cA + (size_t)(t + 2) * kstep; const char* b2 = last ? nB : cB + (size_t)(t + 2) * kstep;
;             const char* a3 = a2 + kstep; const char* b3 = b2 + kstep;
;             PG8_LDB(B0, 0, 0); PG8_LDB(B1, 0, 1); PG8_SCHED; PG8_LDA(At, 0, 0); PG8_STAGE(PG8_SA(1, 1), a1 + hstepA, voffA);
;             PG8_WAIT_V(8); PG8_WAIT_L(0); PG8_BAR; PG8_MMA(0, 0, At, B0); PG8_MMA(0, 1, At, B1); PG8_BAR; PG8_SCHED;
;             PG8_LDA(At, 0, 1); PG8_STAGE(PG8_SB(0, 0), b2, voffB); PG8_STAGE(PG8_SB(0, 1), b2 + hstepB, voffB); PG8_STAGE(PG8_SA(0, 0), a2, voffA);
;             PG8_WAIT_V(8); PG8_WAIT_L(0); PG8_BAR; PG8_MMA(1, 0, At, B0); PG8_MMA(1, 1, At, B1); PG8_BAR; PG8_SCHED;
.LBB0_1284:
	s_add_u32 s2, s66, 0xfff80080
	s_addc_u32 s3, s67, -1
	s_add_i32 vcc_hi, 0, 0x10000
	s_cmp_eq_u32 vcc_lo, 12
	s_cselect_b32 s69, s11, s3
	s_cselect_b32 s68, s88, s2
	v_add_u32_e32 v144, vcc_hi, v171
	s_cselect_b32 s31, s9, s93
	s_cselect_b32 s30, s89, s92
	s_add_i32 s0, 0, 0x14000
	ds_read_b128 v[140:143], v144
	ds_read_b128 v[176:179], v144 offset:1024
	ds_read_b128 v[180:183], v144 offset:2048
	ds_read_b128 v[184:187], v144 offset:3072
	v_add_u32_e32 v144, s0, v171
	ds_read_b128 v[188:191], v144
	ds_read_b128 v[192:195], v144 offset:1024
	ds_read_b128 v[196:199], v144 offset:2048
	ds_read_b128 v[200:203], v144 offset:3072
	v_lshl_add_u64 v[144:145], s[66:67], 0, v[136:137]
	s_add_i32 m0, s71, 0xc000
	s_nop 0
	global_load_lds_dwordx4 v[144:145], off
	v_lshl_add_u64 v[144:145], s[66:67], 0, v[138:139]
	s_add_i32 m0, s71, 0xe000
	s_nop 0
	global_load_lds_dwordx4 v[144:145], off
	ds_read_b128 v[210:213], v174
	ds_read_b128 v[214:217], v174 offset:1024
	ds_read_b128 v[218:221], v174 offset:2048
	ds_read_b128 v[222:225], v174 offset:3072
	ds_read_b128 v[226:229], v174 offset:4096
	ds_read_b128 v[230:233], v174 offset:5120
	ds_read_b128 v[234:237], v174 offset:6144
	ds_read_b128 v[238:241], v174 offset:7168
	s_waitcnt vmcnt(8)
	s_waitcnt lgkmcnt(0)
	s_barrier
	s_setprio 1
	s_waitcnt lgkmcnt(0)
	v_mfma_f32_16x16x32_bf16 v[126:129], v[140:143], v[210:213], v[126:129]
	v_mfma_f32_16x16x32_bf16 v[122:125], v[180:183], v[210:213], v[122:125]
	v_mfma_f32_16x16x32_bf16 v[118:121], v[140:143], v[218:221], v[118:121]
	v_mfma_f32_16x16x32_bf16 v[110:113], v[180:183], v[218:221], v[110:113]
	v_mfma_f32_16x16x32_bf16 v[94:97], v[140:143], v[226:229], v[94:97]
	v_mfma_f32_16x16x32_bf16 v[90:93], v[180:183], v[226:229], v[90:93]
	v_mfma_f32_16x16x32_bf16 v[86:89], v[140:143], v[234:237], v[86:89]
	v_mfma_f32_16x16x32_bf16 v[78:81], v[180:183], v[234:237], v[78:81]
	v_mfma_f32_16x16x32_bf16 v[126:129], v[176:179], v[214:217], v[126:129]
	v_mfma_f32_16x16x32_bf16 v[122:125], v[184:187], v[214:217], v[122:125]
	v_mfma_f32_16x16x32_bf16 v[118:121], v[176:179], v[222:225], v[118:121]
	v_mfma_f32_16x16x32_bf16 v[110:113], v[184:187], v[222:225], v[110:113]
	v_mfma_f32_16x16x32_bf16 v[94:97], v[176:179], v[230:233], v[94:97]
	v_mfma_f32_16x16x32_bf16 v[90:93], v[184:187], v[230:233], v[90:93]
	v_mfma_f32_16x16x32_bf16 v[86:89], v[176:179], v[238:241], v[86:89]
	v_mfma_f32_16x16x32_bf16 v[78:81], v[184:187], v[238:241], v[78:81]
	s_setprio 0
	s_setprio 1
	v_mfma_f32_16x16x32_bf16 v[114:117], v[188:191], v[210:213], v[114:117]
	v_mfma_f32_16x16x32_bf16 v[106:109], v[196:199], v[210:213], v[106:109]
	v_mfma_f32_16x16x32_bf16 v[102:105], v[188:191], v[218:221], v[102:105]
	v_mfma_f32_16x16x32_bf16 v[98:101], v[196:199], v[218:221], v[98:101]
	v_mfma_f32_16x16x32_bf16 v[82:85], v[188:191], v[226:229], v[82:85]
	v_mfma_f32_16x16x32_bf16 v[74:77], v[196:199], v[226:229], v[74:77]
	v_mfma_f32_16x16x32_bf16 v[70:73], v[188:191], v[234:237], v[70:73]
	v_mfma_f32_16x16x32_bf16 v[66:69], v[196:199], v[234:237], v[66:69]
	v_mfma_f32_16x16x32_bf16 v[114:117], v[192:195], v[214:217], v[114:117]
	v_mfma_f32_16x16x32_bf16 v[106:109], v[200:203], v[214:217], v[106:109]
	v_mfma_f32_16x16x32_bf16 v[102:105], v[192:195], v[222:225], v[102:105]
	v_mfma_f32_16x16x32_bf16 v[98:101], v[200:203], v[222:225], v[98:101]
	v_mfma_f32_16x16x32_bf16 v[82:85], v[192:195], v[230:233], v[82:85]
	v_mfma_f32_16x16x32_bf16 v[74:77], v[200:203], v[230:233], v[74:77]
	v_mfma_f32_16x16x32_bf16 v[70:73], v[192:195], v[238:241], v[70:73]
	v_mfma_f32_16x16x32_bf16 v[66:69], v[200:203], v[238:241], v[66:69]
	s_setprio 0
	s_barrier
	s_add_i32 s1, vcc_hi, s28
	v_lshl_add_u64 v[144:145], s[30:31], 0, v[0:1]
	s_mov_b32 m0, s1
	s_nop 0
	global_load_lds_dwordx4 v[144:145], off
	s_add_i32 m0, s1, 0x2000
	s_add_u32 s2, s30, 0x40000
	v_lshl_add_u64 v[162:163], s[30:31], 0, v[130:131]
	s_addc_u32 s3, s31, 0
	s_add_i32 s0, s0, s28
	global_load_lds_dwordx4 v[162:163], off
	v_lshl_add_u64 v[164:165], s[2:3], 0, v[0:1]
	s_mov_b32 m0, s0
	v_lshl_add_u64 v[206:207], s[68:69], 0, v[132:133]
	global_load_lds_dwordx4 v[164:165], off
	v_lshl_add_u64 v[164:165], s[2:3], 0, v[130:131]
	s_add_i32 m0, s0, 0x2000
	s_nop 0
	global_load_lds_dwordx4 v[164:165], off
	v_lshl_add_u64 v[164:165], s[68:69], 0, v[134:135]
	s_mov_b32 m0, s71
	s_nop 0
	global_load_lds_dwordx4 v[164:165], off
	s_mov_b32 m0, s72
	s_nop 0
	global_load_lds_dwordx4 v[206:207], off
	ds_read_b128 v[210:213], v174 offset:16384
	ds_read_b128 v[214:217], v174 offset:17408
	ds_read_b128 v[218:221], v174 offset:18432
	ds_read_b128 v[222:225], v174 offset:19456
	ds_read_b128 v[226:229], v174 offset:20480
	ds_read_b128 v[230:233], v174 offset:21504
	ds_read_b128 v[234:237], v174 offset:22528
	ds_read_b128 v[238:241], v174 offset:23552
	s_waitcnt vmcnt(8)
	s_waitcnt lgkmcnt(0)
	s_barrier
; #define PG8_STAGE(bufoff, gbase, voff) do { _Pragma("unroll") for (int _i = 0; _i < 2; ++_i) \
;         __builtin_amdgcn_global_load_lds((const unsigned*)((const char*)(gbase) + (voff)[_i]), (LAS unsigned*)(lds + (bufoff) + ldsw + _i * 8192), 16, 0, 0); } while (0)
; #define PG8_LDA(dst, b, h) do { _Pragma("unroll") for (int m = 0; m < 4; ++m) _Pragma("unroll") for (int k = 0; k < 2; ++k) dst[m][k] = *(const LAS bf16x8*)(lds + PG8_SA(b, h) + aoff + m * 2048 + k * 1024); } while (0)
; #define PG8_LDB(dst, b, h) do { _Pragma("unroll") for (int n = 0; n < 2; ++n) _Pragma("unroll") for (int k = 0; k < 2; ++k) dst[n][k] = *(const LAS bf16x8*)(lds + PG8_SB(b, h) + boff + n * 2048 + k * 1024); } while (0)
; #define PG8_MMA(ai, bj, At, Bt) do { __builtin_amdgcn_s_setprio(1); _Pragma("unroll") for (int m = 0; m < 4; ++m) _Pragma("unroll") for (int n = 0; n < 2; ++n) _Pragma("unroll") for (int k = 0; k < 2; ++k) \
;         acc[ai][bj][m][n] = __builtin_amdgcn_mfma_f32_16x16x32_bf16(Bt[n][k], At[m][k], acc[ai][bj][m][n], 0, 0, 0); __builtin_amdgcn_s_setprio(0); } while (0)
; #define PG8_WAIT_V(n) asm volatile("s_waitcnt vmcnt(" #n ")" ::: "memory")
; #define PG8_WAIT_L(n) asm volatile("s_waitcnt lgkmcnt(" #n ")" ::: "memory")
; #define PG8_BAR __builtin_amdgcn_s_barrier()
; #define PG8_SCHED __builtin_amdgcn_sched_barrier(0)
; template <class Epi>
; __device__ __forceinline__ void gemm_phase(LAS unsigned char* lds, const int tid, const Gemm g, const StaticOrder& S, const Epi& E) {
;     ...
;             PG8_WAIT_V(8); PG8_WAIT_L(0); PG8_BAR; PG8_MMA(1, 0, At, B0); PG8_MMA(1, 1, At, B1); PG8_BAR; PG8_SCHED;
;             PG8_LDB(B0, 1, 0); PG8_LDB(B1, 1, 1); PG8_SCHED; PG8_LDA(At, 1, 0); PG8_STAGE(PG8_SA(0, 1), a2 + hstepA, voffA);
;             PG8_WAIT_V(8); PG8_WAIT_L(0); PG8_BAR; PG8_MMA(0, 0, At, B0); PG8_MMA(0, 1, At, B1); PG8_BAR; PG8_SCHED;
	s_setprio 1
	s_waitcnt lgkmcnt(0)
	v_mfma_f32_16x16x32_bf16 v[62:65], v[140:143], v[210:213], v[62:65]
	v_mfma_f32_16x16x32_bf16 v[58:61], v[180:183], v[210:213], v[58:61]
	v_mfma_f32_16x16x32_bf16 v[54:57], v[140:143], v[218:221], v[54:57]
	v_mfma_f32_16x16x32_bf16 v[46:49], v[180:183], v[218:221], v[46:49]
	v_mfma_f32_16x16x32_bf16 v[30:33], v[140:143], v[226:229], v[30:33]
	v_mfma_f32_16x16x32_bf16 v[26:29], v[180:183], v[226:229], v[26:29]
	v_mfma_f32_16x16x32_bf16 v[22:25], v[140:143], v[234:237], v[22:25]
	v_mfma_f32_16x16x32_bf16 v[14:17], v[180:183], v[234:237], v[14:17]
	v_mfma_f32_16x16x32_bf16 v[62:65], v[176:179], v[214:217], v[62:65]
	v_mfma_f32_16x16x32_bf16 v[58:61], v[184:187], v[214:217], v[58:61]
	v_mfma_f32_16x16x32_bf16 v[54:57], v[176:179], v[222:225], v[54:57]
	v_mfma_f32_16x16x32_bf16 v[46:49], v[184:187], v[222:225], v[46:49]
	v_mfma_f32_16x16x32_bf16 v[30:33], v[176:179], v[230:233], v[30:33]
	v_mfma_f32_16x16x32_bf16 v[26:29], v[184:187], v[230:233], v[26:29]
	v_mfma_f32_16x16x32_bf16 v[22:25], v[176:179], v[238:241], v[22:25]
	v_mfma_f32_16x16x32_bf16 v[14:17], v[184:187], v[238:241], v[14:17]
	s_setprio 0
	s_setprio 1
	v_mfma_f32_16x16x32_bf16 v[50:53], v[188:191], v[210:213], v[50:53]
	v_mfma_f32_16x16x32_bf16 v[42:45], v[196:199], v[210:213], v[42:45]
	v_mfma_f32_16x16x32_bf16 v[38:41], v[188:191], v[218:221], v[38:41]
	v_mfma_f32_16x16x32_bf16 v[34:37], v[196:199], v[218:221], v[34:37]
	v_mfma_f32_16x16x32_bf16 v[18:21], v[188:191], v[226:229], v[18:21]
	v_mfma_f32_16x16x32_bf16 v[10:13], v[196:199], v[226:229], v[10:13]
	v_mfma_f32_16x16x32_bf16 v[6:9], v[188:191], v[234:237], v[6:9]
	v_mfma_f32_16x16x32_bf16 v[2:5], v[196:199], v[234:237], v[2:5]
	v_mfma_f32_16x16x32_bf16 v[50:53], v[192:195], v[214:217], v[50:53]
	v_mfma_f32_16x16x32_bf16 v[42:45], v[200:203], v[214:217], v[42:45]
	v_mfma_f32_16x16x32_bf16 v[38:41], v[192:195], v[222:225], v[38:41]
	v_mfma_f32_16x16x32_bf16 v[34:37], v[200:203], v[222:225], v[34:37]
	v_mfma_f32_16x16x32_bf16 v[18:21], v[192:195], v[230:233], v[18:21]
	v_mfma_f32_16x16x32_bf16 v[10:13], v[200:203], v[230:233], v[10:13]
	v_mfma_f32_16x16x32_bf16 v[6:9], v[192:195], v[238:241], v[6:9]
	v_mfma_f32_16x16x32_bf16 v[2:5], v[200:203], v[238:241], v[2:5]
	s_setprio 0
	s_barrier
	s_add_i32 s0, 0, 0x18000
	v_add_u32_e32 v175, s0, v171
	s_add_i32 s1, 0, 0x1c000
	ds_read_b128 v[140:143], v175
	ds_read_b128 v[176:179], v175 offset:1024
	ds_read_b128 v[180:183], v175 offset:2048
	ds_read_b128 v[184:187], v175 offset:3072
	v_add_u32_e32 v175, s1, v171
	ds_read_b128 v[188:191], v175
	ds_read_b128 v[192:195], v175 offset:1024
	ds_read_b128 v[196:199], v175 offset:2048
	ds_read_b128 v[200:203], v175 offset:3072
	s_add_u32 s2, s68, 0x80000
	s_addc_u32 s3, s69, 0
	s_mov_b32 m0, s73
	v_lshl_add_u64 v[242:243], s[2:3], 0, v[134:135]
	global_load_lds_dwordx4 v[242:243], off
	v_lshl_add_u64 v[242:243], s[2:3], 0, v[132:133]
	s_mov_b32 m0, s74
	s_nop 0
	global_load_lds_dwordx4 v[242:243], off
	ds_read_b128 v[210:213], v174 offset:32768
	ds_read_b128 v[214:217], v174 offset:33792
	ds_read_b128 v[218:221], v174 offset:34816
	ds_read_b128 v[222:225], v174 offset:35840
	ds_read_b128 v[226:229], v174 offset:36864
	ds_read_b128 v[230:233], v174 offset:37888
	ds_read_b128 v[234:237], v174 offset:38912
	ds_read_b128 v[238:241], v174 offset:39936
	s_waitcnt vmcnt(8)
	s_waitcnt lgkmcnt(0)
	s_barrier
	s_setprio 1
	s_waitcnt lgkmcnt(0)
	v_mfma_f32_16x16x32_bf16 v[126:129], v[140:143], v[210:213], v[126:129]
	v_mfma_f32_16x16x32_bf16 v[122:125], v[180:183], v[210:213], v[122:125]
	v_mfma_f32_16x16x32_bf16 v[118:121], v[140:143], v[218:221], v[118:121]
	v_mfma_f32_16x16x32_bf16 v[110:113], v[180:183], v[218:221], v[110:113]
	v_mfma_f32_16x16x32_bf16 v[94:97], v[140:143], v[226:229], v[94:97]
	v_mfma_f32_16x16x32_bf16 v[90:93], v[180:183], v[226:229], v[90:93]
	v_mfma_f32_16x16x32_bf16 v[86:89], v[140:143], v[234:237], v[86:89]
	v_mfma_f32_16x16x32_bf16 v[78:81], v[180:183], v[234:237], v[78:81]
	v_mfma_f32_16x16x32_bf16 v[126:129], v[176:179], v[214:217], v[126:129]
	v_mfma_f32_16x16x32_bf16 v[122:125], v[184:187], v[214:217], v[122:125]
	v_mfma_f32_16x16x32_bf16 v[118:121], v[176:179], v[222:225], v[118:121]
	v_mfma_f32_16x16x32_bf16 v[110:113], v[184:187], v[222:225], v[110:113]
	v_mfma_f32_16x16x32_bf16 v[94:97], v[176:179], v[230:233], v[94:97]
	v_mfma_f32_16x16x32_bf16 v[90:93], v[184:187], v[230:233], v[90:93]
	v_mfma_f32_16x16x32_bf16 v[86:89], v[176:179], v[238:241], v[86:89]
	v_mfma_f32_16x16x32_bf16 v[78:81], v[184:187], v[238:241], v[78:81]
	s_setprio 0
	s_setprio 1
	v_mfma_f32_16x16x32_bf16 v[114:117], v[188:191], v[210:213], v[114:117]
	v_mfma_f32_16x16x32_bf16 v[106:109], v[196:199], v[210:213], v[106:109]
	v_mfma_f32_16x16x32_bf16 v[102:105], v[188:191], v[218:221], v[102:105]
	v_mfma_f32_16x16x32_bf16 v[98:101], v[196:199], v[218:221], v[98:101]
	v_mfma_f32_16x16x32_bf16 v[82:85], v[188:191], v[226:229], v[82:85]
	v_mfma_f32_16x16x32_bf16 v[74:77], v[196:199], v[226:229], v[74:77]
	v_mfma_f32_16x16x32_bf16 v[70:73], v[188:191], v[234:237], v[70:73]
	v_mfma_f32_16x16x32_bf16 v[66:69], v[196:199], v[234:237], v[66:69]
	v_mfma_f32_16x16x32_bf16 v[114:117], v[192:195], v[214:217], v[114:117]
	v_mfma_f32_16x16x32_bf16 v[106:109], v[200:203], v[214:217], v[106:109]
	v_mfma_f32_16x16x32_bf16 v[102:105], v[192:195], v[222:225], v[102:105]
	v_mfma_f32_16x16x32_bf16 v[98:101], v[200:203], v[222:225], v[98:101]
	v_mfma_f32_16x16x32_bf16 v[82:85], v[192:195], v[230:233], v[82:85]
	v_mfma_f32_16x16x32_bf16 v[74:77], v[200:203], v[230:233], v[74:77]
	v_mfma_f32_16x16x32_bf16 v[70:73], v[192:195], v[238:241], v[70:73]
	v_mfma_f32_16x16x32_bf16 v[66:69], v[200:203], v[238:241], v[66:69]
	s_setprio 0
	s_barrier
; #define PG8_STAGE(bufoff, gbase, voff) do { _Pragma("unroll") for (int _i = 0; _i < 2; ++_i) \
;         __builtin_amdgcn_global_load_lds((const unsigned*)((const char*)(gbase) + (voff)[_i]), (LAS unsigned*)(lds + (bufoff) + ldsw + _i * 8192), 16, 0, 0); } while (0)
; #define PG8_LDA(dst, b, h) do { _Pragma("unroll") for (int m = 0; m < 4; ++m) _Pragma("unroll") for (int k = 0; k < 2; ++k) dst[m][k] = *(const LAS bf16x8*)(lds + PG8_SA(b, h) + aoff + m * 2048 + k * 1024); } while (0)
; #define PG8_MMA(ai, bj, At, Bt) do { __builtin_amdgcn_s_setprio(1); _Pragma("unroll") for (int m = 0; m < 4; ++m) _Pragma("unroll") for (int n = 0; n < 2; ++n) _Pragma("unroll") for (int k = 0; k < 2; ++k) \
;         acc[ai][bj][m][n] = __builtin_amdgcn_mfma_f32_16x16x32_bf16(Bt[n][k], At[m][k], acc[ai][bj][m][n], 0, 0, 0); __builtin_amdgcn_s_setprio(0); } while (0)
; #define PG8_WAIT_V(n) asm volatile("s_waitcnt vmcnt(" #n ")" ::: "memory")
; #define PG8_WAIT_L(n) asm volatile("s_waitcnt lgkmcnt(" #n ")" ::: "memory")
; #define PG8_BAR __builtin_amdgcn_s_barrier()
; template <class Epi>
; __device__ __forceinline__ void gemm_phase(LAS unsigned char* lds, const int tid, const Gemm g, const StaticOrder& S, const Epi& E) {
;     ...
;             PG8_LDA(At, 1, 1); PG8_STAGE(PG8_SB(1, 0), b3, voffB); PG8_STAGE(PG8_SB(1, 1), b3 + hstepB, voffB); PG8_STAGE(PG8_SA(1, 0), a3, voffA);
;             PG8_WAIT_V(8); PG8_WAIT_L(0); PG8_BAR; PG8_MMA(1, 0, At, B0); PG8_MMA(1, 1, At, B1); PG8_BAR; PG8_SCHED;
;         }
;         if (wr == 0) PG8_BAR;
;     template <int NA, int NM> __device__ __forceinline__ void operator()(const f32x4 (&acc)[NA][2][NM][2], const pg8::Unit& u, int ro, int wr, int wc, int fr, int fq) const {
;         const int colt = u.pn * 256 + wc * 32 + 8 * fq;
; #pragma unroll
;         for (int ai = 0; ai < NA; ++ai) {
; #pragma unroll
;             for (int mp = 0; mp < NM; mp += 2) {
;             u32x4 g[4][2], t[4][2];
; #pragma unroll
;             for (int m = mp; m < (NM < 2 ? NM : mp + 2); ++m)
; #pragma unroll
;                 for (int bj = 0; bj < 2; ++bj) {
;                     const size_t o = (size_t)(u.pm * 256 + ro + ai * 128 + wr * 64 + m * 16 + fr) * D + colt + bj * 128;
;                     g[m][bj] = *(const u32x4*)(SG + o);
;                     if (PASS == 2) t[m][bj] = *(const u32x4*)(T + o);
;                 }
	s_add_i32 s0, s0, s28
	v_lshl_add_u64 v[144:145], v[144:145], 0, s[36:37]
	s_mov_b32 m0, s0
	s_nop 0
	global_load_lds_dwordx4 v[144:145], off
	s_add_i32 m0, s0, 0x2000
	s_add_u32 s2, s30, 0x40080
	v_lshl_add_u64 v[144:145], v[162:163], 0, s[36:37]
	s_addc_u32 s3, s31, 0
	s_add_i32 s0, s1, s28
	global_load_lds_dwordx4 v[144:145], off
	v_lshl_add_u64 v[144:145], s[2:3], 0, v[0:1]
	s_mov_b32 m0, s0
	s_nop 0
	global_load_lds_dwordx4 v[144:145], off
	v_lshl_add_u64 v[144:145], s[2:3], 0, v[130:131]
	s_add_i32 m0, s0, 0x2000
	s_nop 0
	global_load_lds_dwordx4 v[144:145], off
	v_lshl_add_u64 v[144:145], v[164:165], 0, s[36:37]
	s_mov_b32 m0, s75
	s_nop 0
	global_load_lds_dwordx4 v[144:145], off
	v_lshl_add_u64 v[144:145], v[206:207], 0, s[36:37]
	s_mov_b32 m0, s76
	s_nop 0
	global_load_lds_dwordx4 v[144:145], off
	ds_read_b128 v[210:213], v174 offset:49152
	ds_read_b128 v[214:217], v174 offset:50176
	ds_read_b128 v[218:221], v174 offset:51200
	ds_read_b128 v[222:225], v174 offset:52224
	ds_read_b128 v[226:229], v174 offset:53248
	ds_read_b128 v[230:233], v174 offset:54272
	ds_read_b128 v[234:237], v174 offset:55296
	ds_read_b128 v[238:241], v174 offset:56320
	s_waitcnt vmcnt(8)
	s_waitcnt lgkmcnt(0)
	s_barrier
	s_setprio 1
	s_waitcnt lgkmcnt(0)
	v_mfma_f32_16x16x32_bf16 v[62:65], v[140:143], v[210:213], v[62:65]
	v_mfma_f32_16x16x32_bf16 v[58:61], v[180:183], v[210:213], v[58:61]
	v_mfma_f32_16x16x32_bf16 v[54:57], v[140:143], v[218:221], v[54:57]
	v_mfma_f32_16x16x32_bf16 v[46:49], v[180:183], v[218:221], v[46:49]
	v_mfma_f32_16x16x32_bf16 v[30:33], v[140:143], v[226:229], v[30:33]
	v_mfma_f32_16x16x32_bf16 v[26:29], v[180:183], v[226:229], v[26:29]
	v_mfma_f32_16x16x32_bf16 v[22:25], v[140:143], v[234:237], v[22:25]
	v_mfma_f32_16x16x32_bf16 v[14:17], v[180:183], v[234:237], v[14:17]
	v_mfma_f32_16x16x32_bf16 v[62:65], v[176:179], v[214:217], v[62:65]
	v_mfma_f32_16x16x32_bf16 v[58:61], v[184:187], v[214:217], v[58:61]
	v_mfma_f32_16x16x32_bf16 v[54:57], v[176:179], v[222:225], v[54:57]
	v_mfma_f32_16x16x32_bf16 v[46:49], v[184:187], v[222:225], v[46:49]
	v_mfma_f32_16x16x32_bf16 v[30:33], v[176:179], v[230:233], v[30:33]
	v_mfma_f32_16x16x32_bf16 v[26:29], v[184:187], v[230:233], v[26:29]
	v_mfma_f32_16x16x32_bf16 v[22:25], v[176:179], v[238:241], v[22:25]
	v_mfma_f32_16x16x32_bf16 v[14:17], v[184:187], v[238:241], v[14:17]
	s_setprio 0
	s_setprio 1
	v_mfma_f32_16x16x32_bf16 v[50:53], v[188:191], v[210:213], v[50:53]
	v_mfma_f32_16x16x32_bf16 v[42:45], v[196:199], v[210:213], v[42:45]
	v_mfma_f32_16x16x32_bf16 v[38:41], v[188:191], v[218:221], v[38:41]
	v_mfma_f32_16x16x32_bf16 v[34:37], v[196:199], v[218:221], v[34:37]
	v_mfma_f32_16x16x32_bf16 v[18:21], v[188:191], v[226:229], v[18:21]
	v_mfma_f32_16x16x32_bf16 v[10:13], v[196:199], v[226:229], v[10:13]
	v_mfma_f32_16x16x32_bf16 v[6:9], v[188:191], v[234:237], v[6:9]
	v_mfma_f32_16x16x32_bf16 v[2:5], v[196:199], v[234:237], v[2:5]
	v_mfma_f32_16x16x32_bf16 v[50:53], v[192:195], v[214:217], v[50:53]
	v_mfma_f32_16x16x32_bf16 v[42:45], v[200:203], v[214:217], v[42:45]
	v_mfma_f32_16x16x32_bf16 v[38:41], v[192:195], v[222:225], v[38:41]
	v_mfma_f32_16x16x32_bf16 v[34:37], v[200:203], v[222:225], v[34:37]
	v_mfma_f32_16x16x32_bf16 v[18:21], v[192:195], v[230:233], v[18:21]
	v_mfma_f32_16x16x32_bf16 v[10:13], v[200:203], v[230:233], v[10:13]
	v_mfma_f32_16x16x32_bf16 v[6:9], v[192:195], v[238:241], v[6:9]
	v_mfma_f32_16x16x32_bf16 v[2:5], v[200:203], v[238:241], v[2:5]
	s_setprio 0
	s_barrier
	s_add_i32 vcc_lo, vcc_lo, 2
	s_add_u32 s66, s66, 0x100
	s_addc_u32 s67, s67, 0
	s_add_u32 s92, s92, 0x100
	s_addc_u32 s93, s93, 0
	s_cmp_gt_u32 vcc_lo, 13
	s_cbranch_scc0 .LBB0_1284
	s_mov_b32 s92, 0x2c000
	s_mov_b32 s93, 0x2e000
.LBB0_1287:
	v_lshl_or_b32 v140, s83, 8, v173
	v_lshl_add_u32 v144, s82, 8, v170
	v_ashrrev_i32_e32 v141, 31, v140
	v_lshlrev_b64 v[140:141], 1, v[140:141]
	v_ashrrev_i32_e32 v145, 31, v144
	v_lshl_add_u64 v[142:143], s[22:23], 0, v[140:141]
	v_lshlrev_b64 v[162:163], 11, v[144:145]
	v_lshl_add_u64 v[164:165], v[142:143], 0, v[162:163]
	global_load_dwordx4 v[176:179], v[164:165], off
	global_load_dwordx4 v[180:183], v[164:165], off offset:256
	v_or_b32_e32 v164, 16, v144
	v_ashrrev_i32_e32 v165, 31, v164
	v_lshlrev_b64 v[164:165], 11, v[164:165]
	v_lshl_add_u64 v[188:189], v[142:143], 0, v[164:165]
	global_load_dwordx4 v[184:187], v[188:189], off
	s_nop 0
	global_load_dwordx4 v[188:191], v[188:189], off offset:256
	v_readlane_b32 s36, v249, 8
	v_readlane_b32 s50, v249, 22
	v_readlane_b32 s51, v249, 23
	s_mov_b64 s[30:31], -1
	s_andn2_b64 vcc, exec, s[64:65]
	v_readlane_b32 s37, v249, 9
	v_readlane_b32 s38, v249, 10
	v_readlane_b32 s39, v249, 11
	v_readlane_b32 s40, v249, 12
	v_readlane_b32 s41, v249, 13
	v_readlane_b32 s42, v249, 14
	v_readlane_b32 s43, v249, 15
	v_readlane_b32 s44, v249, 16
	v_readlane_b32 s45, v249, 17
	v_readlane_b32 s46, v249, 18
	v_readlane_b32 s47, v249, 19
	v_readlane_b32 s48, v249, 20
	v_readlane_b32 s49, v249, 21
	s_waitcnt vmcnt(0)
	s_cmp_lg_u64 s[6:7], 0
	s_cbranch_scc0 .Lal_4
	s_barrier
; __device__ __forceinline__ unsigned pk2(float lo, float hi) { const f32x2 v = {lo, hi}; const bf16x2_t b = __builtin_convertvector(v, bf16x2_t); return __builtin_bit_cast(unsigned, b); }
;     template <int NA, int NM> __device__ __forceinline__ void operator()(const f32x4 (&acc)[NA][2][NM][2], const pg8::Unit& u, int ro, int wr, int wc, int fr, int fq) const {
;     ...
; #pragma unroll
;             for (int m = mp; m < (NM < 2 ? NM : mp + 2); ++m)
; #pragma unroll
;                 for (int bj = 0; bj < 2; ++bj) {
;                     const size_t o = (size_t)(u.pm * 256 + ro + ai * 128 + wr * 64 + m * 16 + fr) * D + colt + bj * 128;
;                     const u32x4 gg = g[m][bj];
;                     f32x4 v0 = acc[ai][bj][m][0], v1 = acc[ai][bj][m][1];
;                     v0.x *= bflo(gg.x); v0.y *= bfhi(gg.x); v0.z *= bflo(gg.y); v0.w *= bfhi(gg.y);
;                     v1.x *= bflo(gg.z); v1.y *= bfhi(gg.z); v1.z *= bflo(gg.w); v1.w *= bfhi(gg.w);
;                     if (PASS == 2) { const u32x4 tt = t[m][bj];
;                         v0.x += bflo(tt.x); v0.y += bfhi(tt.x); v0.z += bflo(tt.y); v0.w += bfhi(tt.y);
;                         v1.x += bflo(tt.z); v1.y += bfhi(tt.z); v1.z += bflo(tt.w); v1.w += bfhi(tt.w); }
;                     u32x4 w; w.x = pk2(v0.x, v0.y); w.y = pk2(v0.z, v0.w); w.z = pk2(v1.x, v1.y); w.w = pk2(v1.z, v1.w);
;                     *(u32x4*)(Y + o) = w;
;                 }
.Lal_4:
	v_lshlrev_b32_e32 v192, 16, v176
	v_and_b32_e32 v193, 0xffff0000, v176
	v_lshlrev_b32_e32 v176, 16, v177
	v_and_b32_e32 v177, 0xffff0000, v177
	v_pk_mul_f32 v[128:129], v[128:129], v[176:177]
	v_lshlrev_b32_e32 v176, 16, v178
	v_and_b32_e32 v177, 0xffff0000, v178
	v_pk_mul_f32 v[126:127], v[126:127], v[192:193]
	v_pk_mul_f32 v[176:177], v[122:123], v[176:177]
	v_lshlrev_b32_e32 v122, 16, v179
	v_and_b32_e32 v123, 0xffff0000, v179
	v_pk_mul_f32 v[178:179], v[124:125], v[122:123]
	v_cvt_pk_bf16_f32 v122, v126, v127
	v_lshl_add_u64 v[126:127], s[50:51], 0, v[162:163]
	v_cvt_pk_bf16_f32 v123, v128, v129
	v_cvt_pk_bf16_f32 v124, v176, v177
	v_cvt_pk_bf16_f32 v125, v178, v179
	v_lshl_add_u64 v[126:127], v[126:127], 0, v[140:141]
	global_store_dwordx4 v[126:127], v[122:125], off
	s_nop 1
	v_lshlrev_b32_e32 v122, 16, v180
	v_and_b32_e32 v123, 0xffff0000, v180
	v_pk_mul_f32 v[114:115], v[114:115], v[122:123]
	v_lshlrev_b32_e32 v122, 16, v181
	v_and_b32_e32 v123, 0xffff0000, v181
	v_pk_mul_f32 v[116:117], v[116:117], v[122:123]
	v_lshlrev_b32_e32 v122, 16, v182
	v_and_b32_e32 v123, 0xffff0000, v182
	v_pk_mul_f32 v[122:123], v[106:107], v[122:123]
	v_lshlrev_b32_e32 v106, 16, v183
	v_and_b32_e32 v107, 0xffff0000, v183
	v_pk_mul_f32 v[124:125], v[108:109], v[106:107]
	v_cvt_pk_bf16_f32 v106, v114, v115
	v_cvt_pk_bf16_f32 v107, v116, v117
	v_cvt_pk_bf16_f32 v108, v122, v123
	v_cvt_pk_bf16_f32 v109, v124, v125
	global_store_dwordx4 v[126:127], v[106:109], off offset:256
	v_lshlrev_b32_e32 v114, 16, v186
	v_and_b32_e32 v115, 0xffff0000, v186
	v_lshlrev_b32_e32 v106, 16, v184
	v_and_b32_e32 v107, 0xffff0000, v184
	v_lshlrev_b32_e32 v108, 16, v185
	v_and_b32_e32 v109, 0xffff0000, v185
	v_pk_mul_f32 v[106:107], v[118:119], v[106:107]
	v_pk_mul_f32 v[108:109], v[120:121], v[108:109]
	v_pk_mul_f32 v[110:111], v[110:111], v[114:115]
	v_lshlrev_b32_e32 v114, 16, v187
	v_and_b32_e32 v115, 0xffff0000, v187
	v_pk_mul_f32 v[112:113], v[112:113], v[114:115]
	v_cvt_pk_bf16_f32 v106, v106, v107
	v_cvt_pk_bf16_f32 v107, v108, v109
	v_cvt_pk_bf16_f32 v108, v110, v111
	v_lshl_add_u64 v[110:111], s[50:51], 0, v[164:165]
	v_cvt_pk_bf16_f32 v109, v112, v113
	v_lshl_add_u64 v[110:111], v[110:111], 0, v[140:141]
	global_store_dwordx4 v[110:111], v[106:109], off
	s_nop 1
	v_lshlrev_b32_e32 v106, 16, v188
	v_and_b32_e32 v107, 0xffff0000, v188
	v_pk_mul_f32 v[102:103], v[102:103], v[106:107]
	v_lshlrev_b32_e32 v106, 16, v189
	v_and_b32_e32 v107, 0xffff0000, v189
	v_pk_mul_f32 v[104:105], v[104:105], v[106:107]
	v_lshlrev_b32_e32 v106, 16, v190
	v_and_b32_e32 v107, 0xffff0000, v190
	v_pk_mul_f32 v[106:107], v[98:99], v[106:107]
	v_lshlrev_b32_e32 v98, 16, v191
	v_and_b32_e32 v99, 0xffff0000, v191
	v_pk_mul_f32 v[108:109], v[100:101], v[98:99]
	v_cvt_pk_bf16_f32 v98, v102, v103
	v_cvt_pk_bf16_f32 v99, v104, v105
	v_cvt_pk_bf16_f32 v100, v106, v107
	v_cvt_pk_bf16_f32 v101, v108, v109
	global_store_dwordx4 v[110:111], v[98:101], off offset:256
	v_or_b32_e32 v106, 48, v144
	v_ashrrev_i32_e32 v107, 31, v106
	v_or_b32_e32 v98, 32, v144
	v_ashrrev_i32_e32 v99, 31, v98
	v_lshlrev_b64 v[114:115], 11, v[98:99]
	v_lshl_add_u64 v[102:103], v[142:143], 0, v[114:115]
	global_load_dwordx4 v[98:101], v[102:103], off
	s_nop 0
	global_load_dwordx4 v[102:105], v[102:103], off offset:256
	v_lshlrev_b64 v[116:117], 11, v[106:107]
	v_lshl_add_u64 v[110:111], v[142:143], 0, v[116:117]
	global_load_dwordx4 v[106:109], v[110:111], off
	s_nop 0
	global_load_dwordx4 v[110:113], v[110:111], off offset:256
	s_waitcnt vmcnt(3)
	v_lshlrev_b32_e32 v118, 16, v98
	v_and_b32_e32 v119, 0xffff0000, v98
	v_lshlrev_b32_e32 v98, 16, v99
	v_and_b32_e32 v99, 0xffff0000, v99
	v_pk_mul_f32 v[96:97], v[96:97], v[98:99]
	v_lshlrev_b32_e32 v98, 16, v100
	v_and_b32_e32 v99, 0xffff0000, v100
	v_pk_mul_f32 v[94:95], v[94:95], v[118:119]
	v_pk_mul_f32 v[98:99], v[90:91], v[98:99]
	v_lshlrev_b32_e32 v90, 16, v101
	v_and_b32_e32 v91, 0xffff0000, v101
	v_pk_mul_f32 v[100:101], v[92:93], v[90:91]
	v_cvt_pk_bf16_f32 v90, v94, v95
	v_lshl_add_u64 v[94:95], s[50:51], 0, v[114:115]
	v_cvt_pk_bf16_f32 v91, v96, v97
	v_cvt_pk_bf16_f32 v92, v98, v99
	v_cvt_pk_bf16_f32 v93, v100, v101
	v_lshl_add_u64 v[94:95], v[94:95], 0, v[140:141]
	global_store_dwordx4 v[94:95], v[90:93], off
	s_waitcnt vmcnt(3)
	s_nop 0
	v_lshlrev_b32_e32 v90, 16, v102
	v_and_b32_e32 v91, 0xffff0000, v102
	v_pk_mul_f32 v[82:83], v[82:83], v[90:91]
	v_lshlrev_b32_e32 v90, 16, v103
	v_and_b32_e32 v91, 0xffff0000, v103
	v_pk_mul_f32 v[84:85], v[84:85], v[90:91]
	v_lshlrev_b32_e32 v90, 16, v104
	v_and_b32_e32 v91, 0xffff0000, v104
	v_pk_mul_f32 v[90:91], v[74:75], v[90:91]
	v_lshlrev_b32_e32 v74, 16, v105
	v_and_b32_e32 v75, 0xffff0000, v105
	v_pk_mul_f32 v[92:93], v[76:77], v[74:75]
	v_cvt_pk_bf16_f32 v74, v82, v83
	v_cvt_pk_bf16_f32 v75, v84, v85
	v_cvt_pk_bf16_f32 v76, v90, v91
	v_cvt_pk_bf16_f32 v77, v92, v93
	global_store_dwordx4 v[94:95], v[74:77], off offset:256
	s_waitcnt vmcnt(3)
	v_lshlrev_b32_e32 v82, 16, v108
	v_and_b32_e32 v83, 0xffff0000, v108
	v_lshlrev_b32_e32 v74, 16, v106
	v_and_b32_e32 v75, 0xffff0000, v106
	v_lshlrev_b32_e32 v76, 16, v107
	v_and_b32_e32 v77, 0xffff0000, v107
	v_pk_mul_f32 v[74:75], v[86:87], v[74:75]
	v_pk_mul_f32 v[76:77], v[88:89], v[76:77]
	v_pk_mul_f32 v[78:79], v[78:79], v[82:83]
	v_lshlrev_b32_e32 v82, 16, v109
	v_and_b32_e32 v83, 0xffff0000, v109
	v_pk_mul_f32 v[80:81], v[80:81], v[82:83]
	v_cvt_pk_bf16_f32 v74, v74, v75
	v_cvt_pk_bf16_f32 v75, v76, v77
	v_cvt_pk_bf16_f32 v76, v78, v79
	v_lshl_add_u64 v[78:79], s[50:51], 0, v[116:117]
	v_cvt_pk_bf16_f32 v77, v80, v81
	v_lshl_add_u64 v[78:79], v[78:79], 0, v[140:141]
	global_store_dwordx4 v[78:79], v[74:77], off
	s_waitcnt vmcnt(3)
; __device__ __forceinline__ unsigned pk2(float lo, float hi) { const f32x2 v = {lo, hi}; const bf16x2_t b = __builtin_convertvector(v, bf16x2_t); return __builtin_bit_cast(unsigned, b); }
;     template <int NA, int NM> __device__ __forceinline__ void operator()(const f32x4 (&acc)[NA][2][NM][2], const pg8::Unit& u, int ro, int wr, int wc, int fr, int fq) const {
;     ...
;             u32x4 g[4][2], t[4][2];
; #pragma unroll
;             for (int m = mp; m < (NM < 2 ? NM : mp + 2); ++m)
; #pragma unroll
;                 for (int bj = 0; bj < 2; ++bj) {
;                     const size_t o = (size_t)(u.pm * 256 + ro + ai * 128 + wr * 64 + m * 16 + fr) * D + colt + bj * 128;
;                     g[m][bj] = *(const u32x4*)(SG + o);
;                     if (PASS == 2) t[m][bj] = *(const u32x4*)(T + o);
;                 }
; #pragma unroll
;             for (int m = mp; m < (NM < 2 ? NM : mp + 2); ++m)
; #pragma unroll
;                 for (int bj = 0; bj < 2; ++bj) {
;                     const size_t o = (size_t)(u.pm * 256 + ro + ai * 128 + wr * 64 + m * 16 + fr) * D + colt + bj * 128;
;                     const u32x4 gg = g[m][bj];
;                     f32x4 v0 = acc[ai][bj][m][0], v1 = acc[ai][bj][m][1];
;                     v0.x *= bflo(gg.x); v0.y *= bfhi(gg.x); v0.z *= bflo(gg.y); v0.w *= bfhi(gg.y);
;                     v1.x *= bflo(gg.z); v1.y *= bfhi(gg.z); v1.z *= bflo(gg.w); v1.w *= bfhi(gg.w);
;                     if (PASS == 2) { const u32x4 tt = t[m][bj];
;                         v0.x += bflo(tt.x); v0.y += bfhi(tt.x); v0.z += bflo(tt.y); v0.w += bfhi(tt.y);
;                         v1.x += bflo(tt.z); v1.y += bfhi(tt.z); v1.z += bflo(tt.w); v1.w += bfhi(tt.w); }
;                     u32x4 w; w.x = pk2(v0.x, v0.y); w.y = pk2(v0.z, v0.w); w.z = pk2(v1.x, v1.y); w.w = pk2(v1.z, v1.w);
;                     *(u32x4*)(Y + o) = w;
;                 }
	s_nop 0
	v_lshlrev_b32_e32 v74, 16, v110
	v_and_b32_e32 v75, 0xffff0000, v110
	v_pk_mul_f32 v[70:71], v[70:71], v[74:75]
	v_lshlrev_b32_e32 v74, 16, v111
	v_and_b32_e32 v75, 0xffff0000, v111
	v_pk_mul_f32 v[72:73], v[72:73], v[74:75]
	v_lshlrev_b32_e32 v74, 16, v112
	v_and_b32_e32 v75, 0xffff0000, v112
	v_pk_mul_f32 v[74:75], v[66:67], v[74:75]
	v_lshlrev_b32_e32 v66, 16, v113
	v_and_b32_e32 v67, 0xffff0000, v113
	v_pk_mul_f32 v[76:77], v[68:69], v[66:67]
	v_cvt_pk_bf16_f32 v66, v70, v71
	v_cvt_pk_bf16_f32 v67, v72, v73
	v_cvt_pk_bf16_f32 v68, v74, v75
	v_cvt_pk_bf16_f32 v69, v76, v77
	global_store_dwordx4 v[78:79], v[66:69], off offset:256
	v_add_u32_e32 v74, 0x90, v144
	v_ashrrev_i32_e32 v75, 31, v74
	v_add_u32_e32 v66, 0x80, v144
	v_ashrrev_i32_e32 v67, 31, v66
	v_lshlrev_b64 v[82:83], 11, v[66:67]
	v_lshl_add_u64 v[70:71], v[142:143], 0, v[82:83]
	global_load_dwordx4 v[66:69], v[70:71], off
	s_nop 0
	global_load_dwordx4 v[70:73], v[70:71], off offset:256
	v_lshlrev_b64 v[84:85], 11, v[74:75]
	v_lshl_add_u64 v[78:79], v[142:143], 0, v[84:85]
	global_load_dwordx4 v[74:77], v[78:79], off
	s_nop 0
	global_load_dwordx4 v[78:81], v[78:79], off offset:256
	s_waitcnt vmcnt(3)
	v_lshlrev_b32_e32 v86, 16, v66
	v_and_b32_e32 v87, 0xffff0000, v66
	v_lshlrev_b32_e32 v66, 16, v67
	v_and_b32_e32 v67, 0xffff0000, v67
	v_pk_mul_f32 v[64:65], v[64:65], v[66:67]
	v_lshlrev_b32_e32 v66, 16, v68
	v_and_b32_e32 v67, 0xffff0000, v68
	v_pk_mul_f32 v[62:63], v[62:63], v[86:87]
	v_pk_mul_f32 v[66:67], v[58:59], v[66:67]
	v_lshlrev_b32_e32 v58, 16, v69
	v_and_b32_e32 v59, 0xffff0000, v69
	v_pk_mul_f32 v[68:69], v[60:61], v[58:59]
	v_cvt_pk_bf16_f32 v58, v62, v63
	v_lshl_add_u64 v[62:63], s[50:51], 0, v[82:83]
	v_cvt_pk_bf16_f32 v59, v64, v65
	v_cvt_pk_bf16_f32 v60, v66, v67
	v_cvt_pk_bf16_f32 v61, v68, v69
	v_lshl_add_u64 v[62:63], v[62:63], 0, v[140:141]
	global_store_dwordx4 v[62:63], v[58:61], off
	s_waitcnt vmcnt(3)
	s_nop 0
	v_lshlrev_b32_e32 v58, 16, v70
	v_and_b32_e32 v59, 0xffff0000, v70
	v_pk_mul_f32 v[50:51], v[50:51], v[58:59]
	v_lshlrev_b32_e32 v58, 16, v71
	v_and_b32_e32 v59, 0xffff0000, v71
	v_pk_mul_f32 v[52:53], v[52:53], v[58:59]
	v_lshlrev_b32_e32 v58, 16, v72
	v_and_b32_e32 v59, 0xffff0000, v72
	v_pk_mul_f32 v[58:59], v[42:43], v[58:59]
	v_lshlrev_b32_e32 v42, 16, v73
	v_and_b32_e32 v43, 0xffff0000, v73
	v_pk_mul_f32 v[60:61], v[44:45], v[42:43]
	v_cvt_pk_bf16_f32 v42, v50, v51
	v_cvt_pk_bf16_f32 v43, v52, v53
	v_cvt_pk_bf16_f32 v44, v58, v59
	v_cvt_pk_bf16_f32 v45, v60, v61
	global_store_dwordx4 v[62:63], v[42:45], off offset:256
	s_waitcnt vmcnt(3)
	v_lshlrev_b32_e32 v50, 16, v76
	v_and_b32_e32 v51, 0xffff0000, v76
	v_lshlrev_b32_e32 v42, 16, v74
	v_and_b32_e32 v43, 0xffff0000, v74
	v_lshlrev_b32_e32 v44, 16, v75
	v_and_b32_e32 v45, 0xffff0000, v75
	v_pk_mul_f32 v[42:43], v[54:55], v[42:43]
	v_pk_mul_f32 v[44:45], v[56:57], v[44:45]
	v_pk_mul_f32 v[46:47], v[46:47], v[50:51]
	v_lshlrev_b32_e32 v50, 16, v77
	v_and_b32_e32 v51, 0xffff0000, v77
	v_pk_mul_f32 v[48:49], v[48:49], v[50:51]
	v_cvt_pk_bf16_f32 v42, v42, v43
	v_cvt_pk_bf16_f32 v43, v44, v45
	v_cvt_pk_bf16_f32 v44, v46, v47
	v_lshl_add_u64 v[46:47], s[50:51], 0, v[84:85]
	v_cvt_pk_bf16_f32 v45, v48, v49
	v_lshl_add_u64 v[46:47], v[46:47], 0, v[140:141]
	global_store_dwordx4 v[46:47], v[42:45], off
	s_waitcnt vmcnt(3)
; #define PG8_BAR __builtin_amdgcn_s_barrier()
; template <class Epi>
; __device__ __forceinline__ void gemm_phase(LAS unsigned char* lds, const int tid, const Gemm g, const StaticOrder& S, const Epi& E) {
;     ...
;         if (!has_next) break;
; #pragma unroll
;         for (int a = 0; a < 2; ++a)
; #pragma unroll
;             for (int b = 0; b < 2; ++b)
; #pragma unroll
;                 for (int m = 0; m < 4; ++m)
; #pragma unroll
;                     for (int n = 0; n < 2; ++n) acc[a][b][m][n] = (f32x4){0.f, 0.f, 0.f, 0.f};
;         cur = nxt; cA = nA; cB = nB; ++ui;
;         if (wr == 1) PG8_BAR;
;     template <int NA, int NM> __device__ __forceinline__ void operator()(const f32x4 (&acc)[NA][2][NM][2], const pg8::Unit& u, int ro, int wr, int wc, int fr, int fq) const {
;     ...
;             u32x4 g[4][2], t[4][2];
; #pragma unroll
;             for (int m = mp; m < (NM < 2 ? NM : mp + 2); ++m)
; #pragma unroll
;                 for (int bj = 0; bj < 2; ++bj) {
;                     const size_t o = (size_t)(u.pm * 256 + ro + ai * 128 + wr * 64 + m * 16 + fr) * D + colt + bj * 128;
;                     g[m][bj] = *(const u32x4*)(SG + o);
;                     if (PASS == 2) t[m][bj] = *(const u32x4*)(T + o);
;                 }
; #pragma unroll
;             for (int m = mp; m < (NM < 2 ? NM : mp + 2); ++m)
; #pragma unroll
;                 for (int bj = 0; bj < 2; ++bj) {
;                     const size_t o = (size_t)(u.pm * 256 + ro + ai * 128 + wr * 64 + m * 16 + fr) * D + colt + bj * 128;
;                     const u32x4 gg = g[m][bj];
;                     f32x4 v0 = acc[ai][bj][m][0], v1 = acc[ai][bj][m][1];
;                     v0.x *= bflo(gg.x); v0.y *= bfhi(gg.x); v0.z *= bflo(gg.y); v0.w *= bfhi(gg.y);
;                     v1.x *= bflo(gg.z); v1.y *= bfhi(gg.z); v1.z *= bflo(gg.w); v1.w *= bfhi(gg.w);
;                     if (PASS == 2) { const u32x4 tt = t[m][bj];
;                         v0.x += bflo(tt.x); v0.y += bfhi(tt.x); v0.z += bflo(tt.y); v0.w += bfhi(tt.y);
;                         v1.x += bflo(tt.z); v1.y += bfhi(tt.z); v1.z += bflo(tt.w); v1.w += bfhi(tt.w); }
;                     u32x4 w; w.x = pk2(v0.x, v0.y); w.y = pk2(v0.z, v0.w); w.z = pk2(v1.x, v1.y); w.w = pk2(v1.z, v1.w);
;                     *(u32x4*)(Y + o) = w;
;                 }
	s_nop 0
	v_lshlrev_b32_e32 v42, 16, v78
	v_and_b32_e32 v43, 0xffff0000, v78
	v_pk_mul_f32 v[38:39], v[38:39], v[42:43]
	v_lshlrev_b32_e32 v42, 16, v79
	v_and_b32_e32 v43, 0xffff0000, v79
	v_pk_mul_f32 v[40:41], v[40:41], v[42:43]
	v_lshlrev_b32_e32 v42, 16, v80
	v_and_b32_e32 v43, 0xffff0000, v80
	v_pk_mul_f32 v[42:43], v[34:35], v[42:43]
	v_lshlrev_b32_e32 v34, 16, v81
	v_and_b32_e32 v35, 0xffff0000, v81
	v_pk_mul_f32 v[44:45], v[36:37], v[34:35]
	v_cvt_pk_bf16_f32 v34, v38, v39
	v_cvt_pk_bf16_f32 v35, v40, v41
	v_cvt_pk_bf16_f32 v36, v42, v43
	v_cvt_pk_bf16_f32 v37, v44, v45
	global_store_dwordx4 v[46:47], v[34:37], off offset:256
	v_add_u32_e32 v42, 0xb0, v144
	v_ashrrev_i32_e32 v43, 31, v42
	v_add_u32_e32 v34, 0xa0, v144
	v_ashrrev_i32_e32 v35, 31, v34
	v_lshlrev_b64 v[50:51], 11, v[34:35]
	v_lshl_add_u64 v[38:39], v[142:143], 0, v[50:51]
	global_load_dwordx4 v[34:37], v[38:39], off
	s_nop 0
	global_load_dwordx4 v[38:41], v[38:39], off offset:256
	v_lshlrev_b64 v[52:53], 11, v[42:43]
	v_lshl_add_u64 v[46:47], v[142:143], 0, v[52:53]
	global_load_dwordx4 v[42:45], v[46:47], off
	s_nop 0
	global_load_dwordx4 v[46:49], v[46:47], off offset:256
	s_waitcnt vmcnt(3)
	v_lshlrev_b32_e32 v54, 16, v34
	v_and_b32_e32 v55, 0xffff0000, v34
	v_lshlrev_b32_e32 v34, 16, v35
	v_and_b32_e32 v35, 0xffff0000, v35
	v_pk_mul_f32 v[32:33], v[32:33], v[34:35]
	v_lshlrev_b32_e32 v34, 16, v36
	v_and_b32_e32 v35, 0xffff0000, v36
	v_pk_mul_f32 v[30:31], v[30:31], v[54:55]
	v_pk_mul_f32 v[34:35], v[26:27], v[34:35]
	v_lshlrev_b32_e32 v26, 16, v37
	v_and_b32_e32 v27, 0xffff0000, v37
	v_pk_mul_f32 v[36:37], v[28:29], v[26:27]
	v_cvt_pk_bf16_f32 v26, v30, v31
	v_lshl_add_u64 v[30:31], s[50:51], 0, v[50:51]
	v_cvt_pk_bf16_f32 v27, v32, v33
	v_cvt_pk_bf16_f32 v28, v34, v35
	v_cvt_pk_bf16_f32 v29, v36, v37
	v_lshl_add_u64 v[30:31], v[30:31], 0, v[140:141]
	global_store_dwordx4 v[30:31], v[26:29], off
	s_waitcnt vmcnt(3)
	s_nop 0
	v_lshlrev_b32_e32 v26, 16, v38
	v_and_b32_e32 v27, 0xffff0000, v38
	v_pk_mul_f32 v[18:19], v[18:19], v[26:27]
	v_lshlrev_b32_e32 v26, 16, v39
	v_and_b32_e32 v27, 0xffff0000, v39
	v_pk_mul_f32 v[20:21], v[20:21], v[26:27]
	v_lshlrev_b32_e32 v26, 16, v40
	v_and_b32_e32 v27, 0xffff0000, v40
	v_pk_mul_f32 v[26:27], v[10:11], v[26:27]
	v_lshlrev_b32_e32 v10, 16, v41
	v_and_b32_e32 v11, 0xffff0000, v41
	v_pk_mul_f32 v[28:29], v[12:13], v[10:11]
	v_cvt_pk_bf16_f32 v10, v18, v19
	v_cvt_pk_bf16_f32 v11, v20, v21
	v_cvt_pk_bf16_f32 v12, v26, v27
	v_cvt_pk_bf16_f32 v13, v28, v29
	global_store_dwordx4 v[30:31], v[10:13], off offset:256
	s_waitcnt vmcnt(3)
	v_lshlrev_b32_e32 v18, 16, v44
	v_and_b32_e32 v19, 0xffff0000, v44
	v_lshlrev_b32_e32 v10, 16, v42
	v_and_b32_e32 v11, 0xffff0000, v42
	v_lshlrev_b32_e32 v12, 16, v43
	v_and_b32_e32 v13, 0xffff0000, v43
	v_pk_mul_f32 v[10:11], v[22:23], v[10:11]
	v_pk_mul_f32 v[12:13], v[24:25], v[12:13]
	v_pk_mul_f32 v[14:15], v[14:15], v[18:19]
	v_lshlrev_b32_e32 v18, 16, v45
	v_and_b32_e32 v19, 0xffff0000, v45
	v_pk_mul_f32 v[16:17], v[16:17], v[18:19]
	v_cvt_pk_bf16_f32 v10, v10, v11
	v_cvt_pk_bf16_f32 v11, v12, v13
	v_cvt_pk_bf16_f32 v12, v14, v15
	v_lshl_add_u64 v[14:15], s[50:51], 0, v[52:53]
	v_cvt_pk_bf16_f32 v13, v16, v17
	v_lshl_add_u64 v[14:15], v[14:15], 0, v[140:141]
	global_store_dwordx4 v[14:15], v[10:13], off
	s_waitcnt vmcnt(3)
	s_nop 0
	v_lshlrev_b32_e32 v10, 16, v46
	v_and_b32_e32 v11, 0xffff0000, v46
	v_pk_mul_f32 v[6:7], v[6:7], v[10:11]
	v_lshlrev_b32_e32 v10, 16, v47
	v_and_b32_e32 v11, 0xffff0000, v47
	v_pk_mul_f32 v[8:9], v[8:9], v[10:11]
	v_lshlrev_b32_e32 v10, 16, v48
	v_and_b32_e32 v11, 0xffff0000, v48
	v_pk_mul_f32 v[10:11], v[2:3], v[10:11]
	v_lshlrev_b32_e32 v2, 16, v49
	v_and_b32_e32 v3, 0xffff0000, v49
	v_pk_mul_f32 v[12:13], v[4:5], v[2:3]
	v_cvt_pk_bf16_f32 v2, v6, v7
	v_cvt_pk_bf16_f32 v3, v8, v9
	v_cvt_pk_bf16_f32 v4, v10, v11
	v_cvt_pk_bf16_f32 v5, v12, v13
	global_store_dwordx4 v[14:15], v[2:5], off offset:256
	s_cbranch_vccnz .LBB0_1276
	s_andn2_b64 vcc, exec, s[4:5]
	s_cbranch_vccnz .LBB0_1275
	s_barrier
	s_branch .LBB0_1275

; __device__ __forceinline__ unsigned pk2(float lo, float hi) { const f32x2 v = {lo, hi}; const bf16x2_t b = __builtin_convertvector(v, bf16x2_t); return __builtin_bit_cast(unsigned, b); }
; #define PG8_BAR __builtin_amdgcn_s_barrier()
; template <class Epi>
; __device__ __forceinline__ void gemm_phase(LAS unsigned char* lds, const int tid, const Gemm g, const StaticOrder& S, const Epi& E) {
;     ...
;         if (wr == 0) PG8_BAR;
;     template <int NA, int NM> __device__ __forceinline__ void operator()(const f32x4 (&acc)[NA][2][NM][2], const pg8::Unit& u, int ro, int wr, int wc, int fr, int fq) const {
;     ...
;             u32x4 g[4][2], t[4][2];
; #pragma unroll
;             for (int m = mp; m < (NM < 2 ? NM : mp + 2); ++m)
; #pragma unroll
;                 for (int bj = 0; bj < 2; ++bj) {
;                     const size_t o = (size_t)(u.pm * 256 + ro + ai * 128 + wr * 64 + m * 16 + fr) * D + colt + bj * 128;
;                     g[m][bj] = *(const u32x4*)(SG + o);
;                     if (PASS == 2) t[m][bj] = *(const u32x4*)(T + o);
;                 }
; #pragma unroll
;             for (int m = mp; m < (NM < 2 ? NM : mp + 2); ++m)
; #pragma unroll
;                 for (int bj = 0; bj < 2; ++bj) {
;                     const size_t o = (size_t)(u.pm * 256 + ro + ai * 128 + wr * 64 + m * 16 + fr) * D + colt + bj * 128;
;                     const u32x4 gg = g[m][bj];
;                     f32x4 v0 = acc[ai][bj][m][0], v1 = acc[ai][bj][m][1];
;                     v0.x *= bflo(gg.x); v0.y *= bfhi(gg.x); v0.z *= bflo(gg.y); v0.w *= bfhi(gg.y);
;                     v1.x *= bflo(gg.z); v1.y *= bfhi(gg.z); v1.z *= bflo(gg.w); v1.w *= bfhi(gg.w);
;                     if (PASS == 2) { const u32x4 tt = t[m][bj];
;                         v0.x += bflo(tt.x); v0.y += bfhi(tt.x); v0.z += bflo(tt.y); v0.w += bfhi(tt.y);
;                         v1.x += bflo(tt.z); v1.y += bfhi(tt.z); v1.z += bflo(tt.w); v1.w += bfhi(tt.w); }
;                     u32x4 w; w.x = pk2(v0.x, v0.y); w.y = pk2(v0.z, v0.w); w.z = pk2(v1.x, v1.y); w.w = pk2(v1.z, v1.w);
;                     *(u32x4*)(Y + o) = w;
;                 }
.LBB0_1336:
	v_lshl_add_u32 v160, s82, 8, v188
	v_lshl_or_b32 v158, s83, 8, v190
	v_ashrrev_i32_e32 v161, 31, v160
	v_ashrrev_i32_e32 v159, 31, v158
	v_lshlrev_b64 v[130:131], 10, v[160:161]
	v_lshl_add_u64 v[130:131], v[130:131], 0, v[158:159]
	v_readlane_b32 s0, v251, 12
	v_lshlrev_b64 v[130:131], 1, v[130:131]
	v_readlane_b32 s1, v251, 13
	v_readlane_b32 s36, v249, 8
	v_readlane_b32 s50, v249, 22
	v_lshl_add_u64 v[132:133], s[0:1], 0, v[130:131]
	v_readlane_b32 s51, v249, 23
	global_load_dwordx4 v[192:195], v[132:133], off
	v_or_b32_e32 v170, 16, v160
	v_lshl_add_u64 v[132:133], s[50:51], 0, v[130:131]
	global_load_dwordx4 v[196:199], v[132:133], off
	v_or_b32_e32 v130, 0x100, v130
	v_lshl_add_u64 v[130:131], s[0:1], 0, v[130:131]
	global_load_dwordx4 v[200:203], v[130:131], off
	global_load_dwordx4 v[210:213], v[132:133], off offset:256
	v_ashrrev_i32_e32 v171, 31, v170
	v_lshlrev_b64 v[130:131], 10, v[170:171]
	v_lshl_add_u64 v[130:131], v[130:131], 0, v[158:159]
	v_lshlrev_b64 v[130:131], 1, v[130:131]
	v_lshl_add_u64 v[132:133], s[0:1], 0, v[130:131]
	global_load_dwordx4 v[142:145], v[132:133], off
	v_lshl_add_u64 v[132:133], s[50:51], 0, v[130:131]
	global_load_dwordx4 v[138:141], v[132:133], off
	v_or_b32_e32 v130, 0x100, v130
	v_lshl_add_u64 v[130:131], s[0:1], 0, v[130:131]
	global_load_dwordx4 v[134:137], v[130:131], off
	s_nop 0
	global_load_dwordx4 v[130:133], v[132:133], off offset:256
	v_lshlrev_b64 v[162:163], 11, v[160:161]
	s_mov_b64 s[30:31], -1
	s_andn2_b64 vcc, exec, s[62:63]
	s_mov_b32 s92, 0x2c000
	s_mov_b32 s93, 0x2e000
	v_readlane_b32 s37, v249, 9
	v_readlane_b32 s38, v249, 10
	v_readlane_b32 s39, v249, 11
	v_readlane_b32 s40, v249, 12
	v_readlane_b32 s41, v249, 13
	v_readlane_b32 s42, v249, 14
	v_readlane_b32 s43, v249, 15
	v_readlane_b32 s44, v249, 16
	v_readlane_b32 s45, v249, 17
	v_readlane_b32 s46, v249, 18
	v_readlane_b32 s47, v249, 19
	v_readlane_b32 s48, v249, 20
	v_readlane_b32 s49, v249, 21
	s_waitcnt vmcnt(0)
	s_cmp_lg_u64 s[6:7], 0
	s_cbranch_scc0 .Lal_5
	s_barrier
.Lal_5:
	v_lshlrev_b32_e32 v164, 16, v192
	v_and_b32_e32 v165, 0xffff0000, v192
	v_lshlrev_b32_e32 v206, 16, v196
	v_and_b32_e32 v207, 0xffff0000, v196
	v_pk_fma_f32 v[126:127], v[126:127], v[164:165], v[206:207]
	v_lshlrev_b32_e32 v164, 16, v193
	v_and_b32_e32 v165, 0xffff0000, v193
	v_lshlrev_b32_e32 v192, 16, v197
	v_and_b32_e32 v193, 0xffff0000, v197
	v_pk_fma_f32 v[128:129], v[128:129], v[164:165], v[192:193]
	v_lshlrev_b32_e32 v164, 16, v194
	v_and_b32_e32 v165, 0xffff0000, v194
	v_lshlrev_b32_e32 v192, 16, v198
	v_and_b32_e32 v193, 0xffff0000, v198
	v_pk_fma_f32 v[122:123], v[122:123], v[164:165], v[192:193]
	v_lshlrev_b32_e32 v164, 16, v195
	v_and_b32_e32 v165, 0xffff0000, v195
	v_lshlrev_b32_e32 v192, 16, v199
	v_and_b32_e32 v193, 0xffff0000, v199
	v_pk_fma_f32 v[164:165], v[124:125], v[164:165], v[192:193]
	v_cvt_pk_bf16_f32 v124, v126, v127
	v_cvt_pk_bf16_f32 v125, v128, v129
	v_cvt_pk_bf16_f32 v126, v122, v123
	v_lshl_add_u64 v[128:129], s[60:61], 0, v[162:163]
	v_lshlrev_b64 v[122:123], 1, v[158:159]
	v_cvt_pk_bf16_f32 v127, v164, v165
	v_lshl_add_u64 v[128:129], v[128:129], 0, v[122:123]
	global_store_dwordx4 v[128:129], v[124:127], off
	s_nop 1
	v_lshlrev_b32_e32 v124, 16, v200
	v_and_b32_e32 v125, 0xffff0000, v200
	v_lshlrev_b32_e32 v126, 16, v210
	v_and_b32_e32 v127, 0xffff0000, v210
	v_pk_fma_f32 v[118:119], v[118:119], v[124:125], v[126:127]
	v_lshlrev_b32_e32 v124, 16, v201
	v_and_b32_e32 v125, 0xffff0000, v201
	v_lshlrev_b32_e32 v126, 16, v211
	v_and_b32_e32 v127, 0xffff0000, v211
	v_pk_fma_f32 v[120:121], v[120:121], v[124:125], v[126:127]
	v_lshlrev_b32_e32 v124, 16, v202
	v_and_b32_e32 v125, 0xffff0000, v202
	v_lshlrev_b32_e32 v126, 16, v212
	v_and_b32_e32 v127, 0xffff0000, v212
	v_pk_fma_f32 v[124:125], v[114:115], v[124:125], v[126:127]
	v_lshlrev_b32_e32 v114, 16, v203
	v_and_b32_e32 v115, 0xffff0000, v203
	v_lshlrev_b32_e32 v126, 16, v213
	v_and_b32_e32 v127, 0xffff0000, v213
	v_pk_fma_f32 v[126:127], v[116:117], v[114:115], v[126:127]
	v_cvt_pk_bf16_f32 v114, v118, v119
	v_cvt_pk_bf16_f32 v115, v120, v121
	v_cvt_pk_bf16_f32 v116, v124, v125
	v_cvt_pk_bf16_f32 v117, v126, v127
	global_store_dwordx4 v[128:129], v[114:117], off offset:256
	v_lshlrev_b32_e32 v118, 16, v138
	v_and_b32_e32 v119, 0xffff0000, v138
	v_lshlrev_b32_e32 v116, 16, v142
	v_and_b32_e32 v117, 0xffff0000, v142
	v_pk_fma_f32 v[110:111], v[110:111], v[116:117], v[118:119]
	v_lshlrev_b32_e32 v116, 16, v143
	v_and_b32_e32 v117, 0xffff0000, v143
	v_lshlrev_b32_e32 v118, 16, v139
	v_and_b32_e32 v119, 0xffff0000, v139
	v_pk_fma_f32 v[112:113], v[112:113], v[116:117], v[118:119]
	v_lshlrev_b32_e32 v116, 16, v144
	v_and_b32_e32 v117, 0xffff0000, v144
	v_lshlrev_b32_e32 v118, 16, v140
	v_and_b32_e32 v119, 0xffff0000, v140
	v_lshlrev_b64 v[114:115], 11, v[170:171]
	v_pk_fma_f32 v[116:117], v[106:107], v[116:117], v[118:119]
	v_lshlrev_b32_e32 v106, 16, v145
	v_and_b32_e32 v107, 0xffff0000, v145
	v_lshlrev_b32_e32 v118, 16, v141
	v_and_b32_e32 v119, 0xffff0000, v141
	v_pk_fma_f32 v[118:119], v[108:109], v[106:107], v[118:119]
	v_cvt_pk_bf16_f32 v106, v110, v111
	v_lshl_add_u64 v[110:111], s[60:61], 0, v[114:115]
	v_cvt_pk_bf16_f32 v107, v112, v113
	v_cvt_pk_bf16_f32 v108, v116, v117
	v_cvt_pk_bf16_f32 v109, v118, v119
	v_lshl_add_u64 v[110:111], v[110:111], 0, v[122:123]
	global_store_dwordx4 v[110:111], v[106:109], off
	s_nop 1
	v_lshlrev_b32_e32 v106, 16, v134
	v_and_b32_e32 v107, 0xffff0000, v134
	v_lshlrev_b32_e32 v108, 16, v130
	v_and_b32_e32 v109, 0xffff0000, v130
	v_pk_fma_f32 v[102:103], v[102:103], v[106:107], v[108:109]
	v_lshlrev_b32_e32 v106, 16, v135
; __device__ __forceinline__ unsigned pk2(float lo, float hi) { const f32x2 v = {lo, hi}; const bf16x2_t b = __builtin_convertvector(v, bf16x2_t); return __builtin_bit_cast(unsigned, b); }
;     template <int NA, int NM> __device__ __forceinline__ void operator()(const f32x4 (&acc)[NA][2][NM][2], const pg8::Unit& u, int ro, int wr, int wc, int fr, int fq) const {
;     ...
;             u32x4 g[4][2], t[4][2];
; #pragma unroll
;             for (int m = mp; m < (NM < 2 ? NM : mp + 2); ++m)
; #pragma unroll
;                 for (int bj = 0; bj < 2; ++bj) {
;                     const size_t o = (size_t)(u.pm * 256 + ro + ai * 128 + wr * 64 + m * 16 + fr) * D + colt + bj * 128;
;                     g[m][bj] = *(const u32x4*)(SG + o);
;                     if (PASS == 2) t[m][bj] = *(const u32x4*)(T + o);
;                 }
; #pragma unroll
;             for (int m = mp; m < (NM < 2 ? NM : mp + 2); ++m)
; #pragma unroll
;                 for (int bj = 0; bj < 2; ++bj) {
;                     const size_t o = (size_t)(u.pm * 256 + ro + ai * 128 + wr * 64 + m * 16 + fr) * D + colt + bj * 128;
;                     const u32x4 gg = g[m][bj];
;                     f32x4 v0 = acc[ai][bj][m][0], v1 = acc[ai][bj][m][1];
;                     v0.x *= bflo(gg.x); v0.y *= bfhi(gg.x); v0.z *= bflo(gg.y); v0.w *= bfhi(gg.y);
;                     v1.x *= bflo(gg.z); v1.y *= bfhi(gg.z); v1.z *= bflo(gg.w); v1.w *= bfhi(gg.w);
;                     if (PASS == 2) { const u32x4 tt = t[m][bj];
;                         v0.x += bflo(tt.x); v0.y += bfhi(tt.x); v0.z += bflo(tt.y); v0.w += bfhi(tt.y);
;                         v1.x += bflo(tt.z); v1.y += bfhi(tt.z); v1.z += bflo(tt.w); v1.w += bfhi(tt.w); }
;                     u32x4 w; w.x = pk2(v0.x, v0.y); w.y = pk2(v0.z, v0.w); w.z = pk2(v1.x, v1.y); w.w = pk2(v1.z, v1.w);
;                     *(u32x4*)(Y + o) = w;
;                 }
	v_and_b32_e32 v107, 0xffff0000, v135
	v_lshlrev_b32_e32 v108, 16, v131
	v_and_b32_e32 v109, 0xffff0000, v131
	v_pk_fma_f32 v[104:105], v[104:105], v[106:107], v[108:109]
	v_lshlrev_b32_e32 v106, 16, v136
	v_and_b32_e32 v107, 0xffff0000, v136
	v_lshlrev_b32_e32 v108, 16, v132
	v_and_b32_e32 v109, 0xffff0000, v132
	v_pk_fma_f32 v[106:107], v[98:99], v[106:107], v[108:109]
	v_lshlrev_b32_e32 v98, 16, v137
	v_and_b32_e32 v99, 0xffff0000, v137
	v_lshlrev_b32_e32 v108, 16, v133
	v_and_b32_e32 v109, 0xffff0000, v133
	v_pk_fma_f32 v[108:109], v[100:101], v[98:99], v[108:109]
	v_or_b32_e32 v132, 32, v160
	v_cvt_pk_bf16_f32 v98, v102, v103
	v_cvt_pk_bf16_f32 v99, v104, v105
	v_cvt_pk_bf16_f32 v100, v106, v107
	v_cvt_pk_bf16_f32 v101, v108, v109
	v_ashrrev_i32_e32 v133, 31, v132
	global_store_dwordx4 v[110:111], v[98:101], off offset:256
	v_or_b32_e32 v134, 48, v160
	v_ashrrev_i32_e32 v135, 31, v134
	v_lshlrev_b64 v[98:99], 10, v[132:133]
	v_lshl_add_u64 v[98:99], v[98:99], 0, v[158:159]
	v_lshlrev_b64 v[106:107], 1, v[98:99]
	v_lshl_add_u64 v[98:99], s[0:1], 0, v[106:107]
	v_lshl_add_u64 v[110:111], s[50:51], 0, v[106:107]
	global_load_dwordx4 v[98:101], v[98:99], off
	v_or_b32_e32 v106, 0x100, v106
	global_load_dwordx4 v[102:105], v[110:111], off
	v_lshl_add_u64 v[106:107], s[0:1], 0, v[106:107]
	global_load_dwordx4 v[106:109], v[106:107], off
	s_nop 0
	global_load_dwordx4 v[110:113], v[110:111], off offset:256
	v_lshlrev_b64 v[114:115], 10, v[134:135]
	v_lshl_add_u64 v[114:115], v[114:115], 0, v[158:159]
	v_lshlrev_b64 v[124:125], 1, v[114:115]
	v_lshl_add_u64 v[114:115], s[0:1], 0, v[124:125]
	v_lshl_add_u64 v[128:129], s[50:51], 0, v[124:125]
	global_load_dwordx4 v[114:117], v[114:115], off
	v_or_b32_e32 v124, 0x100, v124
	global_load_dwordx4 v[118:121], v[128:129], off
	v_lshl_add_u64 v[124:125], s[0:1], 0, v[124:125]
	global_load_dwordx4 v[124:127], v[124:125], off
	s_nop 0
	global_load_dwordx4 v[128:131], v[128:129], off offset:256
	v_lshlrev_b64 v[132:133], 11, v[132:133]
	s_waitcnt vmcnt(7)
	v_lshlrev_b32_e32 v136, 16, v98
	v_and_b32_e32 v137, 0xffff0000, v98
	s_waitcnt vmcnt(6)
	v_lshlrev_b32_e32 v138, 16, v102
	v_and_b32_e32 v139, 0xffff0000, v102
	v_lshlrev_b32_e32 v98, 16, v99
	v_and_b32_e32 v99, 0xffff0000, v99
	v_lshlrev_b32_e32 v102, 16, v103
	v_and_b32_e32 v103, 0xffff0000, v103
	v_pk_fma_f32 v[96:97], v[96:97], v[98:99], v[102:103]
	v_lshlrev_b32_e32 v98, 16, v100
	v_and_b32_e32 v99, 0xffff0000, v100
	v_lshlrev_b32_e32 v102, 16, v104
	v_and_b32_e32 v103, 0xffff0000, v104
	v_pk_fma_f32 v[94:95], v[94:95], v[136:137], v[138:139]
	v_pk_fma_f32 v[98:99], v[90:91], v[98:99], v[102:103]
	v_lshlrev_b32_e32 v90, 16, v101
	v_and_b32_e32 v91, 0xffff0000, v101
	v_lshlrev_b32_e32 v100, 16, v105
	v_and_b32_e32 v101, 0xffff0000, v105
	v_pk_fma_f32 v[100:101], v[92:93], v[90:91], v[100:101]
	v_cvt_pk_bf16_f32 v90, v94, v95
	v_lshl_add_u64 v[94:95], s[60:61], 0, v[132:133]
	v_cvt_pk_bf16_f32 v91, v96, v97
	v_cvt_pk_bf16_f32 v92, v98, v99
	v_cvt_pk_bf16_f32 v93, v100, v101
	v_lshl_add_u64 v[94:95], v[94:95], 0, v[122:123]
	global_store_dwordx4 v[94:95], v[90:93], off
	v_add_u32_e32 v98, 0x80, v160
	v_ashrrev_i32_e32 v99, 31, v98
	s_waitcnt vmcnt(6)
	v_lshlrev_b32_e32 v90, 16, v106
	v_and_b32_e32 v91, 0xffff0000, v106
	s_waitcnt vmcnt(5)
	v_lshlrev_b32_e32 v92, 16, v110
	v_and_b32_e32 v93, 0xffff0000, v110
	v_pk_fma_f32 v[86:87], v[86:87], v[90:91], v[92:93]
	v_lshlrev_b32_e32 v90, 16, v107
	v_and_b32_e32 v91, 0xffff0000, v107
	v_lshlrev_b32_e32 v92, 16, v111
	v_and_b32_e32 v93, 0xffff0000, v111
	v_pk_fma_f32 v[88:89], v[88:89], v[90:91], v[92:93]
	v_lshlrev_b32_e32 v90, 16, v108
	v_and_b32_e32 v91, 0xffff0000, v108
	v_lshlrev_b32_e32 v92, 16, v112
	v_and_b32_e32 v93, 0xffff0000, v112
	v_pk_fma_f32 v[90:91], v[82:83], v[90:91], v[92:93]
	v_lshlrev_b32_e32 v82, 16, v109
	v_and_b32_e32 v83, 0xffff0000, v109
	v_lshlrev_b32_e32 v92, 16, v113
	v_and_b32_e32 v93, 0xffff0000, v113
	v_pk_fma_f32 v[92:93], v[84:85], v[82:83], v[92:93]
	v_cvt_pk_bf16_f32 v82, v86, v87
	v_cvt_pk_bf16_f32 v83, v88, v89
	v_cvt_pk_bf16_f32 v84, v90, v91
	v_cvt_pk_bf16_f32 v85, v92, v93
	global_store_dwordx4 v[94:95], v[82:85], off offset:256
	s_waitcnt vmcnt(4)
	v_lshlrev_b32_e32 v86, 16, v118
	v_and_b32_e32 v87, 0xffff0000, v118
	v_lshlrev_b32_e32 v84, 16, v114
	v_and_b32_e32 v85, 0xffff0000, v114
	v_pk_fma_f32 v[78:79], v[78:79], v[84:85], v[86:87]
	v_lshlrev_b32_e32 v84, 16, v115
	v_and_b32_e32 v85, 0xffff0000, v115
	v_lshlrev_b32_e32 v86, 16, v119
	v_and_b32_e32 v87, 0xffff0000, v119
	v_pk_fma_f32 v[80:81], v[80:81], v[84:85], v[86:87]
	v_lshlrev_b32_e32 v84, 16, v116
	v_and_b32_e32 v85, 0xffff0000, v116
	v_lshlrev_b32_e32 v86, 16, v120
	v_and_b32_e32 v87, 0xffff0000, v120
	v_lshlrev_b64 v[82:83], 11, v[134:135]
	v_pk_fma_f32 v[84:85], v[74:75], v[84:85], v[86:87]
	v_lshlrev_b32_e32 v74, 16, v117
	v_and_b32_e32 v75, 0xffff0000, v117
	v_lshlrev_b32_e32 v86, 16, v121
	v_and_b32_e32 v87, 0xffff0000, v121
	v_pk_fma_f32 v[86:87], v[76:77], v[74:75], v[86:87]
	v_cvt_pk_bf16_f32 v74, v78, v79
	v_lshl_add_u64 v[78:79], s[60:61], 0, v[82:83]
	v_cvt_pk_bf16_f32 v75, v80, v81
	v_cvt_pk_bf16_f32 v76, v84, v85
	v_cvt_pk_bf16_f32 v77, v86, v87
	v_lshl_add_u64 v[78:79], v[78:79], 0, v[122:123]
	global_store_dwordx4 v[78:79], v[74:77], off
	v_add_u32_e32 v100, 0x90, v160
	v_ashrrev_i32_e32 v101, 31, v100
	s_waitcnt vmcnt(4)
	v_lshlrev_b32_e32 v74, 16, v124
	v_and_b32_e32 v75, 0xffff0000, v124
	s_waitcnt vmcnt(3)
; __device__ __forceinline__ unsigned pk2(float lo, float hi) { const f32x2 v = {lo, hi}; const bf16x2_t b = __builtin_convertvector(v, bf16x2_t); return __builtin_bit_cast(unsigned, b); }
;     template <int NA, int NM> __device__ __forceinline__ void operator()(const f32x4 (&acc)[NA][2][NM][2], const pg8::Unit& u, int ro, int wr, int wc, int fr, int fq) const {
;     ...
; #pragma unroll
;             for (int m = mp; m < (NM < 2 ? NM : mp + 2); ++m)
; #pragma unroll
;                 for (int bj = 0; bj < 2; ++bj) {
;                     const size_t o = (size_t)(u.pm * 256 + ro + ai * 128 + wr * 64 + m * 16 + fr) * D + colt + bj * 128;
;                     const u32x4 gg = g[m][bj];
;                     f32x4 v0 = acc[ai][bj][m][0], v1 = acc[ai][bj][m][1];
;                     v0.x *= bflo(gg.x); v0.y *= bfhi(gg.x); v0.z *= bflo(gg.y); v0.w *= bfhi(gg.y);
;                     v1.x *= bflo(gg.z); v1.y *= bfhi(gg.z); v1.z *= bflo(gg.w); v1.w *= bfhi(gg.w);
;                     if (PASS == 2) { const u32x4 tt = t[m][bj];
;                         v0.x += bflo(tt.x); v0.y += bfhi(tt.x); v0.z += bflo(tt.y); v0.w += bfhi(tt.y);
;                         v1.x += bflo(tt.z); v1.y += bfhi(tt.z); v1.z += bflo(tt.w); v1.w += bfhi(tt.w); }
;                     u32x4 w; w.x = pk2(v0.x, v0.y); w.y = pk2(v0.z, v0.w); w.z = pk2(v1.x, v1.y); w.w = pk2(v1.z, v1.w);
;                     *(u32x4*)(Y + o) = w;
;                 }
	v_lshlrev_b32_e32 v76, 16, v128
	v_and_b32_e32 v77, 0xffff0000, v128
	v_pk_fma_f32 v[70:71], v[70:71], v[74:75], v[76:77]
	v_lshlrev_b32_e32 v74, 16, v125
	v_and_b32_e32 v75, 0xffff0000, v125
	v_lshlrev_b32_e32 v76, 16, v129
	v_and_b32_e32 v77, 0xffff0000, v129
	v_pk_fma_f32 v[72:73], v[72:73], v[74:75], v[76:77]
	v_lshlrev_b32_e32 v74, 16, v126
	v_and_b32_e32 v75, 0xffff0000, v126
	v_lshlrev_b32_e32 v76, 16, v130
	v_and_b32_e32 v77, 0xffff0000, v130
	v_pk_fma_f32 v[74:75], v[66:67], v[74:75], v[76:77]
	v_lshlrev_b32_e32 v66, 16, v127
	v_and_b32_e32 v67, 0xffff0000, v127
	v_lshlrev_b32_e32 v76, 16, v131
	v_and_b32_e32 v77, 0xffff0000, v131
	v_pk_fma_f32 v[76:77], v[68:69], v[66:67], v[76:77]
	v_cvt_pk_bf16_f32 v66, v70, v71
	v_cvt_pk_bf16_f32 v67, v72, v73
	v_cvt_pk_bf16_f32 v68, v74, v75
	v_cvt_pk_bf16_f32 v69, v76, v77
	global_store_dwordx4 v[78:79], v[66:69], off offset:256
	v_lshlrev_b64 v[82:83], 10, v[100:101]
	v_lshl_add_u64 v[82:83], v[82:83], 0, v[158:159]
	v_lshlrev_b64 v[66:67], 10, v[98:99]
	v_lshl_add_u64 v[66:67], v[66:67], 0, v[158:159]
	v_lshlrev_b64 v[74:75], 1, v[66:67]
	v_lshl_add_u64 v[66:67], s[0:1], 0, v[74:75]
	v_lshl_add_u64 v[78:79], s[50:51], 0, v[74:75]
	global_load_dwordx4 v[66:69], v[66:67], off
	v_or_b32_e32 v74, 0x100, v74
	global_load_dwordx4 v[70:73], v[78:79], off
	v_lshl_add_u64 v[74:75], s[0:1], 0, v[74:75]
	global_load_dwordx4 v[74:77], v[74:75], off
	s_nop 0
	global_load_dwordx4 v[78:81], v[78:79], off offset:256
	v_lshlrev_b64 v[90:91], 1, v[82:83]
	v_lshl_add_u64 v[82:83], s[0:1], 0, v[90:91]
	v_lshl_add_u64 v[94:95], s[50:51], 0, v[90:91]
	global_load_dwordx4 v[82:85], v[82:83], off
	v_or_b32_e32 v90, 0x100, v90
	global_load_dwordx4 v[86:89], v[94:95], off
	v_lshl_add_u64 v[90:91], s[0:1], 0, v[90:91]
	global_load_dwordx4 v[90:93], v[90:91], off
	s_nop 0
	global_load_dwordx4 v[94:97], v[94:95], off offset:256
	v_lshlrev_b64 v[98:99], 11, v[98:99]
	s_waitcnt vmcnt(7)
	v_lshlrev_b32_e32 v102, 16, v66
	v_and_b32_e32 v103, 0xffff0000, v66
	s_waitcnt vmcnt(6)
	v_lshlrev_b32_e32 v104, 16, v70
	v_and_b32_e32 v105, 0xffff0000, v70
	v_lshlrev_b32_e32 v66, 16, v67
	v_and_b32_e32 v67, 0xffff0000, v67
	v_lshlrev_b32_e32 v70, 16, v71
	v_and_b32_e32 v71, 0xffff0000, v71
	v_pk_fma_f32 v[64:65], v[64:65], v[66:67], v[70:71]
	v_lshlrev_b32_e32 v66, 16, v68
	v_and_b32_e32 v67, 0xffff0000, v68
	v_lshlrev_b32_e32 v70, 16, v72
	v_and_b32_e32 v71, 0xffff0000, v72
	v_pk_fma_f32 v[62:63], v[62:63], v[102:103], v[104:105]
	v_pk_fma_f32 v[66:67], v[58:59], v[66:67], v[70:71]
	v_lshlrev_b32_e32 v58, 16, v69
	v_and_b32_e32 v59, 0xffff0000, v69
	v_lshlrev_b32_e32 v68, 16, v73
	v_and_b32_e32 v69, 0xffff0000, v73
	v_pk_fma_f32 v[68:69], v[60:61], v[58:59], v[68:69]
	v_cvt_pk_bf16_f32 v58, v62, v63
	v_lshl_add_u64 v[62:63], s[60:61], 0, v[98:99]
	v_cvt_pk_bf16_f32 v59, v64, v65
	v_cvt_pk_bf16_f32 v60, v66, v67
	v_cvt_pk_bf16_f32 v61, v68, v69
	v_lshl_add_u64 v[62:63], v[62:63], 0, v[122:123]
	global_store_dwordx4 v[62:63], v[58:61], off
	v_add_u32_e32 v66, 0xa0, v160
	v_ashrrev_i32_e32 v67, 31, v66
	s_waitcnt vmcnt(6)
	v_lshlrev_b32_e32 v58, 16, v74
	v_and_b32_e32 v59, 0xffff0000, v74
	s_waitcnt vmcnt(5)
	v_lshlrev_b32_e32 v60, 16, v78
	v_and_b32_e32 v61, 0xffff0000, v78
	v_pk_fma_f32 v[54:55], v[54:55], v[58:59], v[60:61]
	v_lshlrev_b32_e32 v58, 16, v75
	v_and_b32_e32 v59, 0xffff0000, v75
	v_lshlrev_b32_e32 v60, 16, v79
	v_and_b32_e32 v61, 0xffff0000, v79
	v_pk_fma_f32 v[56:57], v[56:57], v[58:59], v[60:61]
	v_lshlrev_b32_e32 v58, 16, v76
	v_and_b32_e32 v59, 0xffff0000, v76
	v_lshlrev_b32_e32 v60, 16, v80
	v_and_b32_e32 v61, 0xffff0000, v80
	v_pk_fma_f32 v[58:59], v[50:51], v[58:59], v[60:61]
	v_lshlrev_b32_e32 v50, 16, v77
	v_and_b32_e32 v51, 0xffff0000, v77
	v_lshlrev_b32_e32 v60, 16, v81
	v_and_b32_e32 v61, 0xffff0000, v81
	v_pk_fma_f32 v[60:61], v[52:53], v[50:51], v[60:61]
	v_cvt_pk_bf16_f32 v50, v54, v55
	v_cvt_pk_bf16_f32 v51, v56, v57
	v_cvt_pk_bf16_f32 v52, v58, v59
	v_cvt_pk_bf16_f32 v53, v60, v61
	global_store_dwordx4 v[62:63], v[50:53], off offset:256
	s_waitcnt vmcnt(4)
	v_lshlrev_b32_e32 v54, 16, v86
	v_and_b32_e32 v55, 0xffff0000, v86
	v_lshlrev_b32_e32 v52, 16, v82
	v_and_b32_e32 v53, 0xffff0000, v82
	v_pk_fma_f32 v[46:47], v[46:47], v[52:53], v[54:55]
	v_lshlrev_b32_e32 v52, 16, v83
	v_and_b32_e32 v53, 0xffff0000, v83
	v_lshlrev_b32_e32 v54, 16, v87
	v_and_b32_e32 v55, 0xffff0000, v87
	v_pk_fma_f32 v[48:49], v[48:49], v[52:53], v[54:55]
	v_lshlrev_b32_e32 v52, 16, v84
	v_and_b32_e32 v53, 0xffff0000, v84
	v_lshlrev_b32_e32 v54, 16, v88
	v_and_b32_e32 v55, 0xffff0000, v88
	v_lshlrev_b64 v[50:51], 11, v[100:101]
	v_pk_fma_f32 v[52:53], v[42:43], v[52:53], v[54:55]
	v_lshlrev_b32_e32 v42, 16, v85
	v_and_b32_e32 v43, 0xffff0000, v85
	v_lshlrev_b32_e32 v54, 16, v89
	v_and_b32_e32 v55, 0xffff0000, v89
	v_pk_fma_f32 v[54:55], v[44:45], v[42:43], v[54:55]
	v_cvt_pk_bf16_f32 v42, v46, v47
	v_lshl_add_u64 v[46:47], s[60:61], 0, v[50:51]
	v_cvt_pk_bf16_f32 v43, v48, v49
	v_cvt_pk_bf16_f32 v44, v52, v53
	v_cvt_pk_bf16_f32 v45, v54, v55
	v_lshl_add_u64 v[46:47], v[46:47], 0, v[122:123]
	global_store_dwordx4 v[46:47], v[42:45], off
	v_add_u32_e32 v68, 0xb0, v160
	v_ashrrev_i32_e32 v69, 31, v68
	s_waitcnt vmcnt(4)
	v_lshlrev_b32_e32 v42, 16, v90
	v_and_b32_e32 v43, 0xffff0000, v90
	s_waitcnt vmcnt(3)
; __device__ __forceinline__ unsigned pk2(float lo, float hi) { const f32x2 v = {lo, hi}; const bf16x2_t b = __builtin_convertvector(v, bf16x2_t); return __builtin_bit_cast(unsigned, b); }
; #define PG8_BAR __builtin_amdgcn_s_barrier()
; template <class Epi>
; __device__ __forceinline__ void gemm_phase(LAS unsigned char* lds, const int tid, const Gemm g, const StaticOrder& S, const Epi& E) {
;     ...
;         if (!has_next) break;
; #pragma unroll
;         for (int a = 0; a < 2; ++a)
; #pragma unroll
;             for (int b = 0; b < 2; ++b)
; #pragma unroll
;                 for (int m = 0; m < 4; ++m)
; #pragma unroll
;                     for (int n = 0; n < 2; ++n) acc[a][b][m][n] = (f32x4){0.f, 0.f, 0.f, 0.f};
;         cur = nxt; cA = nA; cB = nB; ++ui;
;         if (wr == 1) PG8_BAR;
;     template <int NA, int NM> __device__ __forceinline__ void operator()(const f32x4 (&acc)[NA][2][NM][2], const pg8::Unit& u, int ro, int wr, int wc, int fr, int fq) const {
;     ...
; #pragma unroll
;             for (int m = mp; m < (NM < 2 ? NM : mp + 2); ++m)
; #pragma unroll
;                 for (int bj = 0; bj < 2; ++bj) {
;                     const size_t o = (size_t)(u.pm * 256 + ro + ai * 128 + wr * 64 + m * 16 + fr) * D + colt + bj * 128;
;                     const u32x4 gg = g[m][bj];
;                     f32x4 v0 = acc[ai][bj][m][0], v1 = acc[ai][bj][m][1];
;                     v0.x *= bflo(gg.x); v0.y *= bfhi(gg.x); v0.z *= bflo(gg.y); v0.w *= bfhi(gg.y);
;                     v1.x *= bflo(gg.z); v1.y *= bfhi(gg.z); v1.z *= bflo(gg.w); v1.w *= bfhi(gg.w);
;                     if (PASS == 2) { const u32x4 tt = t[m][bj];
;                         v0.x += bflo(tt.x); v0.y += bfhi(tt.x); v0.z += bflo(tt.y); v0.w += bfhi(tt.y);
;                         v1.x += bflo(tt.z); v1.y += bfhi(tt.z); v1.z += bflo(tt.w); v1.w += bfhi(tt.w); }
;                     u32x4 w; w.x = pk2(v0.x, v0.y); w.y = pk2(v0.z, v0.w); w.z = pk2(v1.x, v1.y); w.w = pk2(v1.z, v1.w);
;                     *(u32x4*)(Y + o) = w;
;                 }
	v_lshlrev_b32_e32 v44, 16, v94
	v_and_b32_e32 v45, 0xffff0000, v94
	v_pk_fma_f32 v[38:39], v[38:39], v[42:43], v[44:45]
	v_lshlrev_b32_e32 v42, 16, v91
	v_and_b32_e32 v43, 0xffff0000, v91
	v_lshlrev_b32_e32 v44, 16, v95
	v_and_b32_e32 v45, 0xffff0000, v95
	v_pk_fma_f32 v[40:41], v[40:41], v[42:43], v[44:45]
	v_lshlrev_b32_e32 v42, 16, v92
	v_and_b32_e32 v43, 0xffff0000, v92
	v_lshlrev_b32_e32 v44, 16, v96
	v_and_b32_e32 v45, 0xffff0000, v96
	v_pk_fma_f32 v[42:43], v[34:35], v[42:43], v[44:45]
	v_lshlrev_b32_e32 v34, 16, v93
	v_and_b32_e32 v35, 0xffff0000, v93
	v_lshlrev_b32_e32 v44, 16, v97
	v_and_b32_e32 v45, 0xffff0000, v97
	v_pk_fma_f32 v[44:45], v[36:37], v[34:35], v[44:45]
	v_cvt_pk_bf16_f32 v34, v38, v39
	v_cvt_pk_bf16_f32 v35, v40, v41
	v_cvt_pk_bf16_f32 v36, v42, v43
	v_cvt_pk_bf16_f32 v37, v44, v45
	global_store_dwordx4 v[46:47], v[34:37], off offset:256
	v_lshlrev_b64 v[50:51], 10, v[68:69]
	v_lshl_add_u64 v[50:51], v[50:51], 0, v[158:159]
	v_lshlrev_b64 v[34:35], 10, v[66:67]
	v_lshl_add_u64 v[34:35], v[34:35], 0, v[158:159]
	v_lshlrev_b64 v[42:43], 1, v[34:35]
	v_lshl_add_u64 v[34:35], s[0:1], 0, v[42:43]
	v_lshl_add_u64 v[46:47], s[50:51], 0, v[42:43]
	global_load_dwordx4 v[34:37], v[34:35], off
	v_or_b32_e32 v42, 0x100, v42
	global_load_dwordx4 v[38:41], v[46:47], off
	v_lshl_add_u64 v[42:43], s[0:1], 0, v[42:43]
	global_load_dwordx4 v[42:45], v[42:43], off
	s_nop 0
	global_load_dwordx4 v[46:49], v[46:47], off offset:256
	v_lshlrev_b64 v[58:59], 1, v[50:51]
	v_lshl_add_u64 v[50:51], s[0:1], 0, v[58:59]
	v_lshl_add_u64 v[62:63], s[50:51], 0, v[58:59]
	global_load_dwordx4 v[50:53], v[50:51], off
	v_or_b32_e32 v58, 0x100, v58
	global_load_dwordx4 v[54:57], v[62:63], off
	v_lshl_add_u64 v[58:59], s[0:1], 0, v[58:59]
	global_load_dwordx4 v[58:61], v[58:59], off
	s_nop 0
	global_load_dwordx4 v[62:65], v[62:63], off offset:256
	v_lshlrev_b64 v[66:67], 11, v[66:67]
	s_waitcnt vmcnt(7)
	v_lshlrev_b32_e32 v70, 16, v34
	v_and_b32_e32 v71, 0xffff0000, v34
	s_waitcnt vmcnt(6)
	v_lshlrev_b32_e32 v72, 16, v38
	v_and_b32_e32 v73, 0xffff0000, v38
	v_lshlrev_b32_e32 v34, 16, v35
	v_and_b32_e32 v35, 0xffff0000, v35
	v_lshlrev_b32_e32 v38, 16, v39
	v_and_b32_e32 v39, 0xffff0000, v39
	v_pk_fma_f32 v[32:33], v[32:33], v[34:35], v[38:39]
	v_lshlrev_b32_e32 v34, 16, v36
	v_and_b32_e32 v35, 0xffff0000, v36
	v_lshlrev_b32_e32 v38, 16, v40
	v_and_b32_e32 v39, 0xffff0000, v40
	v_pk_fma_f32 v[30:31], v[30:31], v[70:71], v[72:73]
	v_pk_fma_f32 v[34:35], v[26:27], v[34:35], v[38:39]
	v_lshlrev_b32_e32 v26, 16, v37
	v_and_b32_e32 v27, 0xffff0000, v37
	v_lshlrev_b32_e32 v36, 16, v41
	v_and_b32_e32 v37, 0xffff0000, v41
	v_pk_fma_f32 v[36:37], v[28:29], v[26:27], v[36:37]
	v_cvt_pk_bf16_f32 v26, v30, v31
	v_lshl_add_u64 v[30:31], s[60:61], 0, v[66:67]
	v_cvt_pk_bf16_f32 v27, v32, v33
	v_cvt_pk_bf16_f32 v28, v34, v35
	v_cvt_pk_bf16_f32 v29, v36, v37
	v_lshl_add_u64 v[30:31], v[30:31], 0, v[122:123]
	global_store_dwordx4 v[30:31], v[26:29], off
	s_waitcnt vmcnt(6)
	s_nop 0
	v_lshlrev_b32_e32 v26, 16, v42
	v_and_b32_e32 v27, 0xffff0000, v42
	s_waitcnt vmcnt(5)
	v_lshlrev_b32_e32 v28, 16, v46
	v_and_b32_e32 v29, 0xffff0000, v46
	v_pk_fma_f32 v[22:23], v[22:23], v[26:27], v[28:29]
	v_lshlrev_b32_e32 v26, 16, v43
	v_and_b32_e32 v27, 0xffff0000, v43
	v_lshlrev_b32_e32 v28, 16, v47
	v_and_b32_e32 v29, 0xffff0000, v47
	v_pk_fma_f32 v[24:25], v[24:25], v[26:27], v[28:29]
	v_lshlrev_b32_e32 v26, 16, v44
	v_and_b32_e32 v27, 0xffff0000, v44
	v_lshlrev_b32_e32 v28, 16, v48
	v_and_b32_e32 v29, 0xffff0000, v48
	v_pk_fma_f32 v[26:27], v[18:19], v[26:27], v[28:29]
	v_lshlrev_b32_e32 v18, 16, v45
	v_and_b32_e32 v19, 0xffff0000, v45
	v_lshlrev_b32_e32 v28, 16, v49
	v_and_b32_e32 v29, 0xffff0000, v49
	v_pk_fma_f32 v[28:29], v[20:21], v[18:19], v[28:29]
	v_cvt_pk_bf16_f32 v18, v22, v23
	v_cvt_pk_bf16_f32 v19, v24, v25
	v_cvt_pk_bf16_f32 v20, v26, v27
	v_cvt_pk_bf16_f32 v21, v28, v29
	global_store_dwordx4 v[30:31], v[18:21], off offset:256
	s_waitcnt vmcnt(4)
	v_lshlrev_b32_e32 v22, 16, v54
	v_and_b32_e32 v23, 0xffff0000, v54
	v_lshlrev_b32_e32 v20, 16, v50
	v_and_b32_e32 v21, 0xffff0000, v50
	v_pk_fma_f32 v[14:15], v[14:15], v[20:21], v[22:23]
	v_lshlrev_b32_e32 v20, 16, v51
	v_and_b32_e32 v21, 0xffff0000, v51
	v_lshlrev_b32_e32 v22, 16, v55
	v_and_b32_e32 v23, 0xffff0000, v55
	v_pk_fma_f32 v[16:17], v[16:17], v[20:21], v[22:23]
	v_lshlrev_b32_e32 v20, 16, v52
	v_and_b32_e32 v21, 0xffff0000, v52
	v_lshlrev_b32_e32 v22, 16, v56
	v_and_b32_e32 v23, 0xffff0000, v56
	v_lshlrev_b64 v[18:19], 11, v[68:69]
	v_pk_fma_f32 v[20:21], v[10:11], v[20:21], v[22:23]
	v_lshlrev_b32_e32 v10, 16, v53
	v_and_b32_e32 v11, 0xffff0000, v53
	v_lshlrev_b32_e32 v22, 16, v57
	v_and_b32_e32 v23, 0xffff0000, v57
	v_pk_fma_f32 v[22:23], v[12:13], v[10:11], v[22:23]
	v_cvt_pk_bf16_f32 v10, v14, v15
	v_lshl_add_u64 v[14:15], s[60:61], 0, v[18:19]
	v_cvt_pk_bf16_f32 v11, v16, v17
	v_cvt_pk_bf16_f32 v12, v20, v21
	v_cvt_pk_bf16_f32 v13, v22, v23
	v_lshl_add_u64 v[14:15], v[14:15], 0, v[122:123]
	global_store_dwordx4 v[14:15], v[10:13], off
	s_waitcnt vmcnt(4)
	s_nop 0
	v_lshlrev_b32_e32 v10, 16, v58
	v_and_b32_e32 v11, 0xffff0000, v58
	s_waitcnt vmcnt(3)
	v_lshlrev_b32_e32 v12, 16, v62
	v_and_b32_e32 v13, 0xffff0000, v62
	v_pk_fma_f32 v[6:7], v[6:7], v[10:11], v[12:13]
	v_lshlrev_b32_e32 v10, 16, v59
	v_and_b32_e32 v11, 0xffff0000, v59
	v_lshlrev_b32_e32 v12, 16, v63
	v_and_b32_e32 v13, 0xffff0000, v63
	v_pk_fma_f32 v[8:9], v[8:9], v[10:11], v[12:13]
	v_lshlrev_b32_e32 v10, 16, v60
	v_and_b32_e32 v11, 0xffff0000, v60
	v_lshlrev_b32_e32 v12, 16, v64
	v_and_b32_e32 v13, 0xffff0000, v64
	v_pk_fma_f32 v[10:11], v[2:3], v[10:11], v[12:13]
	v_lshlrev_b32_e32 v2, 16, v61
	v_and_b32_e32 v3, 0xffff0000, v61
	v_lshlrev_b32_e32 v12, 16, v65
	v_and_b32_e32 v13, 0xffff0000, v65
	v_pk_fma_f32 v[12:13], v[4:5], v[2:3], v[12:13]
	v_cvt_pk_bf16_f32 v2, v6, v7
	v_cvt_pk_bf16_f32 v3, v8, v9
	v_cvt_pk_bf16_f32 v4, v10, v11
	v_cvt_pk_bf16_f32 v5, v12, v13
	global_store_dwordx4 v[14:15], v[2:5], off offset:256
	s_cbranch_vccnz .LBB0_1325
	s_andn2_b64 vcc, exec, s[4:5]
	s_cbranch_vccnz .LBB0_1324
	s_barrier
	s_branch .LBB0_1324

; #define PG8_STAGE(bufoff, gbase, voff) do { _Pragma("unroll") for (int _i = 0; _i < 2; ++_i) \
;         __builtin_amdgcn_global_load_lds((const unsigned*)((const char*)(gbase) + (voff)[_i]), (LAS unsigned*)(lds + (bufoff) + ldsw + _i * 8192), 16, 0, 0); } while (0)
; #define PG8_LDA(dst, b, h) do { _Pragma("unroll") for (int m = 0; m < 4; ++m) _Pragma("unroll") for (int k = 0; k < 2; ++k) dst[m][k] = *(const LAS bf16x8*)(lds + PG8_SA(b, h) + aoff + m * 2048 + k * 1024); } while (0)
; #define PG8_LDB(dst, b, h) do { _Pragma("unroll") for (int n = 0; n < 2; ++n) _Pragma("unroll") for (int k = 0; k < 2; ++k) dst[n][k] = *(const LAS bf16x8*)(lds + PG8_SB(b, h) + boff + n * 2048 + k * 1024); } while (0)
; #define PG8_MMA(ai, bj, At, Bt) do { __builtin_amdgcn_s_setprio(1); _Pragma("unroll") for (int m = 0; m < 4; ++m) _Pragma("unroll") for (int n = 0; n < 2; ++n) _Pragma("unroll") for (int k = 0; k < 2; ++k) \
;         acc[ai][bj][m][n] = __builtin_amdgcn_mfma_f32_16x16x32_bf16(Bt[n][k], At[m][k], acc[ai][bj][m][n], 0, 0, 0); __builtin_amdgcn_s_setprio(0); } while (0)
; #define PG8_WAIT_V(n) asm volatile("s_waitcnt vmcnt(" #n ")" ::: "memory")
; #define PG8_WAIT_L(n) asm volatile("s_waitcnt lgkmcnt(" #n ")" ::: "memory")
; #define PG8_BAR __builtin_amdgcn_s_barrier()
; #define PG8_SCHED __builtin_amdgcn_sched_barrier(0)
; template <class Epi>
; __device__ __forceinline__ void gemm_phase(LAS unsigned char* lds, const int tid, const Gemm g, const StaticOrder& S, const Epi& E) {
;     ...
;             PG8_LDB(B0, 0, 0); PG8_LDB(B1, 0, 1); PG8_SCHED; PG8_LDA(At, 0, 0); PG8_STAGE(PG8_SA(1, 1), a1 + hstepA, voffA);
;             PG8_WAIT_V(8); PG8_WAIT_L(0); PG8_BAR; PG8_MMA(0, 0, At, B0); PG8_MMA(0, 1, At, B1); PG8_BAR; PG8_SCHED;
;             PG8_LDA(At, 0, 1); PG8_STAGE(PG8_SB(0, 0), b2, voffB); PG8_STAGE(PG8_SB(0, 1), b2 + hstepB, voffB); PG8_STAGE(PG8_SA(0, 0), a2, voffA);
;             PG8_WAIT_V(8); PG8_WAIT_L(0); PG8_BAR; PG8_MMA(1, 0, At, B0); PG8_MMA(1, 1, At, B1); PG8_BAR; PG8_SCHED;
.LBB0_1487:
	s_add_u32 s27, s68, 0xfffc0080
	s_addc_u32 s30, s69, -1
	s_add_i32 s62, 0, 0x10000
	s_cmp_eq_u32 s26, 12
	s_cselect_b32 vcc_hi, s28, s30
	s_cselect_b32 vcc_lo, s71, s27
	s_cselect_b32 s31, s5, s83
	s_cselect_b32 s30, s73, s75
	s_add_i32 s27, 0, 0x14000
	v_add_u32_e32 v142, s62, v216
	v_add_u32_e32 v158, s27, v216
	ds_read_b128 v[130:133], v142
	ds_read_b128 v[134:137], v142 offset:1024
	ds_read_b128 v[138:141], v142 offset:2048
	ds_read_b128 v[142:145], v142 offset:3072
	ds_read_b128 v[146:149], v158
	ds_read_b128 v[150:153], v158 offset:1024
	ds_read_b128 v[154:157], v158 offset:2048
	ds_read_b128 v[158:161], v158 offset:3072
	v_lshl_add_u64 v[162:163], s[68:69], 0, v[176:177]
	s_add_i32 m0, s1, 0xc000
	s_nop 0
	global_load_lds_dwordx4 v[162:163], off
	v_lshl_add_u64 v[162:163], s[68:69], 0, v[178:179]
	s_add_i32 m0, s1, 0xe000
	s_nop 0
	global_load_lds_dwordx4 v[162:163], off
	ds_read_b128 v[180:183], v218
	ds_read_b128 v[184:187], v218 offset:1024
	ds_read_b128 v[220:223], v218 offset:2048
	ds_read_b128 v[224:227], v218 offset:3072
	ds_read_b128 v[228:231], v218 offset:4096
	ds_read_b128 v[232:235], v218 offset:5120
	ds_read_b128 v[236:239], v218 offset:6144
	ds_read_b128 v[240:243], v218 offset:7168
	s_waitcnt vmcnt(8)
	s_waitcnt lgkmcnt(0)
	s_barrier
	s_setprio 1
	s_waitcnt lgkmcnt(0)
	v_mfma_f32_16x16x32_bf16 v[126:129], v[130:133], v[180:183], v[126:129]
	v_mfma_f32_16x16x32_bf16 v[122:125], v[138:141], v[180:183], v[122:125]
	v_mfma_f32_16x16x32_bf16 v[110:113], v[130:133], v[220:223], v[110:113]
	v_mfma_f32_16x16x32_bf16 v[106:109], v[138:141], v[220:223], v[106:109]
	v_mfma_f32_16x16x32_bf16 v[94:97], v[130:133], v[228:231], v[94:97]
	v_mfma_f32_16x16x32_bf16 v[90:93], v[138:141], v[228:231], v[90:93]
	v_mfma_f32_16x16x32_bf16 v[78:81], v[130:133], v[236:239], v[78:81]
	v_mfma_f32_16x16x32_bf16 v[74:77], v[138:141], v[236:239], v[74:77]
	v_mfma_f32_16x16x32_bf16 v[126:129], v[134:137], v[184:187], v[126:129]
	v_mfma_f32_16x16x32_bf16 v[122:125], v[142:145], v[184:187], v[122:125]
	v_mfma_f32_16x16x32_bf16 v[110:113], v[134:137], v[224:227], v[110:113]
	v_mfma_f32_16x16x32_bf16 v[106:109], v[142:145], v[224:227], v[106:109]
	v_mfma_f32_16x16x32_bf16 v[94:97], v[134:137], v[232:235], v[94:97]
	v_mfma_f32_16x16x32_bf16 v[90:93], v[142:145], v[232:235], v[90:93]
	v_mfma_f32_16x16x32_bf16 v[78:81], v[134:137], v[240:243], v[78:81]
	v_mfma_f32_16x16x32_bf16 v[74:77], v[142:145], v[240:243], v[74:77]
	s_setprio 0
	s_setprio 1
	v_mfma_f32_16x16x32_bf16 v[118:121], v[146:149], v[180:183], v[118:121]
	v_mfma_f32_16x16x32_bf16 v[114:117], v[154:157], v[180:183], v[114:117]
	v_mfma_f32_16x16x32_bf16 v[102:105], v[146:149], v[220:223], v[102:105]
	v_mfma_f32_16x16x32_bf16 v[98:101], v[154:157], v[220:223], v[98:101]
	v_mfma_f32_16x16x32_bf16 v[86:89], v[146:149], v[228:231], v[86:89]
	v_mfma_f32_16x16x32_bf16 v[82:85], v[154:157], v[228:231], v[82:85]
	v_mfma_f32_16x16x32_bf16 v[70:73], v[146:149], v[236:239], v[70:73]
	v_mfma_f32_16x16x32_bf16 v[66:69], v[154:157], v[236:239], v[66:69]
	v_mfma_f32_16x16x32_bf16 v[118:121], v[150:153], v[184:187], v[118:121]
	v_mfma_f32_16x16x32_bf16 v[114:117], v[158:161], v[184:187], v[114:117]
	v_mfma_f32_16x16x32_bf16 v[102:105], v[150:153], v[224:227], v[102:105]
	v_mfma_f32_16x16x32_bf16 v[98:101], v[158:161], v[224:227], v[98:101]
	v_mfma_f32_16x16x32_bf16 v[86:89], v[150:153], v[232:235], v[86:89]
	v_mfma_f32_16x16x32_bf16 v[82:85], v[158:161], v[232:235], v[82:85]
	v_mfma_f32_16x16x32_bf16 v[70:73], v[150:153], v[240:243], v[70:73]
	v_mfma_f32_16x16x32_bf16 v[66:69], v[158:161], v[240:243], v[66:69]
	s_setprio 0
	s_barrier
	s_add_i32 s62, s62, s0
	v_lshl_add_u64 v[162:163], s[30:31], 0, v[0:1]
	s_mov_b32 m0, s62
	s_nop 0
	global_load_lds_dwordx4 v[162:163], off
	s_add_i32 m0, s62, 0x2000
	s_add_u32 s62, s30, 0x40000
	v_lshl_add_u64 v[164:165], s[30:31], 0, v[170:171]
	s_addc_u32 s63, s31, 0
	s_add_i32 s27, s27, s0
	global_load_lds_dwordx4 v[164:165], off
	v_lshl_add_u64 v[206:207], s[62:63], 0, v[0:1]
	s_mov_b32 m0, s27
	v_lshl_add_u64 v[244:245], vcc, 0, v[174:175]
	global_load_lds_dwordx4 v[206:207], off
	v_lshl_add_u64 v[206:207], s[62:63], 0, v[170:171]
	s_add_i32 m0, s27, 0x2000
	s_nop 0
	global_load_lds_dwordx4 v[206:207], off
	v_lshl_add_u64 v[206:207], vcc, 0, v[172:173]
	s_mov_b32 m0, s1
	s_nop 0
	global_load_lds_dwordx4 v[206:207], off
	s_mov_b32 m0, s2
	s_nop 0
	global_load_lds_dwordx4 v[244:245], off
	ds_read_b128 v[180:183], v218 offset:16384
	ds_read_b128 v[184:187], v218 offset:17408
	ds_read_b128 v[220:223], v218 offset:18432
	ds_read_b128 v[224:227], v218 offset:19456
	ds_read_b128 v[228:231], v218 offset:20480
	ds_read_b128 v[232:235], v218 offset:21504
	ds_read_b128 v[236:239], v218 offset:22528
	ds_read_b128 v[240:243], v218 offset:23552
	s_waitcnt vmcnt(8)
	s_waitcnt lgkmcnt(0)
	s_barrier
; #define PG8_STAGE(bufoff, gbase, voff) do { _Pragma("unroll") for (int _i = 0; _i < 2; ++_i) \
;         __builtin_amdgcn_global_load_lds((const unsigned*)((const char*)(gbase) + (voff)[_i]), (LAS unsigned*)(lds + (bufoff) + ldsw + _i * 8192), 16, 0, 0); } while (0)
; #define PG8_LDA(dst, b, h) do { _Pragma("unroll") for (int m = 0; m < 4; ++m) _Pragma("unroll") for (int k = 0; k < 2; ++k) dst[m][k] = *(const LAS bf16x8*)(lds + PG8_SA(b, h) + aoff + m * 2048 + k * 1024); } while (0)
; #define PG8_LDB(dst, b, h) do { _Pragma("unroll") for (int n = 0; n < 2; ++n) _Pragma("unroll") for (int k = 0; k < 2; ++k) dst[n][k] = *(const LAS bf16x8*)(lds + PG8_SB(b, h) + boff + n * 2048 + k * 1024); } while (0)
; #define PG8_MMA(ai, bj, At, Bt) do { __builtin_amdgcn_s_setprio(1); _Pragma("unroll") for (int m = 0; m < 4; ++m) _Pragma("unroll") for (int n = 0; n < 2; ++n) _Pragma("unroll") for (int k = 0; k < 2; ++k) \
;         acc[ai][bj][m][n] = __builtin_amdgcn_mfma_f32_16x16x32_bf16(Bt[n][k], At[m][k], acc[ai][bj][m][n], 0, 0, 0); __builtin_amdgcn_s_setprio(0); } while (0)
; #define PG8_WAIT_V(n) asm volatile("s_waitcnt vmcnt(" #n ")" ::: "memory")
; #define PG8_WAIT_L(n) asm volatile("s_waitcnt lgkmcnt(" #n ")" ::: "memory")
; #define PG8_BAR __builtin_amdgcn_s_barrier()
; #define PG8_SCHED __builtin_amdgcn_sched_barrier(0)
; template <class Epi>
; __device__ __forceinline__ void gemm_phase(LAS unsigned char* lds, const int tid, const Gemm g, const StaticOrder& S, const Epi& E) {
;     ...
;             PG8_WAIT_V(8); PG8_WAIT_L(0); PG8_BAR; PG8_MMA(1, 0, At, B0); PG8_MMA(1, 1, At, B1); PG8_BAR; PG8_SCHED;
;             PG8_LDB(B0, 1, 0); PG8_LDB(B1, 1, 1); PG8_SCHED; PG8_LDA(At, 1, 0); PG8_STAGE(PG8_SA(0, 1), a2 + hstepA, voffA);
;             PG8_WAIT_V(8); PG8_WAIT_L(0); PG8_BAR; PG8_MMA(0, 0, At, B0); PG8_MMA(0, 1, At, B1); PG8_BAR; PG8_SCHED;
	s_setprio 1
	s_waitcnt lgkmcnt(0)
	v_mfma_f32_16x16x32_bf16 v[62:65], v[130:133], v[180:183], v[62:65]
	v_mfma_f32_16x16x32_bf16 v[58:61], v[138:141], v[180:183], v[58:61]
	v_mfma_f32_16x16x32_bf16 v[46:49], v[130:133], v[220:223], v[46:49]
	v_mfma_f32_16x16x32_bf16 v[42:45], v[138:141], v[220:223], v[42:45]
	v_mfma_f32_16x16x32_bf16 v[30:33], v[130:133], v[228:231], v[30:33]
	v_mfma_f32_16x16x32_bf16 v[26:29], v[138:141], v[228:231], v[26:29]
	v_mfma_f32_16x16x32_bf16 v[14:17], v[130:133], v[236:239], v[14:17]
	v_mfma_f32_16x16x32_bf16 v[10:13], v[138:141], v[236:239], v[10:13]
	v_mfma_f32_16x16x32_bf16 v[62:65], v[134:137], v[184:187], v[62:65]
	v_mfma_f32_16x16x32_bf16 v[58:61], v[142:145], v[184:187], v[58:61]
	v_mfma_f32_16x16x32_bf16 v[46:49], v[134:137], v[224:227], v[46:49]
	v_mfma_f32_16x16x32_bf16 v[42:45], v[142:145], v[224:227], v[42:45]
	v_mfma_f32_16x16x32_bf16 v[30:33], v[134:137], v[232:235], v[30:33]
	v_mfma_f32_16x16x32_bf16 v[26:29], v[142:145], v[232:235], v[26:29]
	v_mfma_f32_16x16x32_bf16 v[14:17], v[134:137], v[240:243], v[14:17]
	v_mfma_f32_16x16x32_bf16 v[10:13], v[142:145], v[240:243], v[10:13]
	s_setprio 0
	s_setprio 1
	v_mfma_f32_16x16x32_bf16 v[54:57], v[146:149], v[180:183], v[54:57]
	v_mfma_f32_16x16x32_bf16 v[50:53], v[154:157], v[180:183], v[50:53]
	v_mfma_f32_16x16x32_bf16 v[38:41], v[146:149], v[220:223], v[38:41]
	v_mfma_f32_16x16x32_bf16 v[34:37], v[154:157], v[220:223], v[34:37]
	v_mfma_f32_16x16x32_bf16 v[22:25], v[146:149], v[228:231], v[22:25]
	v_mfma_f32_16x16x32_bf16 v[18:21], v[154:157], v[228:231], v[18:21]
	v_mfma_f32_16x16x32_bf16 v[6:9], v[146:149], v[236:239], v[6:9]
	v_mfma_f32_16x16x32_bf16 v[2:5], v[154:157], v[236:239], v[2:5]
	v_mfma_f32_16x16x32_bf16 v[54:57], v[150:153], v[184:187], v[54:57]
	v_mfma_f32_16x16x32_bf16 v[50:53], v[158:161], v[184:187], v[50:53]
	v_mfma_f32_16x16x32_bf16 v[38:41], v[150:153], v[224:227], v[38:41]
	v_mfma_f32_16x16x32_bf16 v[34:37], v[158:161], v[224:227], v[34:37]
	v_mfma_f32_16x16x32_bf16 v[22:25], v[150:153], v[232:235], v[22:25]
	v_mfma_f32_16x16x32_bf16 v[18:21], v[158:161], v[232:235], v[18:21]
	v_mfma_f32_16x16x32_bf16 v[6:9], v[150:153], v[240:243], v[6:9]
	v_mfma_f32_16x16x32_bf16 v[2:5], v[158:161], v[240:243], v[2:5]
	s_setprio 0
	s_barrier
	s_add_i32 s27, 0, 0x18000
	s_add_i32 s17, 0, 0x1c000
	v_add_u32_e32 v142, s27, v216
	v_add_u32_e32 v158, s17, v216
	ds_read_b128 v[130:133], v142
	ds_read_b128 v[134:137], v142 offset:1024
	ds_read_b128 v[138:141], v142 offset:2048
	ds_read_b128 v[142:145], v142 offset:3072
	ds_read_b128 v[146:149], v158
	ds_read_b128 v[150:153], v158 offset:1024
	ds_read_b128 v[154:157], v158 offset:2048
	ds_read_b128 v[158:161], v158 offset:3072
	s_add_u32 s62, vcc_lo, 0x40000
	s_addc_u32 s63, vcc_hi, 0
	s_mov_b32 m0, s3
	v_lshl_add_u64 v[246:247], s[62:63], 0, v[172:173]
	global_load_lds_dwordx4 v[246:247], off
	v_lshl_add_u64 v[246:247], s[62:63], 0, v[174:175]
	s_mov_b32 m0, s16
	s_nop 0
	global_load_lds_dwordx4 v[246:247], off
	ds_read_b128 v[180:183], v218 offset:32768
	ds_read_b128 v[184:187], v218 offset:33792
	ds_read_b128 v[220:223], v218 offset:34816
	ds_read_b128 v[224:227], v218 offset:35840
	ds_read_b128 v[228:231], v218 offset:36864
	ds_read_b128 v[232:235], v218 offset:37888
	ds_read_b128 v[236:239], v218 offset:38912
	ds_read_b128 v[240:243], v218 offset:39936
	s_waitcnt vmcnt(8)
	s_waitcnt lgkmcnt(0)
	s_barrier
	s_setprio 1
	s_waitcnt lgkmcnt(0)
	v_mfma_f32_16x16x32_bf16 v[126:129], v[130:133], v[180:183], v[126:129]
	v_mfma_f32_16x16x32_bf16 v[122:125], v[138:141], v[180:183], v[122:125]
	v_mfma_f32_16x16x32_bf16 v[110:113], v[130:133], v[220:223], v[110:113]
	v_mfma_f32_16x16x32_bf16 v[106:109], v[138:141], v[220:223], v[106:109]
	v_mfma_f32_16x16x32_bf16 v[94:97], v[130:133], v[228:231], v[94:97]
	v_mfma_f32_16x16x32_bf16 v[90:93], v[138:141], v[228:231], v[90:93]
	v_mfma_f32_16x16x32_bf16 v[78:81], v[130:133], v[236:239], v[78:81]
	v_mfma_f32_16x16x32_bf16 v[74:77], v[138:141], v[236:239], v[74:77]
	v_mfma_f32_16x16x32_bf16 v[126:129], v[134:137], v[184:187], v[126:129]
	v_mfma_f32_16x16x32_bf16 v[122:125], v[142:145], v[184:187], v[122:125]
	v_mfma_f32_16x16x32_bf16 v[110:113], v[134:137], v[224:227], v[110:113]
	v_mfma_f32_16x16x32_bf16 v[106:109], v[142:145], v[224:227], v[106:109]
	v_mfma_f32_16x16x32_bf16 v[94:97], v[134:137], v[232:235], v[94:97]
	v_mfma_f32_16x16x32_bf16 v[90:93], v[142:145], v[232:235], v[90:93]
	v_mfma_f32_16x16x32_bf16 v[78:81], v[134:137], v[240:243], v[78:81]
	v_mfma_f32_16x16x32_bf16 v[74:77], v[142:145], v[240:243], v[74:77]
	s_setprio 0
	s_setprio 1
	v_mfma_f32_16x16x32_bf16 v[118:121], v[146:149], v[180:183], v[118:121]
	v_mfma_f32_16x16x32_bf16 v[114:117], v[154:157], v[180:183], v[114:117]
	v_mfma_f32_16x16x32_bf16 v[102:105], v[146:149], v[220:223], v[102:105]
	v_mfma_f32_16x16x32_bf16 v[98:101], v[154:157], v[220:223], v[98:101]
	v_mfma_f32_16x16x32_bf16 v[86:89], v[146:149], v[228:231], v[86:89]
	v_mfma_f32_16x16x32_bf16 v[82:85], v[154:157], v[228:231], v[82:85]
	v_mfma_f32_16x16x32_bf16 v[70:73], v[146:149], v[236:239], v[70:73]
	v_mfma_f32_16x16x32_bf16 v[66:69], v[154:157], v[236:239], v[66:69]
	v_mfma_f32_16x16x32_bf16 v[118:121], v[150:153], v[184:187], v[118:121]
	v_mfma_f32_16x16x32_bf16 v[114:117], v[158:161], v[184:187], v[114:117]
	v_mfma_f32_16x16x32_bf16 v[102:105], v[150:153], v[224:227], v[102:105]
	v_mfma_f32_16x16x32_bf16 v[98:101], v[158:161], v[224:227], v[98:101]
	v_mfma_f32_16x16x32_bf16 v[86:89], v[150:153], v[232:235], v[86:89]
	v_mfma_f32_16x16x32_bf16 v[82:85], v[158:161], v[232:235], v[82:85]
	v_mfma_f32_16x16x32_bf16 v[70:73], v[150:153], v[240:243], v[70:73]
	v_mfma_f32_16x16x32_bf16 v[66:69], v[158:161], v[240:243], v[66:69]
	s_setprio 0
	s_barrier
; #define LAS __attribute__((address_space(3)))
; #define PG8_STAGE(bufoff, gbase, voff) do { _Pragma("unroll") for (int _i = 0; _i < 2; ++_i) \
;         __builtin_amdgcn_global_load_lds((const unsigned*)((const char*)(gbase) + (voff)[_i]), (LAS unsigned*)(lds + (bufoff) + ldsw + _i * 8192), 16, 0, 0); } while (0)
; #define PG8_LDA(dst, b, h) do { _Pragma("unroll") for (int m = 0; m < 4; ++m) _Pragma("unroll") for (int k = 0; k < 2; ++k) dst[m][k] = *(const LAS bf16x8*)(lds + PG8_SA(b, h) + aoff + m * 2048 + k * 1024); } while (0)
; #define PG8_WAIT_V(n) asm volatile("s_waitcnt vmcnt(" #n ")" ::: "memory")
; #define PG8_WAIT_L(n) asm volatile("s_waitcnt lgkmcnt(" #n ")" ::: "memory")
; #define PG8_BAR __builtin_amdgcn_s_barrier()
; #define PG8_SCHED __builtin_amdgcn_sched_barrier(0)
; template <class Epi>
; __device__ __forceinline__ void gemm_phase(LAS unsigned char* lds, const int tid, const Gemm g, const StaticOrder& S, const Epi& E) {
;     ...
;             PG8_WAIT_V(8); PG8_WAIT_L(0); PG8_BAR; PG8_MMA(0, 0, At, B0); PG8_MMA(0, 1, At, B1); PG8_BAR; PG8_SCHED;
;             PG8_LDA(At, 1, 1); PG8_STAGE(PG8_SB(1, 0), b3, voffB); PG8_STAGE(PG8_SB(1, 1), b3 + hstepB, voffB); PG8_STAGE(PG8_SA(1, 0), a3, voffA);
;             PG8_WAIT_V(8); PG8_WAIT_L(0); PG8_BAR; PG8_MMA(1, 0, At, B0); PG8_MMA(1, 1, At, B1); PG8_BAR; PG8_SCHED;
;         }
;         if (wr == 0) PG8_BAR;
;     template <int NA, int NM> __device__ __forceinline__ void operator()(const f32x4 (&acc)[NA][2][NM][2], const pg8::Unit& u, int ro, int wr, int wc, int fr, int fq) const {
;         const int j = u.pm < 32 ? 0 : (u.pm < 64 ? 1 : 2);
;         const int colt = u.pn * 256 + wc * 32 + 8 * fq;
;         LAS f32x4* cs = (LAS f32x4*)((LAS unsigned char*)0 + pg8::STAGE_BYTES) + ((wr * 4 + wc) * 4 + fq) * 8;
; #pragma unroll
;         for (int bj = 0; bj < 2; ++bj)
; #pragma unroll
;             for (int n = 0; n < 2; ++n) {
;                 const f32x4 gvv = *(const f32x4*)(gate + (size_t)j * NMOD + colt + bj * 128 + 4 * n);
;                 f32x4 svv = (f32x4){0.f, 0.f, 0.f, 0.f};
;                 if (nw) svv = *(const f32x4*)(nw + colt + bj * 128 + 4 * n) * (*(const f32x4*)(nsc + (size_t)j * NMOD + colt + bj * 128 + 4 * n) + 1.0f);
;                 if (fr == 0) { cs[bj * 2 + n] = gvv; cs[4 + bj * 2 + n] = svv; }
	s_add_i32 s27, s27, s0
	v_lshl_add_u64 v[162:163], v[162:163], 0, s[36:37]
	s_mov_b32 m0, s27
	s_nop 0
	global_load_lds_dwordx4 v[162:163], off
	s_add_i32 m0, s27, 0x2000
	s_add_u32 s30, s30, 0x40080
	v_lshl_add_u64 v[162:163], v[164:165], 0, s[36:37]
	s_addc_u32 s31, s31, 0
	s_add_i32 s17, s17, s0
	global_load_lds_dwordx4 v[162:163], off
	v_lshl_add_u64 v[162:163], s[30:31], 0, v[0:1]
	s_mov_b32 m0, s17
	s_nop 0
	global_load_lds_dwordx4 v[162:163], off
	v_lshl_add_u64 v[162:163], s[30:31], 0, v[170:171]
	s_add_i32 m0, s17, 0x2000
	s_nop 0
	global_load_lds_dwordx4 v[162:163], off
	v_lshl_add_u64 v[162:163], v[206:207], 0, s[36:37]
	s_mov_b32 m0, s10
	s_nop 0
	global_load_lds_dwordx4 v[162:163], off
	v_lshl_add_u64 v[162:163], v[244:245], 0, s[36:37]
	s_mov_b32 m0, s11
	s_nop 0
	global_load_lds_dwordx4 v[162:163], off
	ds_read_b128 v[180:183], v218 offset:49152
	ds_read_b128 v[184:187], v218 offset:50176
	ds_read_b128 v[220:223], v218 offset:51200
	ds_read_b128 v[224:227], v218 offset:52224
	ds_read_b128 v[228:231], v218 offset:53248
	ds_read_b128 v[232:235], v218 offset:54272
	ds_read_b128 v[236:239], v218 offset:55296
	ds_read_b128 v[240:243], v218 offset:56320
	s_waitcnt vmcnt(8)
	s_waitcnt lgkmcnt(0)
	s_barrier
	s_setprio 1
	s_waitcnt lgkmcnt(0)
	v_mfma_f32_16x16x32_bf16 v[62:65], v[130:133], v[180:183], v[62:65]
	v_mfma_f32_16x16x32_bf16 v[58:61], v[138:141], v[180:183], v[58:61]
	v_mfma_f32_16x16x32_bf16 v[46:49], v[130:133], v[220:223], v[46:49]
	v_mfma_f32_16x16x32_bf16 v[42:45], v[138:141], v[220:223], v[42:45]
	v_mfma_f32_16x16x32_bf16 v[30:33], v[130:133], v[228:231], v[30:33]
	v_mfma_f32_16x16x32_bf16 v[26:29], v[138:141], v[228:231], v[26:29]
	v_mfma_f32_16x16x32_bf16 v[14:17], v[130:133], v[236:239], v[14:17]
	v_mfma_f32_16x16x32_bf16 v[10:13], v[138:141], v[236:239], v[10:13]
	v_mfma_f32_16x16x32_bf16 v[62:65], v[134:137], v[184:187], v[62:65]
	v_mfma_f32_16x16x32_bf16 v[58:61], v[142:145], v[184:187], v[58:61]
	v_mfma_f32_16x16x32_bf16 v[46:49], v[134:137], v[224:227], v[46:49]
	v_mfma_f32_16x16x32_bf16 v[42:45], v[142:145], v[224:227], v[42:45]
	v_mfma_f32_16x16x32_bf16 v[30:33], v[134:137], v[232:235], v[30:33]
	v_mfma_f32_16x16x32_bf16 v[26:29], v[142:145], v[232:235], v[26:29]
	v_mfma_f32_16x16x32_bf16 v[14:17], v[134:137], v[240:243], v[14:17]
	v_mfma_f32_16x16x32_bf16 v[10:13], v[142:145], v[240:243], v[10:13]
	s_setprio 0
	s_setprio 1
	v_mfma_f32_16x16x32_bf16 v[54:57], v[146:149], v[180:183], v[54:57]
	v_mfma_f32_16x16x32_bf16 v[50:53], v[154:157], v[180:183], v[50:53]
	v_mfma_f32_16x16x32_bf16 v[38:41], v[146:149], v[220:223], v[38:41]
	v_mfma_f32_16x16x32_bf16 v[34:37], v[154:157], v[220:223], v[34:37]
	v_mfma_f32_16x16x32_bf16 v[22:25], v[146:149], v[228:231], v[22:25]
	v_mfma_f32_16x16x32_bf16 v[18:21], v[154:157], v[228:231], v[18:21]
	v_mfma_f32_16x16x32_bf16 v[6:9], v[146:149], v[236:239], v[6:9]
	v_mfma_f32_16x16x32_bf16 v[2:5], v[154:157], v[236:239], v[2:5]
	v_mfma_f32_16x16x32_bf16 v[54:57], v[150:153], v[184:187], v[54:57]
	v_mfma_f32_16x16x32_bf16 v[50:53], v[158:161], v[184:187], v[50:53]
	v_mfma_f32_16x16x32_bf16 v[38:41], v[150:153], v[224:227], v[38:41]
	v_mfma_f32_16x16x32_bf16 v[34:37], v[158:161], v[224:227], v[34:37]
	v_mfma_f32_16x16x32_bf16 v[22:25], v[150:153], v[232:235], v[22:25]
	v_mfma_f32_16x16x32_bf16 v[18:21], v[158:161], v[232:235], v[18:21]
	v_mfma_f32_16x16x32_bf16 v[6:9], v[150:153], v[240:243], v[6:9]
	v_mfma_f32_16x16x32_bf16 v[2:5], v[158:161], v[240:243], v[2:5]
	s_setprio 0
	s_barrier
	s_add_i32 s26, s26, 2
	s_add_u32 s68, s68, 0x100
	s_addc_u32 s69, s69, 0
	s_add_u32 s75, s75, 0x100
	s_addc_u32 s83, s83, 0
	s_cmp_gt_u32 s26, 13
	s_cbranch_scc0 .LBB0_1487
	v_readlane_b32 s26, v255, 55
	v_readlane_b32 s27, v255, 56
	s_cmp_lg_u64 s[26:27], 0
	s_cselect_b32 s100, 1, 0
.LBB0_1490:
	s_cmp_lt_i32 s70, 64
	s_movk_i32 s5, 0x3000
	s_cselect_b32 s5, 0x1800, s5
	s_cmp_gt_i32 s70, 31
	s_cselect_b32 s5, s5, 0
	s_lshl_b32 s5, s5, 2
	v_readlane_b32 s26, v255, 27
	v_lshl_or_b32 v180, s74, 8, v217
	v_readlane_b32 s27, v255, 28
	s_add_u32 s26, s26, s5
	v_ashrrev_i32_e32 v181, 31, v180
	s_addc_u32 s27, s27, 0
	v_lshl_add_u64 v[142:143], v[180:181], 2, s[26:27]
	global_load_dwordx4 v[130:133], v[142:143], off
	v_readlane_b32 s26, v253, 22
	v_readlane_b32 s27, v253, 23
	s_andn2_b64 vcc, exec, s[26:27]
	v_lshlrev_b64 v[138:139], 2, v[180:181]
	v_cndmask_b32_e64 v134, 0, 1, s[26:27]
	v_readlane_b32 s26, v255, 21
	v_readlane_b32 s27, v255, 22
	v_readlane_b32 s36, v255, 52
	v_cmp_ne_u32_e64 s[68:69], 1, v134
	v_lshl_add_u64 v[140:141], s[26:27], 0, v[138:139]
	s_mov_b32 s17, s38
	v_readlane_b32 s37, v255, 53
	s_cmp_lg_u32 s100, 0
	s_cbranch_scc0 .Lal_6
	s_barrier
.Lal_6:
	s_cbranch_vccnz .LBB0_1504
	v_readlane_b32 s26, v255, 23
	v_readlane_b32 s27, v255, 24
	s_add_u32 s26, s26, s5
	s_addc_u32 s27, s27, 0
	v_lshl_add_u64 v[134:135], s[26:27], 0, v[138:139]
	global_load_dwordx4 v[134:137], v[134:135], off
	s_nop 0
	global_load_dwordx4 v[144:147], v[140:141], off
	s_waitcnt vmcnt(0)
	v_pk_add_f32 v[136:137], v[136:137], 1.0 op_sel_hi:[1,0]
	v_pk_add_f32 v[134:135], v[134:135], 1.0 op_sel_hi:[1,0]
	v_pk_mul_f32 v[136:137], v[146:147], v[136:137]
	v_pk_mul_f32 v[134:135], v[144:145], v[134:135]
	s_and_saveexec_b64 s[30:31], s[36:37]
	s_cbranch_execz .LBB0_1493

; #define LAS __attribute__((address_space(3)))
; __device__ __forceinline__ unsigned pk2(float lo, float hi) { const f32x2 v = {lo, hi}; const bf16x2_t b = __builtin_convertvector(v, bf16x2_t); return __builtin_bit_cast(unsigned, b); }
; #define PG8_BAR __builtin_amdgcn_s_barrier()
; template <class Epi>
; __device__ __forceinline__ void gemm_phase(LAS unsigned char* lds, const int tid, const Gemm g, const StaticOrder& S, const Epi& E) {
;     ...
;         if (wr == 0) PG8_BAR;
;     template <int NA, int NM> __device__ __forceinline__ void operator()(const f32x4 (&acc)[NA][2][NM][2], const pg8::Unit& u, int ro, int wr, int wc, int fr, int fq) const {
;         const int j = u.pm < 32 ? 0 : (u.pm < 64 ? 1 : 2);
;         const int colt = u.pn * 256 + wc * 32 + 8 * fq;
;         const LAS float* rsl = EpiCommon::rstd_slot(ssq, u, wr, wc, fr, fq);
;         f32x4 bv[2][2];
; #pragma unroll
;         for (int bj = 0; bj < 2; ++bj)
; #pragma unroll
;             for (int n = 0; n < 2; ++n) bv[bj][n] = *(const f32x4*)(bias + (size_t)j * NUP + colt + bj * 128 + 4 * n);
; #pragma unroll
;         for (int ai = 0; ai < NA; ++ai)
; #pragma unroll
;             for (int m = 0; m < NM; ++m) {
;                 const int row = u.pm * 256 + ro + ai * 128 + wr * 64 + m * 16 + fr;
;                 const float rs = rsl[ro + ai * 128 + m * 16];
; #pragma unroll
;                 for (int bj = 0; bj < 2; ++bj) {
;                     const f32x4 v0 = acc[ai][bj][m][0] * rs + bv[bj][0], v1 = acc[ai][bj][m][1] * rs + bv[bj][1];
;                     u32x4 w; w.x = pk2(v0.x, v0.y); w.y = pk2(v0.z, v0.w); w.z = pk2(v1.x, v1.y); w.w = pk2(v1.z, v1.w);
;                     *(u32x4*)(UV + (size_t)row * NUP + colt + bj * 128) = w;
;                 }
;             }
.LBB0_1915:
	s_cmp_lt_i32 s68, 64
	s_movk_i32 s7, 0x2c00
	s_cselect_b32 s5, 0x1600, s7
	s_cmp_gt_i32 s68, 31
	s_cselect_b32 s5, s5, 0
	s_lshl_b32 s5, s5, 2
	v_lshl_or_b32 v162, s64, 8, v159
	s_add_u32 s30, s16, s5
	s_addc_u32 s31, s26, 0
	v_ashrrev_i32_e32 v163, 31, v162
	v_lshl_add_u64 v[102:103], v[162:163], 2, s[30:31]
	global_load_dwordx4 v[106:109], v[102:103], off offset:16
	global_load_dwordx4 v[110:113], v[102:103], off
	global_load_dwordx4 v[98:101], v[102:103], off offset:528
	s_nop 0
	global_load_dwordx4 v[102:105], v[102:103], off offset:512
	v_lshl_add_u32 v174, s69, 10, v171
	ds_read2_b32 v[164:165], v174 offset1:16
	v_readlane_b32 s30, v254, 19
	s_lshl_b32 s5, s68, 8
	v_readlane_b32 s31, v254, 20
	v_add_u32_e32 v173, s5, v157
	s_andn2_b64 vcc, exec, s[62:63]
	s_waitcnt vmcnt(0) lgkmcnt(0)
	s_cmp_lg_u64 s[2:3], 0
	s_cbranch_scc0 .Lal_3
	s_barrier
.Lal_3:
	v_pk_fma_f32 v[138:139], v[138:139], v[164:165], v[106:107] op_sel_hi:[1,0,1]
	v_pk_fma_f32 v[144:145], v[144:145], v[164:165], v[112:113] op_sel_hi:[1,0,1]
	v_pk_fma_f32 v[142:143], v[142:143], v[164:165], v[110:111] op_sel_hi:[1,0,1]
	v_pk_fma_f32 v[140:141], v[140:141], v[164:165], v[108:109] op_sel_hi:[1,0,1]
	v_cvt_pk_bf16_f32 v142, v142, v143
	v_cvt_pk_bf16_f32 v143, v144, v145
	v_cvt_pk_bf16_f32 v144, v138, v139
	v_mov_b64_e32 v[138:139], s[30:31]
	v_cvt_pk_bf16_f32 v145, v140, v141
	v_mad_i64_i32 v[176:177], s[30:31], v173, s7, v[138:139]
	v_lshlrev_b64 v[140:141], 1, v[162:163]
	v_lshl_add_u64 v[162:163], v[176:177], 0, v[140:141]
	global_store_dwordx4 v[162:163], v[142:145], off
	v_pk_fma_f32 v[128:129], v[128:129], v[164:165], v[104:105] op_sel_hi:[1,0,1]
	v_pk_fma_f32 v[126:127], v[126:127], v[164:165], v[102:103] op_sel_hi:[1,0,1]
	v_pk_fma_f32 v[142:143], v[124:125], v[164:165], v[100:101] op_sel_hi:[1,0,1]
	v_pk_fma_f32 v[124:125], v[122:123], v[164:165], v[98:99] op_sel_hi:[1,0,1]
	v_cvt_pk_bf16_f32 v122, v126, v127
	v_cvt_pk_bf16_f32 v123, v128, v129
	v_cvt_pk_bf16_f32 v124, v124, v125
	v_cvt_pk_bf16_f32 v125, v142, v143
	v_add_u32_e32 v127, s5, v160
	v_mov_b32_e32 v126, v165
	global_store_dwordx4 v[162:163], v[122:125], off offset:256
	v_pk_fma_f32 v[128:129], v[132:133], v[126:127], v[108:109] op_sel_hi:[1,0,1]
	v_pk_fma_f32 v[130:131], v[130:131], v[126:127], v[106:107] op_sel_hi:[1,0,1]
	v_pk_fma_f32 v[124:125], v[136:137], v[126:127], v[112:113] op_sel_hi:[1,0,1]
	v_pk_fma_f32 v[122:123], v[134:135], v[126:127], v[110:111] op_sel_hi:[1,0,1]
	v_pk_fma_f32 v[120:121], v[120:121], v[126:127], v[104:105] op_sel_hi:[1,0,1]
	v_cvt_pk_bf16_f32 v122, v122, v123
	v_cvt_pk_bf16_f32 v123, v124, v125
	v_cvt_pk_bf16_f32 v125, v128, v129
	v_mad_i64_i32 v[128:129], s[30:31], v127, s7, v[138:139]
	v_cvt_pk_bf16_f32 v124, v130, v131
	v_lshl_add_u64 v[128:129], v[128:129], 0, v[140:141]
	global_store_dwordx4 v[128:129], v[122:125], off
	v_pk_fma_f32 v[118:119], v[118:119], v[126:127], v[102:103] op_sel_hi:[1,0,1]
	s_nop 0
	v_pk_fma_f32 v[122:123], v[116:117], v[126:127], v[100:101] op_sel_hi:[1,0,1]
	v_pk_fma_f32 v[116:117], v[114:115], v[126:127], v[98:99] op_sel_hi:[1,0,1]
	v_cvt_pk_bf16_f32 v114, v118, v119
	v_cvt_pk_bf16_f32 v115, v120, v121
	v_cvt_pk_bf16_f32 v116, v116, v117
	v_cvt_pk_bf16_f32 v117, v122, v123
	global_store_dwordx4 v[128:129], v[114:117], off offset:256
	ds_read2_b32 v[114:115], v174 offset0:32 offset1:48
	v_add_u32_e32 v118, s5, v161
	s_waitcnt lgkmcnt(0)
	v_pk_fma_f32 v[94:95], v[94:95], v[114:115], v[110:111] op_sel_hi:[1,0,1]
	v_pk_fma_f32 v[96:97], v[96:97], v[114:115], v[112:113] op_sel_hi:[1,0,1]
	v_pk_fma_f32 v[116:117], v[92:93], v[114:115], v[108:109] op_sel_hi:[1,0,1]
	v_pk_fma_f32 v[92:93], v[90:91], v[114:115], v[106:107] op_sel_hi:[1,0,1]
	v_cvt_pk_bf16_f32 v90, v94, v95
	v_mad_i64_i32 v[94:95], s[30:31], v118, s7, v[138:139]
	v_cvt_pk_bf16_f32 v91, v96, v97
	v_cvt_pk_bf16_f32 v92, v92, v93
	v_cvt_pk_bf16_f32 v93, v116, v117
	v_lshl_add_u64 v[94:95], v[94:95], 0, v[140:141]
	global_store_dwordx4 v[94:95], v[90:93], off
	v_pk_fma_f32 v[88:89], v[88:89], v[114:115], v[104:105] op_sel_hi:[1,0,1]
	v_pk_fma_f32 v[86:87], v[86:87], v[114:115], v[102:103] op_sel_hi:[1,0,1]
	v_pk_fma_f32 v[90:91], v[84:85], v[114:115], v[100:101] op_sel_hi:[1,0,1]
	v_pk_fma_f32 v[84:85], v[82:83], v[114:115], v[98:99] op_sel_hi:[1,0,1]
	v_cvt_pk_bf16_f32 v82, v86, v87
	v_cvt_pk_bf16_f32 v83, v88, v89
	v_cvt_pk_bf16_f32 v84, v84, v85
	v_cvt_pk_bf16_f32 v85, v90, v91
	global_store_dwordx4 v[94:95], v[82:85], off offset:256
	s_nop 1
	v_add_u32_e32 v83, s5, v170
	v_mov_b32_e32 v82, v115
	v_pk_fma_f32 v[78:79], v[78:79], v[82:83], v[110:111] op_sel_hi:[1,0,1]
	v_pk_fma_f32 v[80:81], v[80:81], v[82:83], v[112:113] op_sel_hi:[1,0,1]
	v_pk_fma_f32 v[84:85], v[76:77], v[82:83], v[108:109] op_sel_hi:[1,0,1]
	v_pk_fma_f32 v[76:77], v[74:75], v[82:83], v[106:107] op_sel_hi:[1,0,1]
	v_cvt_pk_bf16_f32 v74, v78, v79
	v_mad_i64_i32 v[78:79], s[30:31], v83, s7, v[138:139]
	v_cvt_pk_bf16_f32 v75, v80, v81
	v_cvt_pk_bf16_f32 v76, v76, v77
	v_cvt_pk_bf16_f32 v77, v84, v85
	v_lshl_add_u64 v[78:79], v[78:79], 0, v[140:141]
	global_store_dwordx4 v[78:79], v[74:77], off
	v_pk_fma_f32 v[72:73], v[72:73], v[82:83], v[104:105] op_sel_hi:[1,0,1]
	v_pk_fma_f32 v[70:71], v[70:71], v[82:83], v[102:103] op_sel_hi:[1,0,1]
	v_pk_fma_f32 v[74:75], v[68:69], v[82:83], v[100:101] op_sel_hi:[1,0,1]
	v_pk_fma_f32 v[68:69], v[66:67], v[82:83], v[98:99] op_sel_hi:[1,0,1]
	v_cvt_pk_bf16_f32 v66, v70, v71
	v_cvt_pk_bf16_f32 v67, v72, v73
	v_cvt_pk_bf16_f32 v68, v68, v69
	v_cvt_pk_bf16_f32 v69, v74, v75
	global_store_dwordx4 v[78:79], v[66:69], off offset:256
	ds_read2_b32 v[66:67], v174 offset0:128 offset1:144
	v_add_u32_e32 v70, 0x80, v173
	s_waitcnt lgkmcnt(0)
; __device__ __forceinline__ unsigned pk2(float lo, float hi) { const f32x2 v = {lo, hi}; const bf16x2_t b = __builtin_convertvector(v, bf16x2_t); return __builtin_bit_cast(unsigned, b); }
; #define PG8_BAR __builtin_amdgcn_s_barrier()
; template <class Epi>
; __device__ __forceinline__ void gemm_phase(LAS unsigned char* lds, const int tid, const Gemm g, const StaticOrder& S, const Epi& E) {
;     ...
;         if (!has_next) break;
; #pragma unroll
;         for (int a = 0; a < 2; ++a)
; #pragma unroll
;             for (int b = 0; b < 2; ++b)
; #pragma unroll
;                 for (int m = 0; m < 4; ++m)
; #pragma unroll
;                     for (int n = 0; n < 2; ++n) acc[a][b][m][n] = (f32x4){0.f, 0.f, 0.f, 0.f};
;         cur = nxt; cA = nA; cB = nB; ++ui;
;         if (wr == 1) PG8_BAR;
;     template <int NA, int NM> __device__ __forceinline__ void operator()(const f32x4 (&acc)[NA][2][NM][2], const pg8::Unit& u, int ro, int wr, int wc, int fr, int fq) const {
;     ...
;         for (int ai = 0; ai < NA; ++ai)
; #pragma unroll
;             for (int m = 0; m < NM; ++m) {
;                 const int row = u.pm * 256 + ro + ai * 128 + wr * 64 + m * 16 + fr;
;                 const float rs = rsl[ro + ai * 128 + m * 16];
; #pragma unroll
;                 for (int bj = 0; bj < 2; ++bj) {
;                     const f32x4 v0 = acc[ai][bj][m][0] * rs + bv[bj][0], v1 = acc[ai][bj][m][1] * rs + bv[bj][1];
;                     u32x4 w; w.x = pk2(v0.x, v0.y); w.y = pk2(v0.z, v0.w); w.z = pk2(v1.x, v1.y); w.w = pk2(v1.z, v1.w);
;                     *(u32x4*)(UV + (size_t)row * NUP + colt + bj * 128) = w;
;                 }
;             }
	v_pk_fma_f32 v[62:63], v[62:63], v[66:67], v[110:111] op_sel_hi:[1,0,1]
	v_pk_fma_f32 v[64:65], v[64:65], v[66:67], v[112:113] op_sel_hi:[1,0,1]
	v_pk_fma_f32 v[68:69], v[60:61], v[66:67], v[108:109] op_sel_hi:[1,0,1]
	v_pk_fma_f32 v[60:61], v[58:59], v[66:67], v[106:107] op_sel_hi:[1,0,1]
	v_cvt_pk_bf16_f32 v58, v62, v63
	v_mad_i64_i32 v[62:63], s[30:31], v70, s7, v[138:139]
	v_cvt_pk_bf16_f32 v59, v64, v65
	v_cvt_pk_bf16_f32 v60, v60, v61
	v_cvt_pk_bf16_f32 v61, v68, v69
	v_lshl_add_u64 v[62:63], v[62:63], 0, v[140:141]
	global_store_dwordx4 v[62:63], v[58:61], off
	v_pk_fma_f32 v[52:53], v[52:53], v[66:67], v[104:105] op_sel_hi:[1,0,1]
	v_pk_fma_f32 v[50:51], v[50:51], v[66:67], v[102:103] op_sel_hi:[1,0,1]
	v_pk_fma_f32 v[58:59], v[44:45], v[66:67], v[100:101] op_sel_hi:[1,0,1]
	v_pk_fma_f32 v[44:45], v[42:43], v[66:67], v[98:99] op_sel_hi:[1,0,1]
	v_cvt_pk_bf16_f32 v42, v50, v51
	v_cvt_pk_bf16_f32 v43, v52, v53
	v_cvt_pk_bf16_f32 v44, v44, v45
	v_cvt_pk_bf16_f32 v45, v58, v59
	v_add_u32_e32 v51, 0x90, v173
	v_mov_b32_e32 v50, v67
	global_store_dwordx4 v[62:63], v[42:45], off offset:256
	v_pk_fma_f32 v[46:47], v[46:47], v[50:51], v[106:107] op_sel_hi:[1,0,1]
	v_pk_fma_f32 v[48:49], v[48:49], v[50:51], v[108:109] op_sel_hi:[1,0,1]
	v_pk_fma_f32 v[44:45], v[56:57], v[50:51], v[112:113] op_sel_hi:[1,0,1]
	v_pk_fma_f32 v[42:43], v[54:55], v[50:51], v[110:111] op_sel_hi:[1,0,1]
	v_pk_fma_f32 v[40:41], v[40:41], v[50:51], v[104:105] op_sel_hi:[1,0,1]
	v_cvt_pk_bf16_f32 v42, v42, v43
	v_cvt_pk_bf16_f32 v43, v44, v45
	v_cvt_pk_bf16_f32 v44, v46, v47
	v_mad_i64_i32 v[46:47], s[30:31], v51, s7, v[138:139]
	v_cvt_pk_bf16_f32 v45, v48, v49
	v_lshl_add_u64 v[46:47], v[46:47], 0, v[140:141]
	global_store_dwordx4 v[46:47], v[42:45], off
	v_pk_fma_f32 v[38:39], v[38:39], v[50:51], v[102:103] op_sel_hi:[1,0,1]
	s_nop 0
	v_pk_fma_f32 v[42:43], v[36:37], v[50:51], v[100:101] op_sel_hi:[1,0,1]
	v_pk_fma_f32 v[36:37], v[34:35], v[50:51], v[98:99] op_sel_hi:[1,0,1]
	v_cvt_pk_bf16_f32 v34, v38, v39
	v_cvt_pk_bf16_f32 v35, v40, v41
	v_cvt_pk_bf16_f32 v36, v36, v37
	v_cvt_pk_bf16_f32 v37, v42, v43
	global_store_dwordx4 v[46:47], v[34:37], off offset:256
	ds_read2_b32 v[34:35], v174 offset0:160 offset1:176
	v_add_u32_e32 v38, 0xa0, v173
	s_waitcnt lgkmcnt(0)
	v_pk_fma_f32 v[30:31], v[30:31], v[34:35], v[110:111] op_sel_hi:[1,0,1]
	v_pk_fma_f32 v[32:33], v[32:33], v[34:35], v[112:113] op_sel_hi:[1,0,1]
	v_pk_fma_f32 v[36:37], v[28:29], v[34:35], v[108:109] op_sel_hi:[1,0,1]
	v_pk_fma_f32 v[28:29], v[26:27], v[34:35], v[106:107] op_sel_hi:[1,0,1]
	v_cvt_pk_bf16_f32 v26, v30, v31
	v_mad_i64_i32 v[30:31], s[30:31], v38, s7, v[138:139]
	v_cvt_pk_bf16_f32 v27, v32, v33
	v_cvt_pk_bf16_f32 v28, v28, v29
	v_cvt_pk_bf16_f32 v29, v36, v37
	v_lshl_add_u64 v[30:31], v[30:31], 0, v[140:141]
	global_store_dwordx4 v[30:31], v[26:29], off
	v_pk_fma_f32 v[20:21], v[20:21], v[34:35], v[104:105] op_sel_hi:[1,0,1]
	v_pk_fma_f32 v[18:19], v[18:19], v[34:35], v[102:103] op_sel_hi:[1,0,1]
	v_pk_fma_f32 v[26:27], v[12:13], v[34:35], v[100:101] op_sel_hi:[1,0,1]
	v_pk_fma_f32 v[12:13], v[10:11], v[34:35], v[98:99] op_sel_hi:[1,0,1]
	v_cvt_pk_bf16_f32 v10, v18, v19
	v_cvt_pk_bf16_f32 v11, v20, v21
	v_cvt_pk_bf16_f32 v12, v12, v13
	v_cvt_pk_bf16_f32 v13, v26, v27
	v_add_u32_e32 v19, 0xb0, v173
	v_mov_b32_e32 v18, v35
	global_store_dwordx4 v[30:31], v[10:13], off offset:256
	v_pk_fma_f32 v[14:15], v[14:15], v[18:19], v[106:107] op_sel_hi:[1,0,1]
	v_pk_fma_f32 v[16:17], v[16:17], v[18:19], v[108:109] op_sel_hi:[1,0,1]
	v_pk_fma_f32 v[12:13], v[24:25], v[18:19], v[112:113] op_sel_hi:[1,0,1]
	v_pk_fma_f32 v[10:11], v[22:23], v[18:19], v[110:111] op_sel_hi:[1,0,1]
	v_pk_fma_f32 v[8:9], v[8:9], v[18:19], v[104:105] op_sel_hi:[1,0,1]
	v_cvt_pk_bf16_f32 v10, v10, v11
	v_cvt_pk_bf16_f32 v11, v12, v13
	v_cvt_pk_bf16_f32 v12, v14, v15
	v_mad_i64_i32 v[14:15], s[30:31], v19, s7, v[138:139]
	v_cvt_pk_bf16_f32 v13, v16, v17
	v_lshl_add_u64 v[14:15], v[14:15], 0, v[140:141]
	global_store_dwordx4 v[14:15], v[10:13], off
	v_pk_fma_f32 v[6:7], v[6:7], v[18:19], v[102:103] op_sel_hi:[1,0,1]
	s_mov_b64 s[30:31], -1
	v_pk_fma_f32 v[10:11], v[4:5], v[18:19], v[100:101] op_sel_hi:[1,0,1]
	v_pk_fma_f32 v[4:5], v[2:3], v[18:19], v[98:99] op_sel_hi:[1,0,1]
	v_cvt_pk_bf16_f32 v2, v6, v7
	v_cvt_pk_bf16_f32 v3, v8, v9
	v_cvt_pk_bf16_f32 v4, v4, v5
	v_cvt_pk_bf16_f32 v5, v10, v11
	global_store_dwordx4 v[14:15], v[2:5], off offset:256
	s_cbranch_vccnz .LBB0_1904
	s_andn2_b64 vcc, exec, s[0:1]
	s_cbranch_vccnz .LBB0_1903
	s_barrier
	s_branch .LBB0_1903

; #define PG8_STAGE(bufoff, gbase, voff) do { _Pragma("unroll") for (int _i = 0; _i < 2; ++_i) \
;         __builtin_amdgcn_global_load_lds((const unsigned*)((const char*)(gbase) + (voff)[_i]), (LAS unsigned*)(lds + (bufoff) + ldsw + _i * 8192), 16, 0, 0); } while (0)
; #define PG8_LDA(dst, b, h) do { _Pragma("unroll") for (int m = 0; m < 4; ++m) _Pragma("unroll") for (int k = 0; k < 2; ++k) dst[m][k] = *(const LAS bf16x8*)(lds + PG8_SA(b, h) + aoff + m * 2048 + k * 1024); } while (0)
; #define PG8_LDB(dst, b, h) do { _Pragma("unroll") for (int n = 0; n < 2; ++n) _Pragma("unroll") for (int k = 0; k < 2; ++k) dst[n][k] = *(const LAS bf16x8*)(lds + PG8_SB(b, h) + boff + n * 2048 + k * 1024); } while (0)
; #define PG8_MMA(ai, bj, At, Bt) do { __builtin_amdgcn_s_setprio(1); _Pragma("unroll") for (int m = 0; m < 4; ++m) _Pragma("unroll") for (int n = 0; n < 2; ++n) _Pragma("unroll") for (int k = 0; k < 2; ++k) \
;         acc[ai][bj][m][n] = __builtin_amdgcn_mfma_f32_16x16x32_bf16(Bt[n][k], At[m][k], acc[ai][bj][m][n], 0, 0, 0); __builtin_amdgcn_s_setprio(0); } while (0)
; #define PG8_WAIT_V(n) asm volatile("s_waitcnt vmcnt(" #n ")" ::: "memory")
; #define PG8_WAIT_L(n) asm volatile("s_waitcnt lgkmcnt(" #n ")" ::: "memory")
; #define PG8_BAR __builtin_amdgcn_s_barrier()
; #define PG8_SCHED __builtin_amdgcn_sched_barrier(0)
; template <class Epi>
; __device__ __forceinline__ void gemm_phase(LAS unsigned char* lds, const int tid, const Gemm g, const StaticOrder& S, const Epi& E) {
;     ...
;             PG8_LDB(B0, 0, 0); PG8_LDB(B1, 0, 1); PG8_SCHED; PG8_LDA(At, 0, 0); PG8_STAGE(PG8_SA(1, 1), a1 + hstepA, voffA);
;             PG8_WAIT_V(8); PG8_WAIT_L(0); PG8_BAR; PG8_MMA(0, 0, At, B0); PG8_MMA(0, 1, At, B1); PG8_BAR; PG8_SCHED;
;             PG8_LDA(At, 0, 1); PG8_STAGE(PG8_SB(0, 0), b2, voffB); PG8_STAGE(PG8_SB(0, 1), b2 + hstepB, voffB); PG8_STAGE(PG8_SA(0, 0), a2, voffA);
;             PG8_WAIT_V(8); PG8_WAIT_L(0); PG8_BAR; PG8_MMA(1, 0, At, B0); PG8_MMA(1, 1, At, B1); PG8_BAR; PG8_SCHED;
.LBB0_2193:
	s_add_u32 s70, s30, 0x100
	s_addc_u32 s71, s31, 0
	s_add_i32 s76, 0, 0x10000
	s_cmp_eq_u32 vcc_hi, 40
	s_cselect_b32 s75, s1, s71
	s_cselect_b32 s74, s0, s70
	s_cselect_b32 s73, s69, vcc_lo
	s_cselect_b32 s72, s68, s28
	s_add_i32 s2, 0, 0x14000
	v_add_u32_e32 v154, s76, v179
	v_add_u32_e32 v162, s2, v179
	ds_read_b128 v[130:133], v154
	ds_read_b128 v[134:137], v154 offset:1024
	ds_read_b128 v[138:141], v154 offset:2048
	ds_read_b128 v[154:157], v154 offset:3072
	ds_read_b128 v[158:161], v162
	ds_read_b128 v[170:173], v162 offset:1024
	ds_read_b128 v[174:177], v162 offset:2048
	ds_read_b128 v[184:187], v162 offset:3072
	v_lshl_add_u64 v[162:163], s[30:31], 0, v[150:151]
	s_add_i32 m0, s5, 0xc000
	s_nop 0
	global_load_lds_dwordx4 v[162:163], off
	v_lshl_add_u64 v[162:163], s[30:31], 0, v[152:153]
	s_add_i32 m0, s5, 0xe000
	s_nop 0
	global_load_lds_dwordx4 v[162:163], off
	ds_read_b128 v[188:191], v181
	ds_read_b128 v[192:195], v181 offset:1024
	ds_read_b128 v[196:199], v181 offset:2048
	ds_read_b128 v[200:203], v181 offset:3072
	ds_read_b128 v[212:215], v181 offset:4096
	ds_read_b128 v[216:219], v181 offset:5120
	ds_read_b128 v[220:223], v181 offset:6144
	ds_read_b128 v[224:227], v181 offset:7168
	s_waitcnt vmcnt(8)
	s_waitcnt lgkmcnt(0)
	s_barrier
	s_setprio 1
	s_waitcnt lgkmcnt(0)
	v_mfma_f32_16x16x32_bf16 v[126:129], v[130:133], v[188:191], v[126:129]
	v_mfma_f32_16x16x32_bf16 v[122:125], v[138:141], v[188:191], v[122:125]
	v_mfma_f32_16x16x32_bf16 v[110:113], v[130:133], v[196:199], v[110:113]
	v_mfma_f32_16x16x32_bf16 v[106:109], v[138:141], v[196:199], v[106:109]
	v_mfma_f32_16x16x32_bf16 v[94:97], v[130:133], v[212:215], v[94:97]
	v_mfma_f32_16x16x32_bf16 v[90:93], v[138:141], v[212:215], v[90:93]
	v_mfma_f32_16x16x32_bf16 v[78:81], v[130:133], v[220:223], v[78:81]
	v_mfma_f32_16x16x32_bf16 v[74:77], v[138:141], v[220:223], v[74:77]
	v_mfma_f32_16x16x32_bf16 v[126:129], v[134:137], v[192:195], v[126:129]
	v_mfma_f32_16x16x32_bf16 v[122:125], v[154:157], v[192:195], v[122:125]
	v_mfma_f32_16x16x32_bf16 v[110:113], v[134:137], v[200:203], v[110:113]
	v_mfma_f32_16x16x32_bf16 v[106:109], v[154:157], v[200:203], v[106:109]
	v_mfma_f32_16x16x32_bf16 v[94:97], v[134:137], v[216:219], v[94:97]
	v_mfma_f32_16x16x32_bf16 v[90:93], v[154:157], v[216:219], v[90:93]
	v_mfma_f32_16x16x32_bf16 v[78:81], v[134:137], v[224:227], v[78:81]
	v_mfma_f32_16x16x32_bf16 v[74:77], v[154:157], v[224:227], v[74:77]
	s_setprio 0
	s_setprio 1
	v_mfma_f32_16x16x32_bf16 v[118:121], v[158:161], v[188:191], v[118:121]
	v_mfma_f32_16x16x32_bf16 v[114:117], v[174:177], v[188:191], v[114:117]
	v_mfma_f32_16x16x32_bf16 v[102:105], v[158:161], v[196:199], v[102:105]
	v_mfma_f32_16x16x32_bf16 v[98:101], v[174:177], v[196:199], v[98:101]
	v_mfma_f32_16x16x32_bf16 v[86:89], v[158:161], v[212:215], v[86:89]
	v_mfma_f32_16x16x32_bf16 v[82:85], v[174:177], v[212:215], v[82:85]
	v_mfma_f32_16x16x32_bf16 v[70:73], v[158:161], v[220:223], v[70:73]
	v_mfma_f32_16x16x32_bf16 v[66:69], v[174:177], v[220:223], v[66:69]
	v_mfma_f32_16x16x32_bf16 v[118:121], v[170:173], v[192:195], v[118:121]
	v_mfma_f32_16x16x32_bf16 v[114:117], v[184:187], v[192:195], v[114:117]
	v_mfma_f32_16x16x32_bf16 v[102:105], v[170:173], v[200:203], v[102:105]
	v_mfma_f32_16x16x32_bf16 v[98:101], v[184:187], v[200:203], v[98:101]
	v_mfma_f32_16x16x32_bf16 v[86:89], v[170:173], v[216:219], v[86:89]
	v_mfma_f32_16x16x32_bf16 v[82:85], v[184:187], v[216:219], v[82:85]
	v_mfma_f32_16x16x32_bf16 v[70:73], v[170:173], v[224:227], v[70:73]
	v_mfma_f32_16x16x32_bf16 v[66:69], v[184:187], v[224:227], v[66:69]
	s_setprio 0
	s_barrier
	s_add_i32 s3, s76, s4
	v_lshl_add_u64 v[162:163], s[72:73], 0, v[0:1]
	s_mov_b32 m0, s3
	s_nop 0
	global_load_lds_dwordx4 v[162:163], off
	s_add_i32 m0, s3, 0x2000
	s_add_u32 s30, s72, 0xb0000
	v_lshl_add_u64 v[164:165], s[72:73], 0, v[148:149]
	s_addc_u32 s31, s73, 0
	s_add_i32 s2, s2, s4
	global_load_lds_dwordx4 v[164:165], off
	v_lshl_add_u64 v[206:207], s[30:31], 0, v[0:1]
	s_mov_b32 m0, s2
	v_lshl_add_u64 v[228:229], s[74:75], 0, v[144:145]
	global_load_lds_dwordx4 v[206:207], off
	v_lshl_add_u64 v[206:207], s[30:31], 0, v[148:149]
	s_add_i32 m0, s2, 0x2000
	s_nop 0
	global_load_lds_dwordx4 v[206:207], off
	v_lshl_add_u64 v[206:207], s[74:75], 0, v[142:143]
	s_mov_b32 m0, s5
	s_nop 0
	global_load_lds_dwordx4 v[206:207], off
	s_mov_b32 m0, s6
	s_nop 0
	global_load_lds_dwordx4 v[228:229], off
	ds_read_b128 v[188:191], v181 offset:16384
	ds_read_b128 v[192:195], v181 offset:17408
	ds_read_b128 v[196:199], v181 offset:18432
	ds_read_b128 v[200:203], v181 offset:19456
	ds_read_b128 v[212:215], v181 offset:20480
	ds_read_b128 v[216:219], v181 offset:21504
	ds_read_b128 v[220:223], v181 offset:22528
	ds_read_b128 v[224:227], v181 offset:23552
	s_waitcnt vmcnt(8)
	s_waitcnt lgkmcnt(0)
	s_barrier
; #define PG8_STAGE(bufoff, gbase, voff) do { _Pragma("unroll") for (int _i = 0; _i < 2; ++_i) \
;         __builtin_amdgcn_global_load_lds((const unsigned*)((const char*)(gbase) + (voff)[_i]), (LAS unsigned*)(lds + (bufoff) + ldsw + _i * 8192), 16, 0, 0); } while (0)
; #define PG8_LDA(dst, b, h) do { _Pragma("unroll") for (int m = 0; m < 4; ++m) _Pragma("unroll") for (int k = 0; k < 2; ++k) dst[m][k] = *(const LAS bf16x8*)(lds + PG8_SA(b, h) + aoff + m * 2048 + k * 1024); } while (0)
; #define PG8_LDB(dst, b, h) do { _Pragma("unroll") for (int n = 0; n < 2; ++n) _Pragma("unroll") for (int k = 0; k < 2; ++k) dst[n][k] = *(const LAS bf16x8*)(lds + PG8_SB(b, h) + boff + n * 2048 + k * 1024); } while (0)
; #define PG8_MMA(ai, bj, At, Bt) do { __builtin_amdgcn_s_setprio(1); _Pragma("unroll") for (int m = 0; m < 4; ++m) _Pragma("unroll") for (int n = 0; n < 2; ++n) _Pragma("unroll") for (int k = 0; k < 2; ++k) \
;         acc[ai][bj][m][n] = __builtin_amdgcn_mfma_f32_16x16x32_bf16(Bt[n][k], At[m][k], acc[ai][bj][m][n], 0, 0, 0); __builtin_amdgcn_s_setprio(0); } while (0)
; #define PG8_WAIT_V(n) asm volatile("s_waitcnt vmcnt(" #n ")" ::: "memory")
; #define PG8_WAIT_L(n) asm volatile("s_waitcnt lgkmcnt(" #n ")" ::: "memory")
; #define PG8_BAR __builtin_amdgcn_s_barrier()
; #define PG8_SCHED __builtin_amdgcn_sched_barrier(0)
; template <class Epi>
; __device__ __forceinline__ void gemm_phase(LAS unsigned char* lds, const int tid, const Gemm g, const StaticOrder& S, const Epi& E) {
;     ...
;             PG8_WAIT_V(8); PG8_WAIT_L(0); PG8_BAR; PG8_MMA(1, 0, At, B0); PG8_MMA(1, 1, At, B1); PG8_BAR; PG8_SCHED;
;             PG8_LDB(B0, 1, 0); PG8_LDB(B1, 1, 1); PG8_SCHED; PG8_LDA(At, 1, 0); PG8_STAGE(PG8_SA(0, 1), a2 + hstepA, voffA);
;             PG8_WAIT_V(8); PG8_WAIT_L(0); PG8_BAR; PG8_MMA(0, 0, At, B0); PG8_MMA(0, 1, At, B1); PG8_BAR; PG8_SCHED;
	s_setprio 1
	s_waitcnt lgkmcnt(0)
	v_mfma_f32_16x16x32_bf16 v[62:65], v[130:133], v[188:191], v[62:65]
	v_mfma_f32_16x16x32_bf16 v[58:61], v[138:141], v[188:191], v[58:61]
	v_mfma_f32_16x16x32_bf16 v[46:49], v[130:133], v[196:199], v[46:49]
	v_mfma_f32_16x16x32_bf16 v[42:45], v[138:141], v[196:199], v[42:45]
	v_mfma_f32_16x16x32_bf16 v[30:33], v[130:133], v[212:215], v[30:33]
	v_mfma_f32_16x16x32_bf16 v[26:29], v[138:141], v[212:215], v[26:29]
	v_mfma_f32_16x16x32_bf16 v[14:17], v[130:133], v[220:223], v[14:17]
	v_mfma_f32_16x16x32_bf16 v[10:13], v[138:141], v[220:223], v[10:13]
	v_mfma_f32_16x16x32_bf16 v[62:65], v[134:137], v[192:195], v[62:65]
	v_mfma_f32_16x16x32_bf16 v[58:61], v[154:157], v[192:195], v[58:61]
	v_mfma_f32_16x16x32_bf16 v[46:49], v[134:137], v[200:203], v[46:49]
	v_mfma_f32_16x16x32_bf16 v[42:45], v[154:157], v[200:203], v[42:45]
	v_mfma_f32_16x16x32_bf16 v[30:33], v[134:137], v[216:219], v[30:33]
	v_mfma_f32_16x16x32_bf16 v[26:29], v[154:157], v[216:219], v[26:29]
	v_mfma_f32_16x16x32_bf16 v[14:17], v[134:137], v[224:227], v[14:17]
	v_mfma_f32_16x16x32_bf16 v[10:13], v[154:157], v[224:227], v[10:13]
	s_setprio 0
	s_setprio 1
	v_mfma_f32_16x16x32_bf16 v[54:57], v[158:161], v[188:191], v[54:57]
	v_mfma_f32_16x16x32_bf16 v[50:53], v[174:177], v[188:191], v[50:53]
	v_mfma_f32_16x16x32_bf16 v[38:41], v[158:161], v[196:199], v[38:41]
	v_mfma_f32_16x16x32_bf16 v[34:37], v[174:177], v[196:199], v[34:37]
	v_mfma_f32_16x16x32_bf16 v[22:25], v[158:161], v[212:215], v[22:25]
	v_mfma_f32_16x16x32_bf16 v[18:21], v[174:177], v[212:215], v[18:21]
	v_mfma_f32_16x16x32_bf16 v[6:9], v[158:161], v[220:223], v[6:9]
	v_mfma_f32_16x16x32_bf16 v[2:5], v[174:177], v[220:223], v[2:5]
	v_mfma_f32_16x16x32_bf16 v[54:57], v[170:173], v[192:195], v[54:57]
	v_mfma_f32_16x16x32_bf16 v[50:53], v[184:187], v[192:195], v[50:53]
	v_mfma_f32_16x16x32_bf16 v[38:41], v[170:173], v[200:203], v[38:41]
	v_mfma_f32_16x16x32_bf16 v[34:37], v[184:187], v[200:203], v[34:37]
	v_mfma_f32_16x16x32_bf16 v[22:25], v[170:173], v[216:219], v[22:25]
	v_mfma_f32_16x16x32_bf16 v[18:21], v[184:187], v[216:219], v[18:21]
	v_mfma_f32_16x16x32_bf16 v[6:9], v[170:173], v[224:227], v[6:9]
	v_mfma_f32_16x16x32_bf16 v[2:5], v[184:187], v[224:227], v[2:5]
	s_setprio 0
	s_barrier
	s_add_i32 s2, 0, 0x18000
	s_add_i32 s3, 0, 0x1c000
	v_add_u32_e32 v154, s2, v179
	v_add_u32_e32 v183, s3, v179
	ds_read_b128 v[130:133], v154
	ds_read_b128 v[134:137], v154 offset:1024
	ds_read_b128 v[138:141], v154 offset:2048
	ds_read_b128 v[154:157], v154 offset:3072
	ds_read_b128 v[158:161], v183
	ds_read_b128 v[170:173], v183 offset:1024
	ds_read_b128 v[174:177], v183 offset:2048
	ds_read_b128 v[184:187], v183 offset:3072
	s_add_u32 s30, s74, 0x160000
	s_addc_u32 s31, s75, 0
	s_mov_b32 m0, s7
	v_lshl_add_u64 v[230:231], s[30:31], 0, v[142:143]
	global_load_lds_dwordx4 v[230:231], off
	v_lshl_add_u64 v[230:231], s[30:31], 0, v[144:145]
	s_mov_b32 m0, s77
	s_nop 0
	global_load_lds_dwordx4 v[230:231], off
	ds_read_b128 v[188:191], v181 offset:32768
	ds_read_b128 v[192:195], v181 offset:33792
	ds_read_b128 v[196:199], v181 offset:34816
	ds_read_b128 v[200:203], v181 offset:35840
	ds_read_b128 v[212:215], v181 offset:36864
	ds_read_b128 v[216:219], v181 offset:37888
	ds_read_b128 v[220:223], v181 offset:38912
	ds_read_b128 v[224:227], v181 offset:39936
	s_waitcnt vmcnt(8)
	s_waitcnt lgkmcnt(0)
	s_barrier
	s_setprio 1
	s_waitcnt lgkmcnt(0)
	v_mfma_f32_16x16x32_bf16 v[126:129], v[130:133], v[188:191], v[126:129]
	v_mfma_f32_16x16x32_bf16 v[122:125], v[138:141], v[188:191], v[122:125]
	v_mfma_f32_16x16x32_bf16 v[110:113], v[130:133], v[196:199], v[110:113]
	v_mfma_f32_16x16x32_bf16 v[106:109], v[138:141], v[196:199], v[106:109]
	v_mfma_f32_16x16x32_bf16 v[94:97], v[130:133], v[212:215], v[94:97]
	v_mfma_f32_16x16x32_bf16 v[90:93], v[138:141], v[212:215], v[90:93]
	v_mfma_f32_16x16x32_bf16 v[78:81], v[130:133], v[220:223], v[78:81]
	v_mfma_f32_16x16x32_bf16 v[74:77], v[138:141], v[220:223], v[74:77]
	v_mfma_f32_16x16x32_bf16 v[126:129], v[134:137], v[192:195], v[126:129]
	v_mfma_f32_16x16x32_bf16 v[122:125], v[154:157], v[192:195], v[122:125]
	v_mfma_f32_16x16x32_bf16 v[110:113], v[134:137], v[200:203], v[110:113]
	v_mfma_f32_16x16x32_bf16 v[106:109], v[154:157], v[200:203], v[106:109]
	v_mfma_f32_16x16x32_bf16 v[94:97], v[134:137], v[216:219], v[94:97]
	v_mfma_f32_16x16x32_bf16 v[90:93], v[154:157], v[216:219], v[90:93]
	v_mfma_f32_16x16x32_bf16 v[78:81], v[134:137], v[224:227], v[78:81]
	v_mfma_f32_16x16x32_bf16 v[74:77], v[154:157], v[224:227], v[74:77]
	s_setprio 0
	s_setprio 1
	v_mfma_f32_16x16x32_bf16 v[118:121], v[158:161], v[188:191], v[118:121]
	v_mfma_f32_16x16x32_bf16 v[114:117], v[174:177], v[188:191], v[114:117]
	v_mfma_f32_16x16x32_bf16 v[102:105], v[158:161], v[196:199], v[102:105]
	v_mfma_f32_16x16x32_bf16 v[98:101], v[174:177], v[196:199], v[98:101]
	v_mfma_f32_16x16x32_bf16 v[86:89], v[158:161], v[212:215], v[86:89]
	v_mfma_f32_16x16x32_bf16 v[82:85], v[174:177], v[212:215], v[82:85]
	v_mfma_f32_16x16x32_bf16 v[70:73], v[158:161], v[220:223], v[70:73]
	v_mfma_f32_16x16x32_bf16 v[66:69], v[174:177], v[220:223], v[66:69]
	v_mfma_f32_16x16x32_bf16 v[118:121], v[170:173], v[192:195], v[118:121]
	v_mfma_f32_16x16x32_bf16 v[114:117], v[184:187], v[192:195], v[114:117]
	v_mfma_f32_16x16x32_bf16 v[102:105], v[170:173], v[200:203], v[102:105]
	v_mfma_f32_16x16x32_bf16 v[98:101], v[184:187], v[200:203], v[98:101]
	v_mfma_f32_16x16x32_bf16 v[86:89], v[170:173], v[216:219], v[86:89]
	v_mfma_f32_16x16x32_bf16 v[82:85], v[184:187], v[216:219], v[82:85]
	v_mfma_f32_16x16x32_bf16 v[70:73], v[170:173], v[224:227], v[70:73]
	v_mfma_f32_16x16x32_bf16 v[66:69], v[184:187], v[224:227], v[66:69]
	s_setprio 0
	s_barrier
; #define PG8_STAGE(bufoff, gbase, voff) do { _Pragma("unroll") for (int _i = 0; _i < 2; ++_i) \
;         __builtin_amdgcn_global_load_lds((const unsigned*)((const char*)(gbase) + (voff)[_i]), (LAS unsigned*)(lds + (bufoff) + ldsw + _i * 8192), 16, 0, 0); } while (0)
; #define PG8_LDA(dst, b, h) do { _Pragma("unroll") for (int m = 0; m < 4; ++m) _Pragma("unroll") for (int k = 0; k < 2; ++k) dst[m][k] = *(const LAS bf16x8*)(lds + PG8_SA(b, h) + aoff + m * 2048 + k * 1024); } while (0)
; #define PG8_MMA(ai, bj, At, Bt) do { __builtin_amdgcn_s_setprio(1); _Pragma("unroll") for (int m = 0; m < 4; ++m) _Pragma("unroll") for (int n = 0; n < 2; ++n) _Pragma("unroll") for (int k = 0; k < 2; ++k) \
;         acc[ai][bj][m][n] = __builtin_amdgcn_mfma_f32_16x16x32_bf16(Bt[n][k], At[m][k], acc[ai][bj][m][n], 0, 0, 0); __builtin_amdgcn_s_setprio(0); } while (0)
; #define PG8_WAIT_V(n) asm volatile("s_waitcnt vmcnt(" #n ")" ::: "memory")
; #define PG8_WAIT_L(n) asm volatile("s_waitcnt lgkmcnt(" #n ")" ::: "memory")
; #define PG8_BAR __builtin_amdgcn_s_barrier()
; #define PG8_SCHED __builtin_amdgcn_sched_barrier(0)
; template <class Epi>
; __device__ __forceinline__ void gemm_phase(LAS unsigned char* lds, const int tid, const Gemm g, const StaticOrder& S, const Epi& E) {
;     ...
;             PG8_LDA(At, 1, 1); PG8_STAGE(PG8_SB(1, 0), b3, voffB); PG8_STAGE(PG8_SB(1, 1), b3 + hstepB, voffB); PG8_STAGE(PG8_SA(1, 0), a3, voffA);
;             PG8_WAIT_V(8); PG8_WAIT_L(0); PG8_BAR; PG8_MMA(1, 0, At, B0); PG8_MMA(1, 1, At, B1); PG8_BAR; PG8_SCHED;
	s_add_i32 s2, s2, s4
	v_lshl_add_u64 v[162:163], v[162:163], 0, s[36:37]
	s_mov_b32 m0, s2
	s_nop 0
	global_load_lds_dwordx4 v[162:163], off
	s_add_i32 m0, s2, 0x2000
	s_add_u32 s30, s72, 0xb0080
	v_lshl_add_u64 v[162:163], v[164:165], 0, s[36:37]
	s_addc_u32 s31, s73, 0
	s_add_i32 s2, s3, s4
	global_load_lds_dwordx4 v[162:163], off
	v_lshl_add_u64 v[162:163], s[30:31], 0, v[0:1]
	s_mov_b32 m0, s2
	s_nop 0
	global_load_lds_dwordx4 v[162:163], off
	v_lshl_add_u64 v[162:163], s[30:31], 0, v[148:149]
	s_add_i32 m0, s2, 0x2000
	s_nop 0
	global_load_lds_dwordx4 v[162:163], off
	v_lshl_add_u64 v[162:163], v[206:207], 0, s[36:37]
	s_mov_b32 m0, s83
	s_nop 0
	global_load_lds_dwordx4 v[162:163], off
	v_lshl_add_u64 v[162:163], v[228:229], 0, s[36:37]
	s_mov_b32 m0, s88
	s_nop 0
	global_load_lds_dwordx4 v[162:163], off
	ds_read_b128 v[188:191], v181 offset:49152
	ds_read_b128 v[192:195], v181 offset:50176
	ds_read_b128 v[196:199], v181 offset:51200
	ds_read_b128 v[200:203], v181 offset:52224
	ds_read_b128 v[212:215], v181 offset:53248
	ds_read_b128 v[216:219], v181 offset:54272
	ds_read_b128 v[220:223], v181 offset:55296
	ds_read_b128 v[224:227], v181 offset:56320
	s_waitcnt vmcnt(8)
	s_waitcnt lgkmcnt(0)
	s_barrier
	s_setprio 1
	s_waitcnt lgkmcnt(0)
	v_mfma_f32_16x16x32_bf16 v[62:65], v[130:133], v[188:191], v[62:65]
	v_mfma_f32_16x16x32_bf16 v[58:61], v[138:141], v[188:191], v[58:61]
	v_mfma_f32_16x16x32_bf16 v[46:49], v[130:133], v[196:199], v[46:49]
	v_mfma_f32_16x16x32_bf16 v[42:45], v[138:141], v[196:199], v[42:45]
	v_mfma_f32_16x16x32_bf16 v[30:33], v[130:133], v[212:215], v[30:33]
	v_mfma_f32_16x16x32_bf16 v[26:29], v[138:141], v[212:215], v[26:29]
	v_mfma_f32_16x16x32_bf16 v[14:17], v[130:133], v[220:223], v[14:17]
	v_mfma_f32_16x16x32_bf16 v[10:13], v[138:141], v[220:223], v[10:13]
	v_mfma_f32_16x16x32_bf16 v[62:65], v[134:137], v[192:195], v[62:65]
	v_mfma_f32_16x16x32_bf16 v[58:61], v[154:157], v[192:195], v[58:61]
	v_mfma_f32_16x16x32_bf16 v[46:49], v[134:137], v[200:203], v[46:49]
	v_mfma_f32_16x16x32_bf16 v[42:45], v[154:157], v[200:203], v[42:45]
	v_mfma_f32_16x16x32_bf16 v[30:33], v[134:137], v[216:219], v[30:33]
	v_mfma_f32_16x16x32_bf16 v[26:29], v[154:157], v[216:219], v[26:29]
	v_mfma_f32_16x16x32_bf16 v[14:17], v[134:137], v[224:227], v[14:17]
	v_mfma_f32_16x16x32_bf16 v[10:13], v[154:157], v[224:227], v[10:13]
	s_setprio 0
	s_setprio 1
	v_mfma_f32_16x16x32_bf16 v[54:57], v[158:161], v[188:191], v[54:57]
	v_mfma_f32_16x16x32_bf16 v[50:53], v[174:177], v[188:191], v[50:53]
	v_mfma_f32_16x16x32_bf16 v[38:41], v[158:161], v[196:199], v[38:41]
	v_mfma_f32_16x16x32_bf16 v[34:37], v[174:177], v[196:199], v[34:37]
	v_mfma_f32_16x16x32_bf16 v[22:25], v[158:161], v[212:215], v[22:25]
	v_mfma_f32_16x16x32_bf16 v[18:21], v[174:177], v[212:215], v[18:21]
	v_mfma_f32_16x16x32_bf16 v[6:9], v[158:161], v[220:223], v[6:9]
	v_mfma_f32_16x16x32_bf16 v[2:5], v[174:177], v[220:223], v[2:5]
	v_mfma_f32_16x16x32_bf16 v[54:57], v[170:173], v[192:195], v[54:57]
	v_mfma_f32_16x16x32_bf16 v[50:53], v[184:187], v[192:195], v[50:53]
	v_mfma_f32_16x16x32_bf16 v[38:41], v[170:173], v[200:203], v[38:41]
	v_mfma_f32_16x16x32_bf16 v[34:37], v[184:187], v[200:203], v[34:37]
	v_mfma_f32_16x16x32_bf16 v[22:25], v[170:173], v[216:219], v[22:25]
	v_mfma_f32_16x16x32_bf16 v[18:21], v[184:187], v[216:219], v[18:21]
	v_mfma_f32_16x16x32_bf16 v[6:9], v[170:173], v[224:227], v[6:9]
	v_mfma_f32_16x16x32_bf16 v[2:5], v[184:187], v[224:227], v[2:5]
	s_setprio 0
	s_barrier
	s_add_i32 vcc_hi, vcc_hi, 2
	s_add_u32 s28, s28, 0x100
	s_addc_u32 vcc_lo, vcc_lo, 0
	s_cmp_gt_u32 vcc_hi, 41
	s_mov_b64 s[30:31], s[70:71]
	s_cbranch_scc0 .LBB0_2193
; #define LAS __attribute__((address_space(3)))
; #define PG8_BAR __builtin_amdgcn_s_barrier()
; template <class Epi>
; __device__ __forceinline__ void gemm_phase(LAS unsigned char* lds, const int tid, const Gemm g, const StaticOrder& S, const Epi& E) {
;     ...
;         if (wr == 0) PG8_BAR;
;     template <int NA, int NM> __device__ __forceinline__ void operator()(const f32x4 (&acc)[NA][2][NM][2], const pg8::Unit& u, int ro, int wr, int wc, int fr, int fq) const {
;         const int j = u.pm < 32 ? 0 : (u.pm < 64 ? 1 : 2);
;         const int colt = u.pn * 256 + wc * 32 + 8 * fq;
;         LAS f32x4* cs = (LAS f32x4*)((LAS unsigned char*)0 + pg8::STAGE_BYTES) + ((wr * 4 + wc) * 4 + fq) * 8;
; #pragma unroll
;         for (int bj = 0; bj < 2; ++bj)
; #pragma unroll
;             for (int n = 0; n < 2; ++n) {
;                 const f32x4 gvv = *(const f32x4*)(gate + (size_t)j * NMOD + colt + bj * 128 + 4 * n);
;                 f32x4 svv = (f32x4){0.f, 0.f, 0.f, 0.f};
;                 if (nw) svv = *(const f32x4*)(nw + colt + bj * 128 + 4 * n) * (*(const f32x4*)(nsc + (size_t)j * NMOD + colt + bj * 128 + 4 * n) + 1.0f);
;                 if (fr == 0) { cs[bj * 2 + n] = gvv; cs[4 + bj * 2 + n] = svv; }
;             }
; #pragma unroll
;         for (int ai = 0; ai < NA; ++ai)
; #pragma unroll
;             for (int mp = 0; mp < NM; mp += 2) {
;                 constexpr int MB = NM < 2 ? NM : 2;
;                 f32x4 xv[MB][2][2];
; #pragma unroll
;                 for (int mi = 0; mi < MB; ++mi) {
;                     const int row = u.pm * 256 + ro + ai * 128 + wr * 64 + (mp + mi) * 16 + fr;
;                     if (slat) {
;                         const float* xs = (row < ML ? slat + (size_t)row * D : sctx + (size_t)(row - ML) * D) + colt;
; #pragma unroll
;                         for (int bj = 0; bj < 2; ++bj) { xv[mi][bj][0] = *(const f32x4*)(xs + bj * 128); xv[mi][bj][1] = *(const f32x4*)(xs + bj * 128 + 4); }
;                     } else {
; #pragma unroll
;                         for (int bj = 0; bj < 2; ++bj) { const u32x4 xw = *(const u32x4*)(xr + (size_t)row * D + colt + bj * 128);
;                             const f32x2 h0 = unpkh2(xw.x), h1 = unpkh2(xw.y), h2 = unpkh2(xw.z), h3 = unpkh2(xw.w);
;                             xv[mi][bj][0] = (f32x4){h0.x, h0.y, h1.x, h1.y}; xv[mi][bj][1] = (f32x4){h2.x, h2.y, h3.x, h3.y}; }
.LBB0_2196:
	v_lshl_or_b32 v154, s42, 8, v180
	v_ashrrev_i32_e32 v155, 31, v154
	s_and_saveexec_b64 s[70:71], s[62:63]
	s_cbranch_execz .LBB0_2198
	s_cmp_lt_i32 s11, 64
	s_movk_i32 s2, 0x3000
	s_cselect_b32 s2, 0x1800, s2
	s_cmp_gt_i32 s11, 31
	s_cselect_b32 s2, s2, 0
	s_lshl_b32 s2, s2, 2
	s_add_u32 s30, s8, s2
	s_addc_u32 s31, s9, 0
	v_lshl_add_u64 v[138:139], v[154:155], 2, s[30:31]
	global_load_dwordx4 v[130:133], v[138:139], off offset:16
	global_load_dwordx4 v[134:137], v[138:139], off
	s_mov_b32 s30, s29
	s_mov_b32 s31, s29
	s_mov_b32 s28, s29
	v_mov_b64_e32 v[158:159], s[30:31]
	v_mov_b64_e32 v[156:157], s[28:29]
	s_waitcnt vmcnt(0)
	ds_write_b128 v182, v[134:137]
	ds_write_b128 v182, v[156:159] offset:64
	ds_write_b128 v182, v[130:133] offset:16
	ds_write_b128 v182, v[156:159] offset:80
	global_load_dwordx4 v[130:133], v[138:139], off offset:528
	global_load_dwordx4 v[134:137], v[138:139], off offset:512
	s_waitcnt vmcnt(0)
	ds_write_b128 v182, v[134:137] offset:32
	ds_write_b128 v182, v[156:159] offset:96
	ds_write_b128 v182, v[130:133] offset:48
	ds_write_b128 v182, v[156:159] offset:112
.LBB0_2198:
	s_or_b64 exec, exec, s[70:71]
	s_cmp_lg_u64 s[26:27], 0
	s_cbranch_scc0 .Lal_7
	s_barrier
.Lal_7:
	v_lshl_add_u32 v158, s11, 8, v178
	v_readlane_b32 s2, v249, 51
	v_readlane_b32 s3, v249, 52
	v_ashrrev_i32_e32 v159, 31, v158
	v_lshlrev_b64 v[176:177], 11, v[158:159]
	v_lshl_add_u64 v[156:157], v[154:155], 1, s[2:3]
	v_lshl_add_u64 v[134:135], v[156:157], 0, v[176:177]
	global_load_dwordx4 v[130:133], v[134:135], off
	global_load_dwordx4 v[138:141], v[134:135], off offset:256
	v_or_b32_e32 v160, 16, v158
	v_ashrrev_i32_e32 v161, 31, v160
	v_lshlrev_b64 v[170:171], 11, v[160:161]
	s_mov_b64 s[30:31], -1
	s_and_b64 vcc, exec, s[16:17]
	s_waitcnt vmcnt(0)
	v_cvt_f32_f16_e32 v162, v130
	v_cvt_f32_f16_sdwa v163, v130 dst_sel:DWORD dst_unused:UNUSED_PAD src0_sel:WORD_1
	v_cvt_f32_f16_e32 v164, v131
	v_cvt_f32_f16_sdwa v165, v131 dst_sel:DWORD dst_unused:UNUSED_PAD src0_sel:WORD_1
	v_lshl_add_u64 v[130:131], v[156:157], 0, v[170:171]
	v_cvt_f32_f16_e32 v192, v132
	v_cvt_f32_f16_sdwa v193, v132 dst_sel:DWORD dst_unused:UNUSED_PAD src0_sel:WORD_1
	v_cvt_f32_f16_e32 v194, v133
	v_cvt_f32_f16_sdwa v195, v133 dst_sel:DWORD dst_unused:UNUSED_PAD src0_sel:WORD_1
	global_load_dwordx4 v[134:137], v[130:131], off
	s_nop 0
	global_load_dwordx4 v[130:133], v[130:131], off offset:256
	ds_read_b128 v[184:187], v182
	ds_read_b128 v[188:191], v182 offset:16
	s_waitcnt lgkmcnt(1)
	v_pk_fma_f32 v[174:175], v[126:127], v[184:185], v[162:163]
	v_pk_fma_f32 v[172:173], v[128:129], v[186:187], v[164:165]
	s_waitcnt lgkmcnt(0)
	v_pk_fma_f32 v[128:129], v[122:123], v[188:189], v[192:193]
	v_cvt_f16_f32_e32 v122, v174
	v_cvt_f16_f32_sdwa v123, v175 dst_sel:WORD_1 dst_unused:UNUSED_PAD src0_sel:DWORD
	v_pk_fma_f32 v[126:127], v[124:125], v[190:191], v[194:195]
	v_cvt_f16_f32_sdwa v124, v173 dst_sel:WORD_1 dst_unused:UNUSED_PAD src0_sel:DWORD
	v_cvt_f16_f32_sdwa v125, v129 dst_sel:WORD_1 dst_unused:UNUSED_PAD src0_sel:DWORD
	v_or_b32_e32 v122, v123, v122
	v_cvt_f16_f32_e32 v123, v172
	v_cvt_f16_f32_sdwa v162, v127 dst_sel:WORD_1 dst_unused:UNUSED_PAD src0_sel:DWORD
	v_or_b32_e32 v123, v124, v123
	v_cvt_f16_f32_e32 v124, v128
	v_or_b32_e32 v124, v125, v124
	v_cvt_f16_f32_e32 v125, v126
	v_or_b32_e32 v125, v162, v125
	s_cbranch_vccz .LBB0_2200
	s_mov_b64 s[30:31], 0

; __device__ __forceinline__ f32x2 unpkh2(unsigned w) { return __builtin_convertvector(__builtin_bit_cast(f16x2_t, w), f32x2); }
; #define PG8_BAR __builtin_amdgcn_s_barrier()
; template <class Epi>
; __device__ __forceinline__ void gemm_phase(LAS unsigned char* lds, const int tid, const Gemm g, const StaticOrder& S, const Epi& E) {
;     ...
;         if (wr == 0) PG8_BAR;
;     __device__ __forceinline__ void operator()(f32x4 (&acc)[2][2][4][2], const pg8::Unit& u, int  , int wr, int wc, int fr, int fq) const {
;         const int j = u.pm < 32 ? 0 : 1;
;         const int colt = u.pn * 256 + wc * 32 + 8 * fq;
;         f32x4 gv[2][2];
; #pragma unroll
;         for (int bj = 0; bj < 2; ++bj)
; #pragma unroll
;             for (int n = 0; n < 2; ++n) gv[bj][n] = *(const f32x4*)(gate + (size_t)j * NMOD + colt + bj * 128 + 4 * n);
; #pragma unroll
;         for (int ai = 0; ai < 2; ++ai)
; #pragma unroll
;             for (int m = 0; m < 4; ++m) {
;                 const int row = u.pm * 256 + ai * 128 + wr * 64 + m * 16 + fr;
;                 const bf16_t* xrp = xr + (size_t)row * D + colt;
;                 float sq = 0.f;
; #pragma unroll
;                 for (int bj = 0; bj < 2; ++bj) {
;                     const u32x4 xw = *(const u32x4*)(xrp + bj * 128);
;                     const f32x2 h0 = unpkh2(xw.x), h1 = unpkh2(xw.y), h2 = unpkh2(xw.z), h3 = unpkh2(xw.w);
;                     const f32x4 x0 = (f32x4){h0.x, h0.y, h1.x, h1.y} + gv[bj][0] * acc[ai][bj][m][0], x1 = (f32x4){h2.x, h2.y, h3.x, h3.y} + gv[bj][1] * acc[ai][bj][m][1];
;                     acc[ai][bj][m][0] = x0; acc[ai][bj][m][1] = x1;
;                     sq += ((x0.x * x0.x + x0.y * x0.y) + (x0.z * x0.z + x0.w * x0.w)) + ((x1.x * x1.x + x1.y * x1.y) + (x1.z * x1.z + x1.w * x1.w));
;                 }
;                 sq += __shfl_xor(sq, 16); sq += __shfl_xor(sq, 32);
;                 if (fq == 0) __hip_atomic_store(ssq + (size_t)row * 16 + u.pn * 4 + wc, sq, RLX_AGENT);
.LBB0_2306:
	s_cmp_gt_i32 s78, 31
	s_cselect_b32 s11, 0x6000, 0
	v_lshl_or_b32 v160, s10, 8, v213
	s_add_u32 s66, s8, s11
	s_addc_u32 s67, s9, 0
	v_ashrrev_i32_e32 v161, 31, v160
	v_lshl_add_u32 v158, s78, 8, v211
	v_lshl_add_u64 v[46:47], v[160:161], 2, s[66:67]
	s_lshl_b32 s66, s10, 2
	v_ashrrev_i32_e32 v159, 31, v158
	v_readlane_b32 s10, v249, 51
	v_lshlrev_b64 v[162:163], 11, v[158:159]
	v_readlane_b32 s11, v249, 52
	global_load_dwordx4 v[66:69], v[46:47], off offset:16
	global_load_dwordx4 v[70:73], v[46:47], off
	global_load_dwordx4 v[42:45], v[46:47], off offset:528
	s_nop 0
	global_load_dwordx4 v[46:49], v[46:47], off offset:512
	v_lshl_add_u64 v[162:163], s[10:11], 0, v[162:163]
	v_lshl_add_u64 v[162:163], v[160:161], 1, v[162:163]
	global_load_dwordx4 v[170:173], v[162:163], off
	v_readlane_b32 s10, v249, 26
	v_readlane_b32 s11, v249, 27
	s_ashr_i32 s67, s66, 31
	s_waitcnt vmcnt(0)
	s_cmp_lg_u64 s[26:27], 0
	s_cbranch_scc0 .Lal_8
	s_barrier
.Lal_8:
	v_cvt_f32_f16_e32 v164, v170
	v_cvt_f32_f16_sdwa v165, v170 dst_sel:DWORD dst_unused:UNUSED_PAD src0_sel:WORD_1
	v_cvt_f32_f16_e32 v170, v171
	v_cvt_f32_f16_sdwa v171, v171 dst_sel:DWORD dst_unused:UNUSED_PAD src0_sel:WORD_1
	v_cvt_f32_f16_e32 v174, v172
	v_cvt_f32_f16_sdwa v175, v172 dst_sel:DWORD dst_unused:UNUSED_PAD src0_sel:WORD_1
	v_cvt_f32_f16_e32 v172, v173
	v_cvt_f32_f16_sdwa v173, v173 dst_sel:DWORD dst_unused:UNUSED_PAD src0_sel:WORD_1
	v_pk_fma_f32 v[144:145], v[144:145], v[72:73], v[170:171]
	v_pk_fma_f32 v[142:143], v[142:143], v[70:71], v[164:165]
	v_mul_f32_e32 v165, v145, v145
	v_mul_f32_e32 v164, v143, v143
	v_pk_fma_f32 v[140:141], v[140:141], v[68:69], v[172:173]
	v_pk_fma_f32 v[138:139], v[138:139], v[66:67], v[174:175]
	v_fmac_f32_e32 v164, v142, v142
	v_fmac_f32_e32 v165, v144, v144
	v_add_f32_e32 v164, v164, v165
	v_mul_f32_e32 v165, v139, v139
	v_mul_f32_e32 v170, v141, v141
	v_fmac_f32_e32 v165, v138, v138
	v_fmac_f32_e32 v170, v140, v140
	v_add_f32_e32 v165, v165, v170
	global_load_dwordx4 v[170:173], v[162:163], off offset:256
	v_add_f32_e32 v174, v164, v165
	s_waitcnt vmcnt(0)
	v_cvt_f32_f16_e32 v162, v170
	v_cvt_f32_f16_sdwa v163, v170 dst_sel:DWORD dst_unused:UNUSED_PAD src0_sel:WORD_1
	v_cvt_f32_f16_e32 v164, v171
	v_cvt_f32_f16_sdwa v165, v171 dst_sel:DWORD dst_unused:UNUSED_PAD src0_sel:WORD_1
	v_cvt_f32_f16_e32 v170, v172
	v_cvt_f32_f16_sdwa v171, v172 dst_sel:DWORD dst_unused:UNUSED_PAD src0_sel:WORD_1
	v_cvt_f32_f16_e32 v172, v173
	v_cvt_f32_f16_sdwa v173, v173 dst_sel:DWORD dst_unused:UNUSED_PAD src0_sel:WORD_1
	v_pk_fma_f32 v[136:137], v[136:137], v[48:49], v[164:165]
	v_pk_fma_f32 v[134:135], v[134:135], v[46:47], v[162:163]
	v_mul_f32_e32 v163, v137, v137
	v_mul_f32_e32 v162, v135, v135
	v_pk_fma_f32 v[132:133], v[132:133], v[44:45], v[172:173]
	v_pk_fma_f32 v[130:131], v[130:131], v[42:43], v[170:171]
	v_fmac_f32_e32 v162, v134, v134
	v_fmac_f32_e32 v163, v136, v136
	v_add_f32_e32 v162, v162, v163
	v_mul_f32_e32 v163, v131, v131
	v_mul_f32_e32 v164, v133, v133
	v_fmac_f32_e32 v163, v130, v130
	v_fmac_f32_e32 v164, v132, v132
	v_add_f32_e32 v163, v163, v164
	v_add_f32_e32 v162, v162, v163
	v_add_f32_e32 v162, v174, v162
	ds_bpermute_b32 v163, v209, v162
	s_waitcnt lgkmcnt(0)
	v_add_f32_e32 v170, v162, v163
	ds_bpermute_b32 v171, v210, v170
	v_lshlrev_b64 v[162:163], 6, v[158:159]
	v_lshl_add_u64 v[172:173], s[10:11], 0, v[162:163]
	s_and_saveexec_b64 s[68:69], s[62:63]
	s_cbranch_execz .LBB0_2308
	v_lshl_add_u64 v[162:163], s[66:67], 2, v[172:173]
	s_lshl_b32 s28, s75, 2
	s_waitcnt lgkmcnt(0)
	v_add_f32_e32 v164, v170, v171
	v_lshl_add_u64 v[162:163], v[162:163], 0, s[28:29]
	global_store_dword v[162:163], v164, off sc1
